# v3 + conformer conv unit: 30 halo-row loads issued together then one wait (was load/wait/unpack per row)
# speedup vs baseline: 1.0060x; 1.0002x over previous
; __device__ __forceinline__ float bflo(unsigned w) { return __uint_as_float(w << 16); }
; __device__ __forceinline__ float bfhi(unsigned w) { return __uint_as_float(w & 0xffff0000u); }
; __device__ __forceinline__ void conf_unit(const Frame& F, int l, int unit) {
;     ...
;     const float* cwp = A.in[I_CCW] + (size_t)l * 31 * WL + tid2;
;     f32x2 w[31];
; #pragma unroll
;     for (int j = 0; j < 31; ++j) w[j] = *(const f32x2*)(cwp + (size_t)j * WL);
;     const f32x2 bias = *(const f32x2*)(A.in[I_CCB] + l * WL + tid2);
;     f32x2 acc[32];
; #pragma unroll
;     for (int t = 0; t < 32; ++t) acc[t] = bias;
; #pragma unroll
;     for (int sg = 0; sg < 64; sg += 16) {
;         f32x2 xg[16];
; #pragma unroll
;         for (int k = 0; k < 16; ++k) { const int s = sg + k; if (s < 62) {
;             const int tg = t0 - 30 + s; f32x2 x;
;             if (tg >= 0) { const unsigned u = *(const unsigned*)(GLU + (size_t)(r0 - 30 + s) * WL + tid2); x = (f32x2){bflo(u), bfhi(u)}; }
;             else if (samp) x = *(const f32x2*)(A.in[I_SCC] + ((size_t)(l * DB + ri.b) * 30 + (30 + tg)) * WL + tid2);
;             else x = (f32x2){0.f, 0.f};
;             xg[k] = x; } }
.LBB0_901:
	s_mov_b64 s[14:15], s[96:97]
	s_lshl_b32 s20, s0, 5
	s_load_dwordx8 s[4:11], s[14:15], 0x88
	s_add_i32 s12, s20, 0xffffe000
	s_ashr_i32 s1, s0, 7
	s_lshr_b32 s12, s12, 6
	v_mov_b32_e32 v134, v198
	v_mov_b32_e32 v0, v199
	s_cmpk_lt_i32 s0, 0x100
	s_cselect_b32 s13, 0xfe0, 32
	s_mov_b64 s[22:23], s[90:91]
	s_cselect_b32 s30, s1, s12
	s_and_b32 s12, s13, s20
	v_lshlrev_b32_e32 v0, 1, v0
	s_mul_i32 s1, s33, 0x1f000
	s_waitcnt lgkmcnt(0)
	s_add_u32 s4, s4, s1
	s_mul_hi_i32 s1, s33, 0x1f000
	v_ashrrev_i32_e32 v1, 31, v0
	s_addc_u32 s5, s5, s1
	v_lshlrev_b64 v[70:71], 2, v[0:1]
	v_lshl_add_u64 v[4:5], s[4:5], 0, v[70:71]
	s_movk_i32 s1, 0x2000
	v_add_co_u32_e32 v2, vcc, s1, v4
	s_movk_i32 s1, 0x4000
	s_nop 0
	v_addc_co_u32_e32 v3, vcc, 0, v5, vcc
	v_add_co_u32_e32 v6, vcc, s1, v4
	s_movk_i32 s1, 0x6000
	s_nop 0
	v_addc_co_u32_e32 v7, vcc, 0, v5, vcc
	global_load_dwordx2 v[64:65], v[4:5], off
	global_load_dwordx2 v[62:63], v[2:3], off offset:-4096
	global_load_dwordx2 v[60:61], v[2:3], off
	global_load_dwordx2 v[58:59], v[6:7], off offset:-4096
	global_load_dwordx2 v[56:57], v[6:7], off
	v_add_co_u32_e32 v2, vcc, s1, v4
	s_mov_b32 s1, 0xa000
	s_nop 0
	v_addc_co_u32_e32 v3, vcc, 0, v5, vcc
	v_add_co_u32_e32 v6, vcc, s81, v4
	s_cmpk_gt_i32 s0, 0xff
	s_nop 0
	v_addc_co_u32_e32 v7, vcc, 0, v5, vcc
	global_load_dwordx2 v[54:55], v[2:3], off offset:-4096
	global_load_dwordx2 v[52:53], v[2:3], off
	global_load_dwordx2 v[50:51], v[6:7], off offset:-4096
	global_load_dwordx2 v[48:49], v[6:7], off
	v_add_co_u32_e32 v2, vcc, s1, v4
	s_mov_b32 s1, 0xc000
	s_nop 0
	v_addc_co_u32_e32 v3, vcc, 0, v5, vcc
	v_add_co_u32_e32 v6, vcc, s1, v4
	s_mov_b32 s1, 0xe000
	s_nop 0
	v_addc_co_u32_e32 v7, vcc, 0, v5, vcc
	global_load_dwordx2 v[46:47], v[2:3], off offset:-4096
	global_load_dwordx2 v[44:45], v[2:3], off
	global_load_dwordx2 v[42:43], v[6:7], off offset:-4096
	global_load_dwordx2 v[40:41], v[6:7], off
	v_add_co_u32_e32 v2, vcc, s1, v4
	s_mov_b32 s1, 0x12000
	s_nop 0
	v_addc_co_u32_e32 v3, vcc, 0, v5, vcc
	v_add_co_u32_e32 v6, vcc, s95, v4
	s_cselect_b64 s[4:5], -1, 0
	s_nop 0
	v_addc_co_u32_e32 v7, vcc, 0, v5, vcc
	global_load_dwordx2 v[38:39], v[2:3], off offset:-4096
	global_load_dwordx2 v[34:35], v[2:3], off
	global_load_dwordx2 v[32:33], v[6:7], off offset:-4096
	global_load_dwordx2 v[30:31], v[6:7], off
	v_add_co_u32_e32 v2, vcc, s1, v4
	s_mov_b32 s1, 0x14000
	s_nop 0
	v_addc_co_u32_e32 v3, vcc, 0, v5, vcc
	v_add_co_u32_e32 v6, vcc, s1, v4
	s_mov_b32 s1, 0x16000
	s_nop 0
	v_addc_co_u32_e32 v7, vcc, 0, v5, vcc
	global_load_dwordx2 v[28:29], v[2:3], off offset:-4096
	global_load_dwordx2 v[26:27], v[2:3], off
	global_load_dwordx2 v[24:25], v[6:7], off offset:-4096
	global_load_dwordx2 v[22:23], v[6:7], off
	v_add_co_u32_e32 v2, vcc, s1, v4
	s_mov_b32 s1, 0x1a000
	s_nop 0
	v_addc_co_u32_e32 v3, vcc, 0, v5, vcc
	v_add_co_u32_e32 v6, vcc, s40, v4
	s_nop 1
	v_addc_co_u32_e32 v7, vcc, 0, v5, vcc
	global_load_dwordx2 v[20:21], v[2:3], off offset:-4096
	global_load_dwordx2 v[18:19], v[2:3], off
	global_load_dwordx2 v[16:17], v[6:7], off offset:-4096
	global_load_dwordx2 v[12:13], v[6:7], off
	v_add_co_u32_e32 v2, vcc, s1, v4
	s_mov_b32 s1, 0x1c000
	s_nop 0
	v_addc_co_u32_e32 v3, vcc, 0, v5, vcc
	v_add_co_u32_e32 v8, vcc, s1, v4
	s_mov_b32 s1, 0x1e000
	s_nop 0
	v_addc_co_u32_e32 v9, vcc, 0, v5, vcc
	v_add_co_u32_e32 v4, vcc, s1, v4
	s_lshl_b64 s[0:1], s[50:51], 2
	s_add_u32 s6, s6, s0
	global_load_dwordx2 v[14:15], v[2:3], off offset:-4096
	global_load_dwordx2 v[10:11], v[2:3], off
	global_load_dwordx2 v[6:7], v[8:9], off offset:-4096
	s_nop 0
	global_load_dwordx2 v[2:3], v[8:9], off
	s_addc_u32 s7, s7, s1
	v_addc_co_u32_e32 v5, vcc, 0, v5, vcc
	v_lshl_add_u64 v[36:37], s[6:7], 0, v[70:71]
	global_load_dwordx2 v[8:9], v[4:5], off offset:-4096
	s_nop 0
	global_load_dwordx2 v[4:5], v[4:5], off
	s_cmp_lg_u32 s12, 0
	global_load_dwordx2 v[66:67], v[36:37], off
	v_lshl_add_u64 v[36:37], v[0:1], 1, s[22:23]
	s_mov_b64 s[6:7], 0x25e40000
	s_cselect_b64 s[12:13], -1, 0
	v_lshl_add_u64 v[36:37], v[36:37], 0, s[6:7]
	s_and_b64 vcc, exec, s[12:13]
	s_cbranch_vccz .LBB0_903
	s_ashr_i32 s21, s20, 31
	s_lshl_b64 s[6:7], s[20:21], 11
	v_lshl_add_u64 v[68:69], v[36:37], 0, s[6:7]
	v_add_co_u32_e32 v68, vcc, 0xffff1000, v68
	s_mov_b64 s[6:7], 0
	s_nop 0
	v_addc_co_u32_e32 v69, vcc, -1, v69, vcc
	global_load_dword v68, v[68:69], off
	s_branch .LBB0_904

; __device__ __forceinline__ float bflo(unsigned w) { return __uint_as_float(w << 16); }
; __device__ __forceinline__ float bfhi(unsigned w) { return __uint_as_float(w & 0xffff0000u); }
; __device__ __forceinline__ void conf_unit(const Frame& F, int l, int unit) {
;     ...
;         for (int k = 0; k < 16; ++k) { const int s = sg + k; if (s < 62) {
;             const int tg = t0 - 30 + s; f32x2 x;
;             if (tg >= 0) { const unsigned u = *(const unsigned*)(GLU + (size_t)(r0 - 30 + s) * WL + tid2); x = (f32x2){bflo(u), bfhi(u)}; }
;             else if (samp) x = *(const f32x2*)(A.in[I_SCC] + ((size_t)(l * DB + ri.b) * 30 + (30 + tg)) * WL + tid2);
;             else x = (f32x2){0.f, 0.f};
;             xg[k] = x; } }
.LBB0_907:
	v_cndmask_b32_e64 v1, 0, 1, s[12:13]
	v_cmp_ne_u32_e64 s[6:7], 1, v1
	s_andn2_b64 vcc, exec, s[12:13]
	s_cbranch_vccnz .LBB0_909
	s_ashr_i32 s21, s20, 31
	s_lshl_b64 s[14:15], s[20:21], 11
	v_lshl_add_u64 v[70:71], v[36:37], 0, s[14:15]
	v_add_co_u32_e32 v70, vcc, 0xffff2000, v70
	s_nop 1
	v_addc_co_u32_e32 v71, vcc, -1, v71, vcc
	global_load_dword v70, v[70:71], off offset:-2048
	s_cbranch_execz .LBB0_910
	s_branch .LBB0_912

; __device__ __forceinline__ float bflo(unsigned w) { return __uint_as_float(w << 16); }
; __device__ __forceinline__ float bfhi(unsigned w) { return __uint_as_float(w & 0xffff0000u); }
; __device__ __forceinline__ void conf_unit(const Frame& F, int l, int unit) {
;     ...
;         for (int k = 0; k < 16; ++k) { const int s = sg + k; if (s < 62) {
;             const int tg = t0 - 30 + s; f32x2 x;
;             if (tg >= 0) { const unsigned u = *(const unsigned*)(GLU + (size_t)(r0 - 30 + s) * WL + tid2); x = (f32x2){bflo(u), bfhi(u)}; }
;             else if (samp) x = *(const f32x2*)(A.in[I_SCC] + ((size_t)(l * DB + ri.b) * 30 + (30 + tg)) * WL + tid2);
;             else x = (f32x2){0.f, 0.f};
;             xg[k] = x; } }
.LBB0_912:
	s_and_b64 vcc, exec, s[12:13]
	s_cbranch_vccz .LBB0_914
	s_ashr_i32 s21, s20, 31
	s_lshl_b64 s[14:15], s[20:21], 11
	v_lshl_add_u64 v[74:75], v[36:37], 0, s[14:15]
	v_add_co_u32_e32 v74, vcc, 0xffff2000, v74
	s_nop 1
	v_addc_co_u32_e32 v75, vcc, -1, v75, vcc
	global_load_dword v74, v[74:75], off
	s_cbranch_execz .LBB0_915
	s_branch .LBB0_917

; __device__ __forceinline__ float bflo(unsigned w) { return __uint_as_float(w << 16); }
; __device__ __forceinline__ float bfhi(unsigned w) { return __uint_as_float(w & 0xffff0000u); }
; __device__ __forceinline__ void conf_unit(const Frame& F, int l, int unit) {
;     ...
;         for (int k = 0; k < 16; ++k) { const int s = sg + k; if (s < 62) {
;             const int tg = t0 - 30 + s; f32x2 x;
;             if (tg >= 0) { const unsigned u = *(const unsigned*)(GLU + (size_t)(r0 - 30 + s) * WL + tid2); x = (f32x2){bflo(u), bfhi(u)}; }
;             else if (samp) x = *(const f32x2*)(A.in[I_SCC] + ((size_t)(l * DB + ri.b) * 30 + (30 + tg)) * WL + tid2);
;             else x = (f32x2){0.f, 0.f};
;             xg[k] = x; } }
.LBB0_917:
	s_and_b64 vcc, exec, s[12:13]
	s_cbranch_vccz .LBB0_919
	s_ashr_i32 s21, s20, 31
	s_lshl_b64 s[14:15], s[20:21], 11
	v_lshl_add_u64 v[76:77], v[36:37], 0, s[14:15]
	v_add_co_u32_e32 v76, vcc, 0xffff3000, v76
	s_nop 1
	v_addc_co_u32_e32 v77, vcc, -1, v77, vcc
	global_load_dword v76, v[76:77], off offset:-2048
	s_cbranch_execz .LBB0_920
	s_branch .LBB0_922

; __device__ __forceinline__ float bflo(unsigned w) { return __uint_as_float(w << 16); }
; __device__ __forceinline__ float bfhi(unsigned w) { return __uint_as_float(w & 0xffff0000u); }
; __device__ __forceinline__ void conf_unit(const Frame& F, int l, int unit) {
;     ...
;         for (int k = 0; k < 16; ++k) { const int s = sg + k; if (s < 62) {
;             const int tg = t0 - 30 + s; f32x2 x;
;             if (tg >= 0) { const unsigned u = *(const unsigned*)(GLU + (size_t)(r0 - 30 + s) * WL + tid2); x = (f32x2){bflo(u), bfhi(u)}; }
;             else if (samp) x = *(const f32x2*)(A.in[I_SCC] + ((size_t)(l * DB + ri.b) * 30 + (30 + tg)) * WL + tid2);
;             else x = (f32x2){0.f, 0.f};
;             xg[k] = x; } }
.LBB0_922:
	s_and_b64 vcc, exec, s[12:13]
	s_cbranch_vccz .LBB0_924
	s_ashr_i32 s21, s20, 31
	s_lshl_b64 s[14:15], s[20:21], 11
	v_lshl_add_u64 v[78:79], v[36:37], 0, s[14:15]
	v_add_co_u32_e32 v78, vcc, 0xffff3000, v78
	s_nop 1
	v_addc_co_u32_e32 v79, vcc, -1, v79, vcc
	global_load_dword v78, v[78:79], off
	s_cbranch_execz .LBB0_925
	s_branch .LBB0_927

; __device__ __forceinline__ float bflo(unsigned w) { return __uint_as_float(w << 16); }
; __device__ __forceinline__ float bfhi(unsigned w) { return __uint_as_float(w & 0xffff0000u); }
; __device__ __forceinline__ void conf_unit(const Frame& F, int l, int unit) {
;     ...
;         for (int k = 0; k < 16; ++k) { const int s = sg + k; if (s < 62) {
;             const int tg = t0 - 30 + s; f32x2 x;
;             if (tg >= 0) { const unsigned u = *(const unsigned*)(GLU + (size_t)(r0 - 30 + s) * WL + tid2); x = (f32x2){bflo(u), bfhi(u)}; }
;             else if (samp) x = *(const f32x2*)(A.in[I_SCC] + ((size_t)(l * DB + ri.b) * 30 + (30 + tg)) * WL + tid2);
;             else x = (f32x2){0.f, 0.f};
;             xg[k] = x; } }
.LBB0_927:
	s_and_b64 vcc, exec, s[12:13]
	s_cbranch_vccz .LBB0_929
	s_ashr_i32 s21, s20, 31
	s_lshl_b64 s[14:15], s[20:21], 11
	v_lshl_add_u64 v[80:81], v[36:37], 0, s[14:15]
	v_add_co_u32_e32 v80, vcc, 0xffff4000, v80
	s_nop 1
	v_addc_co_u32_e32 v81, vcc, -1, v81, vcc
	global_load_dword v80, v[80:81], off offset:-2048
	s_cbranch_execz .LBB0_930
	s_branch .LBB0_932

; __device__ __forceinline__ float bflo(unsigned w) { return __uint_as_float(w << 16); }
; __device__ __forceinline__ float bfhi(unsigned w) { return __uint_as_float(w & 0xffff0000u); }
; __device__ __forceinline__ void conf_unit(const Frame& F, int l, int unit) {
;     ...
;         for (int k = 0; k < 16; ++k) { const int s = sg + k; if (s < 62) {
;             const int tg = t0 - 30 + s; f32x2 x;
;             if (tg >= 0) { const unsigned u = *(const unsigned*)(GLU + (size_t)(r0 - 30 + s) * WL + tid2); x = (f32x2){bflo(u), bfhi(u)}; }
;             else if (samp) x = *(const f32x2*)(A.in[I_SCC] + ((size_t)(l * DB + ri.b) * 30 + (30 + tg)) * WL + tid2);
;             else x = (f32x2){0.f, 0.f};
;             xg[k] = x; } }
.LBB0_932:
	s_and_b64 vcc, exec, s[12:13]
	s_cbranch_vccz .LBB0_934
	s_ashr_i32 s21, s20, 31
	s_lshl_b64 s[14:15], s[20:21], 11
	v_lshl_add_u64 v[82:83], v[36:37], 0, s[14:15]
	v_add_co_u32_e32 v82, vcc, 0xffff4000, v82
	s_nop 1
	v_addc_co_u32_e32 v83, vcc, -1, v83, vcc
	global_load_dword v82, v[82:83], off
	s_cbranch_execz .LBB0_935
	s_branch .LBB0_937

; __device__ __forceinline__ float bflo(unsigned w) { return __uint_as_float(w << 16); }
; __device__ __forceinline__ float bfhi(unsigned w) { return __uint_as_float(w & 0xffff0000u); }
; __device__ __forceinline__ void conf_unit(const Frame& F, int l, int unit) {
;     ...
;         for (int k = 0; k < 16; ++k) { const int s = sg + k; if (s < 62) {
;             const int tg = t0 - 30 + s; f32x2 x;
;             if (tg >= 0) { const unsigned u = *(const unsigned*)(GLU + (size_t)(r0 - 30 + s) * WL + tid2); x = (f32x2){bflo(u), bfhi(u)}; }
;             else if (samp) x = *(const f32x2*)(A.in[I_SCC] + ((size_t)(l * DB + ri.b) * 30 + (30 + tg)) * WL + tid2);
;             else x = (f32x2){0.f, 0.f};
;             xg[k] = x; } }
.LBB0_937:
	s_and_b64 vcc, exec, s[12:13]
	s_cbranch_vccz .LBB0_939
	s_ashr_i32 s21, s20, 31
	s_lshl_b64 s[14:15], s[20:21], 11
	v_lshl_add_u64 v[84:85], v[36:37], 0, s[14:15]
	v_add_co_u32_e32 v84, vcc, 0xffff5000, v84
	s_nop 1
	v_addc_co_u32_e32 v85, vcc, -1, v85, vcc
	global_load_dword v84, v[84:85], off offset:-2048
	s_cbranch_execz .LBB0_940
	s_branch .LBB0_942

; __device__ __forceinline__ float bflo(unsigned w) { return __uint_as_float(w << 16); }
; __device__ __forceinline__ float bfhi(unsigned w) { return __uint_as_float(w & 0xffff0000u); }
; __device__ __forceinline__ void conf_unit(const Frame& F, int l, int unit) {
;     ...
;         for (int k = 0; k < 16; ++k) { const int s = sg + k; if (s < 62) {
;             const int tg = t0 - 30 + s; f32x2 x;
;             if (tg >= 0) { const unsigned u = *(const unsigned*)(GLU + (size_t)(r0 - 30 + s) * WL + tid2); x = (f32x2){bflo(u), bfhi(u)}; }
;             else if (samp) x = *(const f32x2*)(A.in[I_SCC] + ((size_t)(l * DB + ri.b) * 30 + (30 + tg)) * WL + tid2);
;             else x = (f32x2){0.f, 0.f};
;             xg[k] = x; } }
.LBB0_942:
	s_and_b64 vcc, exec, s[12:13]
	s_cbranch_vccz .LBB0_944
	s_ashr_i32 s21, s20, 31
	s_lshl_b64 s[14:15], s[20:21], 11
	v_lshl_add_u64 v[86:87], v[36:37], 0, s[14:15]
	v_add_co_u32_e32 v86, vcc, 0xffff5000, v86
	s_nop 1
	v_addc_co_u32_e32 v87, vcc, -1, v87, vcc
	global_load_dword v86, v[86:87], off
	s_cbranch_execz .LBB0_945
	s_branch .LBB0_947

; __device__ __forceinline__ float bflo(unsigned w) { return __uint_as_float(w << 16); }
; __device__ __forceinline__ float bfhi(unsigned w) { return __uint_as_float(w & 0xffff0000u); }
; __device__ __forceinline__ void conf_unit(const Frame& F, int l, int unit) {
;     ...
;         for (int k = 0; k < 16; ++k) { const int s = sg + k; if (s < 62) {
;             const int tg = t0 - 30 + s; f32x2 x;
;             if (tg >= 0) { const unsigned u = *(const unsigned*)(GLU + (size_t)(r0 - 30 + s) * WL + tid2); x = (f32x2){bflo(u), bfhi(u)}; }
;             else if (samp) x = *(const f32x2*)(A.in[I_SCC] + ((size_t)(l * DB + ri.b) * 30 + (30 + tg)) * WL + tid2);
;             else x = (f32x2){0.f, 0.f};
;             xg[k] = x; } }
.LBB0_947:
	s_and_b64 vcc, exec, s[12:13]
	s_cbranch_vccz .LBB0_949
	s_ashr_i32 s21, s20, 31
	s_lshl_b64 s[14:15], s[20:21], 11
	v_lshl_add_u64 v[88:89], v[36:37], 0, s[14:15]
	v_add_co_u32_e32 v88, vcc, 0xffff6000, v88
	s_nop 1
	v_addc_co_u32_e32 v89, vcc, -1, v89, vcc
	global_load_dword v90, v[88:89], off offset:-2048
	s_cbranch_execz .LBB0_950
	s_branch .LBB0_952

; __device__ __forceinline__ float bflo(unsigned w) { return __uint_as_float(w << 16); }
; __device__ __forceinline__ float bfhi(unsigned w) { return __uint_as_float(w & 0xffff0000u); }
; __device__ __forceinline__ void conf_unit(const Frame& F, int l, int unit) {
;     ...
;         for (int k = 0; k < 16; ++k) { const int s = sg + k; if (s < 62) {
;             const int tg = t0 - 30 + s; f32x2 x;
;             if (tg >= 0) { const unsigned u = *(const unsigned*)(GLU + (size_t)(r0 - 30 + s) * WL + tid2); x = (f32x2){bflo(u), bfhi(u)}; }
;             else if (samp) x = *(const f32x2*)(A.in[I_SCC] + ((size_t)(l * DB + ri.b) * 30 + (30 + tg)) * WL + tid2);
;             else x = (f32x2){0.f, 0.f};
;             xg[k] = x; } }
.LBB0_952:
	s_and_b64 vcc, exec, s[12:13]
	s_cbranch_vccz .LBB0_954
	s_ashr_i32 s21, s20, 31
	s_lshl_b64 s[14:15], s[20:21], 11
	v_lshl_add_u64 v[88:89], v[36:37], 0, s[14:15]
	v_add_co_u32_e32 v88, vcc, 0xffff6000, v88
	s_nop 1
	v_addc_co_u32_e32 v89, vcc, -1, v89, vcc
	global_load_dword v88, v[88:89], off
	s_cbranch_execz .LBB0_955
	s_branch .LBB0_957

; __device__ __forceinline__ float bflo(unsigned w) { return __uint_as_float(w << 16); }
; __device__ __forceinline__ float bfhi(unsigned w) { return __uint_as_float(w & 0xffff0000u); }
; __device__ __forceinline__ void conf_unit(const Frame& F, int l, int unit) {
;     ...
;         for (int k = 0; k < 16; ++k) { const int s = sg + k; if (s < 62) {
;             const int tg = t0 - 30 + s; f32x2 x;
;             if (tg >= 0) { const unsigned u = *(const unsigned*)(GLU + (size_t)(r0 - 30 + s) * WL + tid2); x = (f32x2){bflo(u), bfhi(u)}; }
;             else if (samp) x = *(const f32x2*)(A.in[I_SCC] + ((size_t)(l * DB + ri.b) * 30 + (30 + tg)) * WL + tid2);
;             else x = (f32x2){0.f, 0.f};
;             xg[k] = x; } }
.LBB0_957:
	s_and_b64 vcc, exec, s[12:13]
	s_cbranch_vccz .LBB0_959
	s_ashr_i32 s21, s20, 31
	s_lshl_b64 s[14:15], s[20:21], 11
	v_lshl_add_u64 v[92:93], v[36:37], 0, s[14:15]
	v_add_co_u32_e32 v92, vcc, 0xffff7000, v92
	s_nop 1
	v_addc_co_u32_e32 v93, vcc, -1, v93, vcc
	global_load_dword v92, v[92:93], off offset:-2048
	s_cbranch_execz .LBB0_960
	s_branch .LBB0_962

; __device__ __forceinline__ float bflo(unsigned w) { return __uint_as_float(w << 16); }
; __device__ __forceinline__ float bfhi(unsigned w) { return __uint_as_float(w & 0xffff0000u); }
; __device__ __forceinline__ void conf_unit(const Frame& F, int l, int unit) {
;     ...
;         for (int k = 0; k < 16; ++k) { const int s = sg + k; if (s < 62) {
;             const int tg = t0 - 30 + s; f32x2 x;
;             if (tg >= 0) { const unsigned u = *(const unsigned*)(GLU + (size_t)(r0 - 30 + s) * WL + tid2); x = (f32x2){bflo(u), bfhi(u)}; }
;             else if (samp) x = *(const f32x2*)(A.in[I_SCC] + ((size_t)(l * DB + ri.b) * 30 + (30 + tg)) * WL + tid2);
;             else x = (f32x2){0.f, 0.f};
;             xg[k] = x; } }
.LBB0_962:
	s_and_b64 vcc, exec, s[12:13]
	s_cbranch_vccz .LBB0_964
	s_ashr_i32 s21, s20, 31
	s_lshl_b64 s[14:15], s[20:21], 11
	v_lshl_add_u64 v[94:95], v[36:37], 0, s[14:15]
	v_add_co_u32_e32 v94, vcc, 0xffff7000, v94
	s_nop 1
	v_addc_co_u32_e32 v95, vcc, -1, v95, vcc
	global_load_dword v94, v[94:95], off
	s_cbranch_execz .LBB0_965
	s_branch .LBB0_967

; __device__ __forceinline__ float bflo(unsigned w) { return __uint_as_float(w << 16); }
; __device__ __forceinline__ float bfhi(unsigned w) { return __uint_as_float(w & 0xffff0000u); }
; __device__ __forceinline__ void conf_unit(const Frame& F, int l, int unit) {
;     ...
;         for (int k = 0; k < 16; ++k) { const int s = sg + k; if (s < 62) {
;             const int tg = t0 - 30 + s; f32x2 x;
;             if (tg >= 0) { const unsigned u = *(const unsigned*)(GLU + (size_t)(r0 - 30 + s) * WL + tid2); x = (f32x2){bflo(u), bfhi(u)}; }
;             else if (samp) x = *(const f32x2*)(A.in[I_SCC] + ((size_t)(l * DB + ri.b) * 30 + (30 + tg)) * WL + tid2);
;             else x = (f32x2){0.f, 0.f};
;             xg[k] = x; } }
.LBB0_967:
	s_and_b64 vcc, exec, s[12:13]
	s_cbranch_vccz .LBB0_969
	s_ashr_i32 s21, s20, 31
	s_lshl_b64 s[14:15], s[20:21], 11
	v_lshl_add_u64 v[96:97], v[36:37], 0, s[14:15]
	v_add_co_u32_e32 v96, vcc, 0xffff8000, v96
	s_nop 1
	v_addc_co_u32_e32 v97, vcc, -1, v97, vcc
	global_load_dword v96, v[96:97], off offset:-2048
	s_cbranch_execz .LBB0_970
	s_branch .LBB0_972

; __device__ __forceinline__ float bflo(unsigned w) { return __uint_as_float(w << 16); }
; __device__ __forceinline__ float bfhi(unsigned w) { return __uint_as_float(w & 0xffff0000u); }
; __device__ __forceinline__ void conf_unit(const Frame& F, int l, int unit) {
;     ...
;         for (int k = 0; k < 16; ++k) { const int s = sg + k; if (s < 62) {
;             const int tg = t0 - 30 + s; f32x2 x;
;             if (tg >= 0) { const unsigned u = *(const unsigned*)(GLU + (size_t)(r0 - 30 + s) * WL + tid2); x = (f32x2){bflo(u), bfhi(u)}; }
;             else if (samp) x = *(const f32x2*)(A.in[I_SCC] + ((size_t)(l * DB + ri.b) * 30 + (30 + tg)) * WL + tid2);
;             else x = (f32x2){0.f, 0.f};
;             xg[k] = x; } }
.LBB0_972:
	s_and_b64 vcc, exec, s[12:13]
	s_cbranch_vccz .LBB0_974
	s_ashr_i32 s21, s20, 31
	s_lshl_b64 s[14:15], s[20:21], 11
	v_lshl_add_u64 v[98:99], v[36:37], 0, s[14:15]
	v_add_co_u32_e32 v98, vcc, 0xffff8000, v98
	s_nop 1
	v_addc_co_u32_e32 v99, vcc, -1, v99, vcc
	global_load_dword v98, v[98:99], off
	s_cbranch_execz .LBB0_975
	s_branch .LBB0_977

; __device__ __forceinline__ float bflo(unsigned w) { return __uint_as_float(w << 16); }
; __device__ __forceinline__ float bfhi(unsigned w) { return __uint_as_float(w & 0xffff0000u); }
; __device__ __forceinline__ void conf_unit(const Frame& F, int l, int unit) {
;     ...
;         for (int k = 0; k < 16; ++k) { const int s = sg + k; if (s < 62) {
;             const int tg = t0 - 30 + s; f32x2 x;
;             if (tg >= 0) { const unsigned u = *(const unsigned*)(GLU + (size_t)(r0 - 30 + s) * WL + tid2); x = (f32x2){bflo(u), bfhi(u)}; }
;             else if (samp) x = *(const f32x2*)(A.in[I_SCC] + ((size_t)(l * DB + ri.b) * 30 + (30 + tg)) * WL + tid2);
;             else x = (f32x2){0.f, 0.f};
;             xg[k] = x; } }
.LBB0_977:
	s_and_b64 vcc, exec, s[12:13]
	s_cbranch_vccz .LBB0_979
	s_ashr_i32 s21, s20, 31
	s_lshl_b64 s[14:15], s[20:21], 11
	v_lshl_add_u64 v[100:101], v[36:37], 0, s[14:15]
	v_add_co_u32_e32 v100, vcc, 0xffff9000, v100
	s_nop 1
	v_addc_co_u32_e32 v101, vcc, -1, v101, vcc
	global_load_dword v100, v[100:101], off offset:-2048
	s_cbranch_execz .LBB0_980
	s_branch .LBB0_982

; __device__ __forceinline__ float bflo(unsigned w) { return __uint_as_float(w << 16); }
; __device__ __forceinline__ float bfhi(unsigned w) { return __uint_as_float(w & 0xffff0000u); }
; __device__ __forceinline__ void conf_unit(const Frame& F, int l, int unit) {
;     ...
;         for (int k = 0; k < 16; ++k) { const int s = sg + k; if (s < 62) {
;             const int tg = t0 - 30 + s; f32x2 x;
;             if (tg >= 0) { const unsigned u = *(const unsigned*)(GLU + (size_t)(r0 - 30 + s) * WL + tid2); x = (f32x2){bflo(u), bfhi(u)}; }
;             else if (samp) x = *(const f32x2*)(A.in[I_SCC] + ((size_t)(l * DB + ri.b) * 30 + (30 + tg)) * WL + tid2);
;             else x = (f32x2){0.f, 0.f};
;             xg[k] = x; } }
.LBB0_982:
	s_and_b64 vcc, exec, s[12:13]
	s_cbranch_vccz .LBB0_984
	s_ashr_i32 s21, s20, 31
	s_lshl_b64 s[14:15], s[20:21], 11
	v_lshl_add_u64 v[102:103], v[36:37], 0, s[14:15]
	v_add_co_u32_e32 v102, vcc, 0xffff9000, v102
	s_nop 1
	v_addc_co_u32_e32 v103, vcc, -1, v103, vcc
	global_load_dword v102, v[102:103], off
	s_cbranch_execz .LBB0_985
	s_branch .LBB0_987

; __device__ __forceinline__ float bflo(unsigned w) { return __uint_as_float(w << 16); }
; __device__ __forceinline__ float bfhi(unsigned w) { return __uint_as_float(w & 0xffff0000u); }
; __device__ __forceinline__ void conf_unit(const Frame& F, int l, int unit) {
;     ...
;         for (int k = 0; k < 16; ++k) { const int s = sg + k; if (s < 62) {
;             const int tg = t0 - 30 + s; f32x2 x;
;             if (tg >= 0) { const unsigned u = *(const unsigned*)(GLU + (size_t)(r0 - 30 + s) * WL + tid2); x = (f32x2){bflo(u), bfhi(u)}; }
;             else if (samp) x = *(const f32x2*)(A.in[I_SCC] + ((size_t)(l * DB + ri.b) * 30 + (30 + tg)) * WL + tid2);
;             else x = (f32x2){0.f, 0.f};
;             xg[k] = x; } }
.LBB0_987:
	s_and_b64 vcc, exec, s[6:7]
	s_cbranch_vccnz .LBB0_989
	s_ashr_i32 s21, s20, 31
	s_lshl_b64 s[6:7], s[20:21], 11
	v_lshl_add_u64 v[104:105], v[36:37], 0, s[6:7]
	v_add_co_u32_e32 v104, vcc, 0xffffa000, v104
	s_nop 1
	v_addc_co_u32_e32 v105, vcc, -1, v105, vcc
	global_load_dword v104, v[104:105], off offset:-2048
	s_cbranch_execz .LBB0_990
	s_branch .LBB0_992

; __device__ __forceinline__ float bflo(unsigned w) { return __uint_as_float(w << 16); }
; __device__ __forceinline__ float bfhi(unsigned w) { return __uint_as_float(w & 0xffff0000u); }
; __device__ __forceinline__ void conf_unit(const Frame& F, int l, int unit) {
;     ...
;         for (int k = 0; k < 16; ++k) { const int s = sg + k; if (s < 62) {
;             const int tg = t0 - 30 + s; f32x2 x;
;             if (tg >= 0) { const unsigned u = *(const unsigned*)(GLU + (size_t)(r0 - 30 + s) * WL + tid2); x = (f32x2){bflo(u), bfhi(u)}; }
;             else if (samp) x = *(const f32x2*)(A.in[I_SCC] + ((size_t)(l * DB + ri.b) * 30 + (30 + tg)) * WL + tid2);
;             else x = (f32x2){0.f, 0.f};
;             xg[k] = x; } }
.LBB0_992:
	s_and_b64 vcc, exec, s[12:13]
	s_cbranch_vccz .LBB0_994
	s_ashr_i32 s21, s20, 31
	s_lshl_b64 s[6:7], s[20:21], 11
	v_lshl_add_u64 v[106:107], v[36:37], 0, s[6:7]
	v_add_co_u32_e32 v106, vcc, 0xffffa000, v106
	s_nop 1
	v_addc_co_u32_e32 v107, vcc, -1, v107, vcc
	global_load_dword v106, v[106:107], off
	s_cbranch_execz .LBB0_995
	s_branch .LBB0_997

; __device__ __forceinline__ float bflo(unsigned w) { return __uint_as_float(w << 16); }
; __device__ __forceinline__ float bfhi(unsigned w) { return __uint_as_float(w & 0xffff0000u); }
; __device__ __forceinline__ void conf_unit(const Frame& F, int l, int unit) {
;     ...
;         for (int k = 0; k < 16; ++k) { const int s = sg + k; if (s < 62) {
;             const int tg = t0 - 30 + s; f32x2 x;
;             if (tg >= 0) { const unsigned u = *(const unsigned*)(GLU + (size_t)(r0 - 30 + s) * WL + tid2); x = (f32x2){bflo(u), bfhi(u)}; }
;             else if (samp) x = *(const f32x2*)(A.in[I_SCC] + ((size_t)(l * DB + ri.b) * 30 + (30 + tg)) * WL + tid2);
;             else x = (f32x2){0.f, 0.f};
;             xg[k] = x; } }
.LBB0_997:
	s_and_b64 vcc, exec, s[12:13]
	s_cbranch_vccz .LBB0_999
	s_ashr_i32 s21, s20, 31
	s_lshl_b64 s[6:7], s[20:21], 11
	v_lshl_add_u64 v[108:109], v[36:37], 0, s[6:7]
	v_add_co_u32_e32 v108, vcc, 0xffffb000, v108
	s_nop 1
	v_addc_co_u32_e32 v109, vcc, -1, v109, vcc
	global_load_dword v108, v[108:109], off offset:-2048
	s_cbranch_execz .LBB0_1000
	s_branch .LBB0_1002

; __device__ __forceinline__ float bflo(unsigned w) { return __uint_as_float(w << 16); }
; __device__ __forceinline__ float bfhi(unsigned w) { return __uint_as_float(w & 0xffff0000u); }
; __device__ __forceinline__ void conf_unit(const Frame& F, int l, int unit) {
;     ...
;         for (int k = 0; k < 16; ++k) { const int s = sg + k; if (s < 62) {
;             const int tg = t0 - 30 + s; f32x2 x;
;             if (tg >= 0) { const unsigned u = *(const unsigned*)(GLU + (size_t)(r0 - 30 + s) * WL + tid2); x = (f32x2){bflo(u), bfhi(u)}; }
;             else if (samp) x = *(const f32x2*)(A.in[I_SCC] + ((size_t)(l * DB + ri.b) * 30 + (30 + tg)) * WL + tid2);
;             else x = (f32x2){0.f, 0.f};
;             xg[k] = x; } }
.LBB0_1002:
	s_and_b64 vcc, exec, s[12:13]
	s_cbranch_vccz .LBB0_1004
	s_ashr_i32 s21, s20, 31
	s_lshl_b64 s[6:7], s[20:21], 11
	v_lshl_add_u64 v[110:111], v[36:37], 0, s[6:7]
	v_add_co_u32_e32 v110, vcc, 0xffffb000, v110
	s_nop 1
	v_addc_co_u32_e32 v111, vcc, -1, v111, vcc
	global_load_dword v110, v[110:111], off
	s_cbranch_execz .LBB0_1005
	s_branch .LBB0_1007

; __device__ __forceinline__ float bflo(unsigned w) { return __uint_as_float(w << 16); }
; __device__ __forceinline__ float bfhi(unsigned w) { return __uint_as_float(w & 0xffff0000u); }
; __device__ __forceinline__ void conf_unit(const Frame& F, int l, int unit) {
;     ...
;         for (int k = 0; k < 16; ++k) { const int s = sg + k; if (s < 62) {
;             const int tg = t0 - 30 + s; f32x2 x;
;             if (tg >= 0) { const unsigned u = *(const unsigned*)(GLU + (size_t)(r0 - 30 + s) * WL + tid2); x = (f32x2){bflo(u), bfhi(u)}; }
;             else if (samp) x = *(const f32x2*)(A.in[I_SCC] + ((size_t)(l * DB + ri.b) * 30 + (30 + tg)) * WL + tid2);
;             else x = (f32x2){0.f, 0.f};
;             xg[k] = x; } }
.LBB0_1007:
	s_and_b64 vcc, exec, s[12:13]
	s_cbranch_vccz .LBB0_1009
	s_ashr_i32 s21, s20, 31
	s_lshl_b64 s[6:7], s[20:21], 11
	v_lshl_add_u64 v[112:113], v[36:37], 0, s[6:7]
	v_add_co_u32_e32 v112, vcc, 0xffffc000, v112
	s_nop 1
	v_addc_co_u32_e32 v113, vcc, -1, v113, vcc
	global_load_dword v112, v[112:113], off offset:-2048
	s_cbranch_execz .LBB0_1010
	s_branch .LBB0_1012

; __device__ __forceinline__ float bflo(unsigned w) { return __uint_as_float(w << 16); }
; __device__ __forceinline__ float bfhi(unsigned w) { return __uint_as_float(w & 0xffff0000u); }
; __device__ __forceinline__ void conf_unit(const Frame& F, int l, int unit) {
;     ...
;         for (int k = 0; k < 16; ++k) { const int s = sg + k; if (s < 62) {
;             const int tg = t0 - 30 + s; f32x2 x;
;             if (tg >= 0) { const unsigned u = *(const unsigned*)(GLU + (size_t)(r0 - 30 + s) * WL + tid2); x = (f32x2){bflo(u), bfhi(u)}; }
;             else if (samp) x = *(const f32x2*)(A.in[I_SCC] + ((size_t)(l * DB + ri.b) * 30 + (30 + tg)) * WL + tid2);
;             else x = (f32x2){0.f, 0.f};
;             xg[k] = x; } }
.LBB0_1012:
	s_and_b64 vcc, exec, s[12:13]
	s_cbranch_vccz .LBB0_1014
	s_ashr_i32 s21, s20, 31
	s_lshl_b64 s[6:7], s[20:21], 11
	v_lshl_add_u64 v[114:115], v[36:37], 0, s[6:7]
	v_add_co_u32_e32 v114, vcc, 0xffffc000, v114
	s_nop 1
	v_addc_co_u32_e32 v115, vcc, -1, v115, vcc
	global_load_dword v114, v[114:115], off
	s_cbranch_execz .LBB0_1015
	s_branch .LBB0_1017

; __device__ __forceinline__ float bflo(unsigned w) { return __uint_as_float(w << 16); }
; __device__ __forceinline__ float bfhi(unsigned w) { return __uint_as_float(w & 0xffff0000u); }
; __device__ __forceinline__ void conf_unit(const Frame& F, int l, int unit) {
;     ...
;         for (int k = 0; k < 16; ++k) { const int s = sg + k; if (s < 62) {
;             const int tg = t0 - 30 + s; f32x2 x;
;             if (tg >= 0) { const unsigned u = *(const unsigned*)(GLU + (size_t)(r0 - 30 + s) * WL + tid2); x = (f32x2){bflo(u), bfhi(u)}; }
;             else if (samp) x = *(const f32x2*)(A.in[I_SCC] + ((size_t)(l * DB + ri.b) * 30 + (30 + tg)) * WL + tid2);
;             else x = (f32x2){0.f, 0.f};
;             xg[k] = x; } }
.LBB0_1017:
	s_and_b64 vcc, exec, s[12:13]
	s_cbranch_vccz .LBB0_1019
	s_ashr_i32 s21, s20, 31
	s_lshl_b64 s[6:7], s[20:21], 11
	v_lshl_add_u64 v[116:117], v[36:37], 0, s[6:7]
	v_add_co_u32_e32 v116, vcc, 0xffffd000, v116
	s_nop 1
	v_addc_co_u32_e32 v117, vcc, -1, v117, vcc
	global_load_dword v116, v[116:117], off offset:-2048
	s_cbranch_execz .LBB0_1020
	s_branch .LBB0_1022

; __device__ __forceinline__ float bflo(unsigned w) { return __uint_as_float(w << 16); }
; __device__ __forceinline__ float bfhi(unsigned w) { return __uint_as_float(w & 0xffff0000u); }
; __device__ __forceinline__ void conf_unit(const Frame& F, int l, int unit) {
;     ...
;         for (int k = 0; k < 16; ++k) { const int s = sg + k; if (s < 62) {
;             const int tg = t0 - 30 + s; f32x2 x;
;             if (tg >= 0) { const unsigned u = *(const unsigned*)(GLU + (size_t)(r0 - 30 + s) * WL + tid2); x = (f32x2){bflo(u), bfhi(u)}; }
;             else if (samp) x = *(const f32x2*)(A.in[I_SCC] + ((size_t)(l * DB + ri.b) * 30 + (30 + tg)) * WL + tid2);
;             else x = (f32x2){0.f, 0.f};
;             xg[k] = x; } }
.LBB0_1022:
	s_and_b64 vcc, exec, s[12:13]
	s_cbranch_vccz .LBB0_1024
	s_ashr_i32 s21, s20, 31
	s_lshl_b64 s[6:7], s[20:21], 11
	v_lshl_add_u64 v[118:119], v[36:37], 0, s[6:7]
	v_add_co_u32_e32 v118, vcc, 0xffffd000, v118
	s_nop 1
	v_addc_co_u32_e32 v119, vcc, -1, v119, vcc
	global_load_dword v118, v[118:119], off
	s_cbranch_execz .LBB0_1025
	s_branch .LBB0_1027

; __device__ __forceinline__ float bflo(unsigned w) { return __uint_as_float(w << 16); }
; __device__ __forceinline__ float bfhi(unsigned w) { return __uint_as_float(w & 0xffff0000u); }
; __device__ __forceinline__ void conf_unit(const Frame& F, int l, int unit) {
;     ...
;         for (int k = 0; k < 16; ++k) { const int s = sg + k; if (s < 62) {
;             const int tg = t0 - 30 + s; f32x2 x;
;             if (tg >= 0) { const unsigned u = *(const unsigned*)(GLU + (size_t)(r0 - 30 + s) * WL + tid2); x = (f32x2){bflo(u), bfhi(u)}; }
;             else if (samp) x = *(const f32x2*)(A.in[I_SCC] + ((size_t)(l * DB + ri.b) * 30 + (30 + tg)) * WL + tid2);
;             else x = (f32x2){0.f, 0.f};
;             xg[k] = x; } }
.LBB0_1027:
	s_and_b64 vcc, exec, s[12:13]
	s_cbranch_vccz .LBB0_1029
	s_ashr_i32 s21, s20, 31
	s_lshl_b64 s[6:7], s[20:21], 11
	v_lshl_add_u64 v[120:121], v[36:37], 0, s[6:7]
	v_add_co_u32_e32 v120, vcc, 0xffffe000, v120
	s_nop 1
	v_addc_co_u32_e32 v121, vcc, -1, v121, vcc
	global_load_dword v120, v[120:121], off offset:-2048
	s_cbranch_execz .LBB0_1030
	s_branch .LBB0_1032

; __device__ __forceinline__ float bflo(unsigned w) { return __uint_as_float(w << 16); }
; __device__ __forceinline__ float bfhi(unsigned w) { return __uint_as_float(w & 0xffff0000u); }
; __device__ __forceinline__ void conf_unit(const Frame& F, int l, int unit) {
;     ...
;         for (int k = 0; k < 16; ++k) { const int s = sg + k; if (s < 62) {
;             const int tg = t0 - 30 + s; f32x2 x;
;             if (tg >= 0) { const unsigned u = *(const unsigned*)(GLU + (size_t)(r0 - 30 + s) * WL + tid2); x = (f32x2){bflo(u), bfhi(u)}; }
;             else if (samp) x = *(const f32x2*)(A.in[I_SCC] + ((size_t)(l * DB + ri.b) * 30 + (30 + tg)) * WL + tid2);
;             else x = (f32x2){0.f, 0.f};
;             xg[k] = x; } }
.LBB0_1032:
	s_and_b64 vcc, exec, s[12:13]
	s_cbranch_vccz .LBB0_1034
	s_ashr_i32 s21, s20, 31
	s_lshl_b64 s[6:7], s[20:21], 11
	v_lshl_add_u64 v[122:123], v[36:37], 0, s[6:7]
	v_add_co_u32_e32 v122, vcc, 0xffffe000, v122
	s_nop 1
	v_addc_co_u32_e32 v123, vcc, -1, v123, vcc
	global_load_dword v122, v[122:123], off
	s_cbranch_execz .LBB0_1035
	s_branch .LBB0_1037

; __device__ __forceinline__ float bflo(unsigned w) { return __uint_as_float(w << 16); }
; __device__ __forceinline__ float bfhi(unsigned w) { return __uint_as_float(w & 0xffff0000u); }
; __device__ __forceinline__ void conf_unit(const Frame& F, int l, int unit) {
;     ...
;         for (int k = 0; k < 16; ++k) { const int s = sg + k; if (s < 62) {
;             const int tg = t0 - 30 + s; f32x2 x;
;             if (tg >= 0) { const unsigned u = *(const unsigned*)(GLU + (size_t)(r0 - 30 + s) * WL + tid2); x = (f32x2){bflo(u), bfhi(u)}; }
;             else if (samp) x = *(const f32x2*)(A.in[I_SCC] + ((size_t)(l * DB + ri.b) * 30 + (30 + tg)) * WL + tid2);
;             else x = (f32x2){0.f, 0.f};
;             xg[k] = x; } }
.LBB0_1037:
	s_and_b64 vcc, exec, s[12:13]
	s_cbranch_vccz .LBB0_1039
	s_ashr_i32 s21, s20, 31
	s_lshl_b64 s[6:7], s[20:21], 11
	v_lshl_add_u64 v[124:125], v[36:37], 0, s[6:7]
	v_add_co_u32_e32 v124, vcc, 0xfffff000, v124
	s_nop 1
	v_addc_co_u32_e32 v125, vcc, -1, v125, vcc
	global_load_dword v124, v[124:125], off offset:-2048
	s_cbranch_execz .LBB0_1040
	s_branch .LBB0_1042

; __device__ __forceinline__ float bflo(unsigned w) { return __uint_as_float(w << 16); }
; __device__ __forceinline__ float bfhi(unsigned w) { return __uint_as_float(w & 0xffff0000u); }
; __device__ __forceinline__ void conf_unit(const Frame& F, int l, int unit) {
;     ...
;         for (int k = 0; k < 16; ++k) { const int s = sg + k; if (s < 62) {
;             const int tg = t0 - 30 + s; f32x2 x;
;             if (tg >= 0) { const unsigned u = *(const unsigned*)(GLU + (size_t)(r0 - 30 + s) * WL + tid2); x = (f32x2){bflo(u), bfhi(u)}; }
;             else if (samp) x = *(const f32x2*)(A.in[I_SCC] + ((size_t)(l * DB + ri.b) * 30 + (30 + tg)) * WL + tid2);
;             else x = (f32x2){0.f, 0.f};
;             xg[k] = x; } }
.LBB0_1042:
	s_and_b64 vcc, exec, s[12:13]
	s_cbranch_vccz .LBB0_1044
	s_ashr_i32 s21, s20, 31
	s_lshl_b64 s[6:7], s[20:21], 11
	v_lshl_add_u64 v[126:127], v[36:37], 0, s[6:7]
	global_load_dword v126, v[126:127], off offset:-4096
	s_cbranch_execz .LBB0_1045
	s_branch .LBB0_1047

; __device__ __forceinline__ float bflo(unsigned w) { return __uint_as_float(w << 16); }
; __device__ __forceinline__ float bfhi(unsigned w) { return __uint_as_float(w & 0xffff0000u); }
; __device__ __forceinline__ void conf_unit(const Frame& F, int l, int unit) {
;     ...
;         for (int k = 0; k < 16; ++k) { const int s = sg + k; if (s < 62) {
;             const int tg = t0 - 30 + s; f32x2 x;
;             if (tg >= 0) { const unsigned u = *(const unsigned*)(GLU + (size_t)(r0 - 30 + s) * WL + tid2); x = (f32x2){bflo(u), bfhi(u)}; }
;             else if (samp) x = *(const f32x2*)(A.in[I_SCC] + ((size_t)(l * DB + ri.b) * 30 + (30 + tg)) * WL + tid2);
;             else x = (f32x2){0.f, 0.f};
;             xg[k] = x; } }
.LBB0_1047:
	s_and_b64 vcc, exec, s[12:13]
	s_cbranch_vccz .LBB0_1049
	s_ashr_i32 s21, s20, 31
	s_lshl_b64 s[6:7], s[20:21], 11
	v_lshl_add_u64 v[128:129], v[36:37], 0, s[6:7]
	global_load_dword v128, v[128:129], off offset:-2048
	s_cbranch_execz .LBB0_1050
	s_branch .LBB0_1052

; __device__ __forceinline__ float bflo(unsigned w) { return __uint_as_float(w << 16); }
; __device__ __forceinline__ float bfhi(unsigned w) { return __uint_as_float(w & 0xffff0000u); }
; __device__ __forceinline__ void conf_unit(const Frame& F, int l, int unit) {
;     ...
;         for (int k = 0; k < 16; ++k) { const int s = sg + k; if (s < 62) {
;             const int tg = t0 - 30 + s; f32x2 x;
;             if (tg >= 0) { const unsigned u = *(const unsigned*)(GLU + (size_t)(r0 - 30 + s) * WL + tid2); x = (f32x2){bflo(u), bfhi(u)}; }
;             else if (samp) x = *(const f32x2*)(A.in[I_SCC] + ((size_t)(l * DB + ri.b) * 30 + (30 + tg)) * WL + tid2);
;             else x = (f32x2){0.f, 0.f};
;             xg[k] = x; } }
; #pragma unroll
;         for (int k = 0; k < 16; ++k) { const int s = sg + k; if (s < 62) {
; #pragma unroll
;             for (int j = 0; j < 31; ++j) { const int t = s - j; if (t >= 0 && t < 32) acc[t] += w[j] * xg[k]; } } }
.LBB0_1052:
	s_ashr_i32 s21, s20, 31
	s_lshl_b64 s[4:5], s[20:21], 11
	v_lshl_add_u64 v[130:131], v[36:37], 0, s[4:5]
	s_or_b32 s4, s20, 1
	s_ashr_i32 s5, s4, 31
	s_lshl_b64 s[4:5], s[4:5], 11
	global_load_dword v1, v[130:131], off
	v_lshl_add_u64 v[130:131], v[36:37], 0, s[4:5]
	global_load_dword v132, v[130:131], off
	s_waitcnt vmcnt(0)
	s_and_b64 vcc, exec, s[12:13]
	s_cbranch_vccz .Lconf_nofix
	v_and_b32_e32 v69, 0xffff0000, v68
	v_lshlrev_b32_e32 v68, 16, v68
	v_and_b32_e32 v71, 0xffff0000, v70
	v_lshlrev_b32_e32 v70, 16, v70
	v_and_b32_e32 v75, 0xffff0000, v74
	v_lshlrev_b32_e32 v74, 16, v74
	v_and_b32_e32 v77, 0xffff0000, v76
	v_lshlrev_b32_e32 v76, 16, v76
	v_and_b32_e32 v79, 0xffff0000, v78
	v_lshlrev_b32_e32 v78, 16, v78
	v_and_b32_e32 v81, 0xffff0000, v80
	v_lshlrev_b32_e32 v80, 16, v80
	v_and_b32_e32 v83, 0xffff0000, v82
	v_lshlrev_b32_e32 v82, 16, v82
	v_and_b32_e32 v85, 0xffff0000, v84
	v_lshlrev_b32_e32 v84, 16, v84
	v_and_b32_e32 v87, 0xffff0000, v86
	v_lshlrev_b32_e32 v86, 16, v86
	v_and_b32_e32 v91, 0xffff0000, v90
	v_lshlrev_b32_e32 v90, 16, v90
	v_and_b32_e32 v89, 0xffff0000, v88
	v_lshlrev_b32_e32 v88, 16, v88
	v_and_b32_e32 v93, 0xffff0000, v92
	v_lshlrev_b32_e32 v92, 16, v92
	v_and_b32_e32 v95, 0xffff0000, v94
	v_lshlrev_b32_e32 v94, 16, v94
	v_and_b32_e32 v97, 0xffff0000, v96
	v_lshlrev_b32_e32 v96, 16, v96
	v_and_b32_e32 v99, 0xffff0000, v98
	v_lshlrev_b32_e32 v98, 16, v98
	v_and_b32_e32 v101, 0xffff0000, v100
	v_lshlrev_b32_e32 v100, 16, v100
	v_and_b32_e32 v103, 0xffff0000, v102
	v_lshlrev_b32_e32 v102, 16, v102
	v_and_b32_e32 v105, 0xffff0000, v104
	v_lshlrev_b32_e32 v104, 16, v104
	v_and_b32_e32 v107, 0xffff0000, v106
	v_lshlrev_b32_e32 v106, 16, v106
	v_and_b32_e32 v109, 0xffff0000, v108
	v_lshlrev_b32_e32 v108, 16, v108
	v_and_b32_e32 v111, 0xffff0000, v110
	v_lshlrev_b32_e32 v110, 16, v110
	v_and_b32_e32 v113, 0xffff0000, v112
	v_lshlrev_b32_e32 v112, 16, v112
	v_and_b32_e32 v115, 0xffff0000, v114
	v_lshlrev_b32_e32 v114, 16, v114
	v_and_b32_e32 v117, 0xffff0000, v116
	v_lshlrev_b32_e32 v116, 16, v116
	v_and_b32_e32 v119, 0xffff0000, v118
	v_lshlrev_b32_e32 v118, 16, v118
	v_and_b32_e32 v121, 0xffff0000, v120
	v_lshlrev_b32_e32 v120, 16, v120
	v_and_b32_e32 v123, 0xffff0000, v122
	v_lshlrev_b32_e32 v122, 16, v122
	v_and_b32_e32 v125, 0xffff0000, v124
	v_lshlrev_b32_e32 v124, 16, v124
	v_and_b32_e32 v127, 0xffff0000, v126
	v_lshlrev_b32_e32 v126, 16, v126
	v_and_b32_e32 v129, 0xffff0000, v128
	v_lshlrev_b32_e32 v128, 16, v128
.Lconf_nofix:
	v_pk_fma_f32 v[68:69], v[64:65], v[68:69], v[66:67]
	v_pk_fma_f32 v[72:73], v[64:65], v[70:71], v[66:67]
	v_pk_fma_f32 v[68:69], v[62:63], v[70:71], v[68:69]
	v_pk_fma_f32 v[70:71], v[64:65], v[74:75], v[66:67]
	v_pk_fma_f32 v[72:73], v[62:63], v[74:75], v[72:73]
	v_pk_fma_f32 v[68:69], v[60:61], v[74:75], v[68:69]
	v_pk_fma_f32 v[74:75], v[64:65], v[76:77], v[66:67]
	v_pk_fma_f32 v[70:71], v[62:63], v[76:77], v[70:71]
	v_pk_fma_f32 v[72:73], v[60:61], v[76:77], v[72:73]
	v_pk_fma_f32 v[68:69], v[58:59], v[76:77], v[68:69]
	v_pk_fma_f32 v[76:77], v[64:65], v[78:79], v[66:67]
	v_pk_fma_f32 v[74:75], v[62:63], v[78:79], v[74:75]
	v_pk_fma_f32 v[70:71], v[60:61], v[78:79], v[70:71]
	v_pk_fma_f32 v[72:73], v[58:59], v[78:79], v[72:73]
	v_pk_fma_f32 v[68:69], v[56:57], v[78:79], v[68:69]
	v_pk_fma_f32 v[78:79], v[64:65], v[80:81], v[66:67]
	v_pk_fma_f32 v[76:77], v[62:63], v[80:81], v[76:77]
	v_pk_fma_f32 v[74:75], v[60:61], v[80:81], v[74:75]
	v_pk_fma_f32 v[70:71], v[58:59], v[80:81], v[70:71]
	v_pk_fma_f32 v[72:73], v[56:57], v[80:81], v[72:73]
	v_pk_fma_f32 v[68:69], v[54:55], v[80:81], v[68:69]
	v_pk_fma_f32 v[80:81], v[64:65], v[82:83], v[66:67]
	v_pk_fma_f32 v[78:79], v[62:63], v[82:83], v[78:79]
	v_pk_fma_f32 v[76:77], v[60:61], v[82:83], v[76:77]
	v_pk_fma_f32 v[74:75], v[58:59], v[82:83], v[74:75]
	v_pk_fma_f32 v[70:71], v[56:57], v[82:83], v[70:71]
	v_pk_fma_f32 v[72:73], v[54:55], v[82:83], v[72:73]
	v_pk_fma_f32 v[68:69], v[52:53], v[82:83], v[68:69]
	v_pk_fma_f32 v[82:83], v[64:65], v[84:85], v[66:67]
	v_pk_fma_f32 v[80:81], v[62:63], v[84:85], v[80:81]
	v_pk_fma_f32 v[78:79], v[60:61], v[84:85], v[78:79]
	v_pk_fma_f32 v[76:77], v[58:59], v[84:85], v[76:77]
	v_pk_fma_f32 v[74:75], v[56:57], v[84:85], v[74:75]
	v_pk_fma_f32 v[70:71], v[54:55], v[84:85], v[70:71]
	v_pk_fma_f32 v[72:73], v[52:53], v[84:85], v[72:73]
	v_pk_fma_f32 v[68:69], v[50:51], v[84:85], v[68:69]
	v_pk_fma_f32 v[84:85], v[64:65], v[86:87], v[66:67]
	v_pk_fma_f32 v[82:83], v[62:63], v[86:87], v[82:83]
	v_pk_fma_f32 v[80:81], v[60:61], v[86:87], v[80:81]
	v_pk_fma_f32 v[78:79], v[58:59], v[86:87], v[78:79]
	v_pk_fma_f32 v[76:77], v[56:57], v[86:87], v[76:77]
	v_pk_fma_f32 v[74:75], v[54:55], v[86:87], v[74:75]
	v_pk_fma_f32 v[70:71], v[52:53], v[86:87], v[70:71]
	v_pk_fma_f32 v[72:73], v[50:51], v[86:87], v[72:73]
	v_pk_fma_f32 v[68:69], v[48:49], v[86:87], v[68:69]
	v_pk_fma_f32 v[86:87], v[64:65], v[90:91], v[66:67]
	v_pk_fma_f32 v[84:85], v[62:63], v[90:91], v[84:85]
	v_pk_fma_f32 v[82:83], v[60:61], v[90:91], v[82:83]
	v_pk_fma_f32 v[80:81], v[58:59], v[90:91], v[80:81]
	v_pk_fma_f32 v[78:79], v[56:57], v[90:91], v[78:79]
	v_pk_fma_f32 v[76:77], v[54:55], v[90:91], v[76:77]
	v_pk_fma_f32 v[74:75], v[52:53], v[90:91], v[74:75]
	v_pk_fma_f32 v[70:71], v[50:51], v[90:91], v[70:71]
	v_pk_fma_f32 v[72:73], v[48:49], v[90:91], v[72:73]
	v_pk_fma_f32 v[68:69], v[46:47], v[90:91], v[68:69]
	v_pk_fma_f32 v[90:91], v[64:65], v[88:89], v[66:67]
	v_pk_fma_f32 v[86:87], v[62:63], v[88:89], v[86:87]
	v_pk_fma_f32 v[84:85], v[60:61], v[88:89], v[84:85]
	v_pk_fma_f32 v[82:83], v[58:59], v[88:89], v[82:83]
; __device__ __forceinline__ float bflo(unsigned w) { return __uint_as_float(w << 16); }
; __device__ __forceinline__ float bfhi(unsigned w) { return __uint_as_float(w & 0xffff0000u); }
; __device__ __forceinline__ void conf_unit(const Frame& F, int l, int unit) {
;     ...
;     for (int sg = 0; sg < 64; sg += 16) {
;         f32x2 xg[16];
; #pragma unroll
;         for (int k = 0; k < 16; ++k) { const int s = sg + k; if (s < 62) {
;             const int tg = t0 - 30 + s; f32x2 x;
;             if (tg >= 0) { const unsigned u = *(const unsigned*)(GLU + (size_t)(r0 - 30 + s) * WL + tid2); x = (f32x2){bflo(u), bfhi(u)}; }
;             else if (samp) x = *(const f32x2*)(A.in[I_SCC] + ((size_t)(l * DB + ri.b) * 30 + (30 + tg)) * WL + tid2);
;             else x = (f32x2){0.f, 0.f};
;             xg[k] = x; } }
; #pragma unroll
;         for (int k = 0; k < 16; ++k) { const int s = sg + k; if (s < 62) {
; #pragma unroll
;             for (int j = 0; j < 31; ++j) { const int t = s - j; if (t >= 0 && t < 32) acc[t] += w[j] * xg[k]; } } }
;         asm volatile("" ::: "memory");
;     }
	v_pk_fma_f32 v[80:81], v[56:57], v[88:89], v[80:81]
	v_pk_fma_f32 v[78:79], v[54:55], v[88:89], v[78:79]
	v_pk_fma_f32 v[76:77], v[52:53], v[88:89], v[76:77]
	v_pk_fma_f32 v[74:75], v[50:51], v[88:89], v[74:75]
	v_pk_fma_f32 v[70:71], v[48:49], v[88:89], v[70:71]
	v_pk_fma_f32 v[72:73], v[46:47], v[88:89], v[72:73]
	v_pk_fma_f32 v[68:69], v[44:45], v[88:89], v[68:69]
	v_pk_fma_f32 v[88:89], v[64:65], v[92:93], v[66:67]
	v_pk_fma_f32 v[90:91], v[62:63], v[92:93], v[90:91]
	v_pk_fma_f32 v[86:87], v[60:61], v[92:93], v[86:87]
	v_pk_fma_f32 v[84:85], v[58:59], v[92:93], v[84:85]
	v_pk_fma_f32 v[82:83], v[56:57], v[92:93], v[82:83]
	v_pk_fma_f32 v[80:81], v[54:55], v[92:93], v[80:81]
	v_pk_fma_f32 v[78:79], v[52:53], v[92:93], v[78:79]
	v_pk_fma_f32 v[76:77], v[50:51], v[92:93], v[76:77]
	v_pk_fma_f32 v[74:75], v[48:49], v[92:93], v[74:75]
	v_pk_fma_f32 v[70:71], v[46:47], v[92:93], v[70:71]
	v_pk_fma_f32 v[72:73], v[44:45], v[92:93], v[72:73]
	v_pk_fma_f32 v[68:69], v[42:43], v[92:93], v[68:69]
	v_pk_fma_f32 v[92:93], v[64:65], v[94:95], v[66:67]
	v_pk_fma_f32 v[88:89], v[62:63], v[94:95], v[88:89]
	v_pk_fma_f32 v[90:91], v[60:61], v[94:95], v[90:91]
	v_pk_fma_f32 v[86:87], v[58:59], v[94:95], v[86:87]
	v_pk_fma_f32 v[84:85], v[56:57], v[94:95], v[84:85]
	v_pk_fma_f32 v[82:83], v[54:55], v[94:95], v[82:83]
	v_pk_fma_f32 v[80:81], v[52:53], v[94:95], v[80:81]
	v_pk_fma_f32 v[78:79], v[50:51], v[94:95], v[78:79]
	v_pk_fma_f32 v[76:77], v[48:49], v[94:95], v[76:77]
	v_pk_fma_f32 v[74:75], v[46:47], v[94:95], v[74:75]
	v_pk_fma_f32 v[70:71], v[44:45], v[94:95], v[70:71]
	v_pk_fma_f32 v[72:73], v[42:43], v[94:95], v[72:73]
	v_pk_fma_f32 v[68:69], v[40:41], v[94:95], v[68:69]
	v_pk_fma_f32 v[94:95], v[64:65], v[96:97], v[66:67]
	v_pk_fma_f32 v[92:93], v[62:63], v[96:97], v[92:93]
	v_pk_fma_f32 v[88:89], v[60:61], v[96:97], v[88:89]
	v_pk_fma_f32 v[90:91], v[58:59], v[96:97], v[90:91]
	v_pk_fma_f32 v[86:87], v[56:57], v[96:97], v[86:87]
	v_pk_fma_f32 v[84:85], v[54:55], v[96:97], v[84:85]
	v_pk_fma_f32 v[82:83], v[52:53], v[96:97], v[82:83]
	v_pk_fma_f32 v[80:81], v[50:51], v[96:97], v[80:81]
	v_pk_fma_f32 v[78:79], v[48:49], v[96:97], v[78:79]
	v_pk_fma_f32 v[76:77], v[46:47], v[96:97], v[76:77]
	v_pk_fma_f32 v[74:75], v[44:45], v[96:97], v[74:75]
	v_pk_fma_f32 v[70:71], v[42:43], v[96:97], v[70:71]
	v_pk_fma_f32 v[72:73], v[40:41], v[96:97], v[72:73]
	v_pk_fma_f32 v[68:69], v[38:39], v[96:97], v[68:69]
	v_pk_fma_f32 v[96:97], v[64:65], v[98:99], v[66:67]
	v_pk_fma_f32 v[94:95], v[62:63], v[98:99], v[94:95]
	v_pk_fma_f32 v[92:93], v[60:61], v[98:99], v[92:93]
	v_pk_fma_f32 v[88:89], v[58:59], v[98:99], v[88:89]
	v_pk_fma_f32 v[90:91], v[56:57], v[98:99], v[90:91]
	v_pk_fma_f32 v[86:87], v[54:55], v[98:99], v[86:87]
	v_pk_fma_f32 v[84:85], v[52:53], v[98:99], v[84:85]
	v_pk_fma_f32 v[82:83], v[50:51], v[98:99], v[82:83]
	v_pk_fma_f32 v[80:81], v[48:49], v[98:99], v[80:81]
	v_pk_fma_f32 v[78:79], v[46:47], v[98:99], v[78:79]
	v_pk_fma_f32 v[76:77], v[44:45], v[98:99], v[76:77]
	v_pk_fma_f32 v[74:75], v[42:43], v[98:99], v[74:75]
	v_pk_fma_f32 v[70:71], v[40:41], v[98:99], v[70:71]
	v_pk_fma_f32 v[72:73], v[38:39], v[98:99], v[72:73]
	v_pk_fma_f32 v[68:69], v[34:35], v[98:99], v[68:69]
	v_pk_fma_f32 v[98:99], v[64:65], v[100:101], v[66:67]
	v_pk_fma_f32 v[96:97], v[62:63], v[100:101], v[96:97]
	v_pk_fma_f32 v[94:95], v[60:61], v[100:101], v[94:95]
	v_pk_fma_f32 v[92:93], v[58:59], v[100:101], v[92:93]
	v_pk_fma_f32 v[88:89], v[56:57], v[100:101], v[88:89]
	v_pk_fma_f32 v[90:91], v[54:55], v[100:101], v[90:91]
	v_pk_fma_f32 v[86:87], v[52:53], v[100:101], v[86:87]
	v_pk_fma_f32 v[84:85], v[50:51], v[100:101], v[84:85]
	v_pk_fma_f32 v[82:83], v[48:49], v[100:101], v[82:83]
	v_pk_fma_f32 v[80:81], v[46:47], v[100:101], v[80:81]
	v_pk_fma_f32 v[78:79], v[44:45], v[100:101], v[78:79]
	v_pk_fma_f32 v[76:77], v[42:43], v[100:101], v[76:77]
	v_pk_fma_f32 v[74:75], v[40:41], v[100:101], v[74:75]
	v_pk_fma_f32 v[130:131], v[38:39], v[100:101], v[70:71]
	v_pk_fma_f32 v[72:73], v[34:35], v[100:101], v[72:73]
	v_pk_fma_f32 v[100:101], v[32:33], v[100:101], v[68:69]
	v_pk_fma_f32 v[98:99], v[62:63], v[102:103], v[98:99]
	v_lshlrev_b32_e32 v70, 16, v132
	v_and_b32_e32 v71, 0xffff0000, v132
	v_pk_fma_f32 v[132:133], v[64:65], v[102:103], v[66:67]
	v_pk_fma_f32 v[96:97], v[60:61], v[102:103], v[96:97]
	v_pk_fma_f32 v[94:95], v[58:59], v[102:103], v[94:95]
	v_pk_fma_f32 v[92:93], v[56:57], v[102:103], v[92:93]
	v_pk_fma_f32 v[88:89], v[54:55], v[102:103], v[88:89]
	v_pk_fma_f32 v[90:91], v[52:53], v[102:103], v[90:91]
	v_pk_fma_f32 v[86:87], v[50:51], v[102:103], v[86:87]
	v_pk_fma_f32 v[84:85], v[48:49], v[102:103], v[84:85]
	v_pk_fma_f32 v[82:83], v[46:47], v[102:103], v[82:83]
	v_pk_fma_f32 v[80:81], v[44:45], v[102:103], v[80:81]
	v_pk_fma_f32 v[78:79], v[42:43], v[102:103], v[78:79]
	v_pk_fma_f32 v[76:77], v[40:41], v[102:103], v[76:77]
	v_pk_fma_f32 v[74:75], v[38:39], v[102:103], v[74:75]
	v_pk_fma_f32 v[130:131], v[34:35], v[102:103], v[130:131]
	v_pk_fma_f32 v[72:73], v[32:33], v[102:103], v[72:73]
	v_pk_fma_f32 v[100:101], v[30:31], v[102:103], v[100:101]
	v_pk_fma_f32 v[102:103], v[64:65], v[104:105], v[66:67]
	v_pk_fma_f32 v[98:99], v[60:61], v[104:105], v[98:99]
	v_pk_fma_f32 v[102:103], v[62:63], v[106:107], v[102:103]
	v_pk_fma_f32 v[98:99], v[58:59], v[106:107], v[98:99]
	v_pk_fma_f32 v[102:103], v[60:61], v[108:109], v[102:103]
	v_pk_fma_f32 v[98:99], v[56:57], v[108:109], v[98:99]
	v_pk_fma_f32 v[132:133], v[62:63], v[104:105], v[132:133]
	v_pk_fma_f32 v[96:97], v[58:59], v[104:105], v[96:97]
	v_pk_fma_f32 v[94:95], v[56:57], v[104:105], v[94:95]
; __device__ __forceinline__ float bflo(unsigned w) { return __uint_as_float(w << 16); }
; __device__ __forceinline__ float bfhi(unsigned w) { return __uint_as_float(w & 0xffff0000u); }
; __device__ __forceinline__ void conf_unit(const Frame& F, int l, int unit) {
;     ...
;     for (int sg = 0; sg < 64; sg += 16) {
;         f32x2 xg[16];
; #pragma unroll
;         for (int k = 0; k < 16; ++k) { const int s = sg + k; if (s < 62) {
;             const int tg = t0 - 30 + s; f32x2 x;
;             if (tg >= 0) { const unsigned u = *(const unsigned*)(GLU + (size_t)(r0 - 30 + s) * WL + tid2); x = (f32x2){bflo(u), bfhi(u)}; }
;             else if (samp) x = *(const f32x2*)(A.in[I_SCC] + ((size_t)(l * DB + ri.b) * 30 + (30 + tg)) * WL + tid2);
;             else x = (f32x2){0.f, 0.f};
;             xg[k] = x; } }
; #pragma unroll
;         for (int k = 0; k < 16; ++k) { const int s = sg + k; if (s < 62) {
; #pragma unroll
;             for (int j = 0; j < 31; ++j) { const int t = s - j; if (t >= 0 && t < 32) acc[t] += w[j] * xg[k]; } } }
;         asm volatile("" ::: "memory");
;     }
	v_pk_fma_f32 v[92:93], v[54:55], v[104:105], v[92:93]
	v_pk_fma_f32 v[88:89], v[52:53], v[104:105], v[88:89]
	v_pk_fma_f32 v[90:91], v[50:51], v[104:105], v[90:91]
	v_pk_fma_f32 v[86:87], v[48:49], v[104:105], v[86:87]
	v_pk_fma_f32 v[84:85], v[46:47], v[104:105], v[84:85]
	v_pk_fma_f32 v[82:83], v[44:45], v[104:105], v[82:83]
	v_pk_fma_f32 v[80:81], v[42:43], v[104:105], v[80:81]
	v_pk_fma_f32 v[78:79], v[40:41], v[104:105], v[78:79]
	v_pk_fma_f32 v[76:77], v[38:39], v[104:105], v[76:77]
	v_pk_fma_f32 v[74:75], v[34:35], v[104:105], v[74:75]
	v_pk_fma_f32 v[130:131], v[32:33], v[104:105], v[130:131]
	v_pk_fma_f32 v[72:73], v[30:31], v[104:105], v[72:73]
	v_pk_fma_f32 v[100:101], v[28:29], v[104:105], v[100:101]
	v_pk_fma_f32 v[102:103], v[58:59], v[110:111], v[102:103]
	v_pk_fma_f32 v[98:99], v[54:55], v[110:111], v[98:99]
	v_pk_fma_f32 v[104:105], v[64:65], v[106:107], v[66:67]
	v_pk_fma_f32 v[132:133], v[60:61], v[106:107], v[132:133]
	v_pk_fma_f32 v[96:97], v[56:57], v[106:107], v[96:97]
	v_pk_fma_f32 v[94:95], v[54:55], v[106:107], v[94:95]
	v_pk_fma_f32 v[92:93], v[52:53], v[106:107], v[92:93]
	v_pk_fma_f32 v[88:89], v[50:51], v[106:107], v[88:89]
	v_pk_fma_f32 v[90:91], v[48:49], v[106:107], v[90:91]
	v_pk_fma_f32 v[86:87], v[46:47], v[106:107], v[86:87]
	v_pk_fma_f32 v[84:85], v[44:45], v[106:107], v[84:85]
	v_pk_fma_f32 v[82:83], v[42:43], v[106:107], v[82:83]
	v_pk_fma_f32 v[80:81], v[40:41], v[106:107], v[80:81]
	v_pk_fma_f32 v[78:79], v[38:39], v[106:107], v[78:79]
	v_pk_fma_f32 v[76:77], v[34:35], v[106:107], v[76:77]
	v_pk_fma_f32 v[74:75], v[32:33], v[106:107], v[74:75]
	v_pk_fma_f32 v[130:131], v[30:31], v[106:107], v[130:131]
	v_pk_fma_f32 v[72:73], v[28:29], v[106:107], v[72:73]
	v_pk_fma_f32 v[100:101], v[26:27], v[106:107], v[100:101]
	v_pk_fma_f32 v[102:103], v[56:57], v[112:113], v[102:103]
	v_pk_fma_f32 v[98:99], v[52:53], v[112:113], v[98:99]
	v_pk_fma_f32 v[106:107], v[64:65], v[108:109], v[66:67]
	v_pk_fma_f32 v[104:105], v[62:63], v[108:109], v[104:105]
	v_pk_fma_f32 v[132:133], v[58:59], v[108:109], v[132:133]
	v_pk_fma_f32 v[96:97], v[54:55], v[108:109], v[96:97]
	v_pk_fma_f32 v[94:95], v[52:53], v[108:109], v[94:95]
	v_pk_fma_f32 v[92:93], v[50:51], v[108:109], v[92:93]
	v_pk_fma_f32 v[88:89], v[48:49], v[108:109], v[88:89]
	v_pk_fma_f32 v[90:91], v[46:47], v[108:109], v[90:91]
	v_pk_fma_f32 v[86:87], v[44:45], v[108:109], v[86:87]
	v_pk_fma_f32 v[84:85], v[42:43], v[108:109], v[84:85]
	v_pk_fma_f32 v[82:83], v[40:41], v[108:109], v[82:83]
	v_pk_fma_f32 v[80:81], v[38:39], v[108:109], v[80:81]
	v_pk_fma_f32 v[78:79], v[34:35], v[108:109], v[78:79]
	v_pk_fma_f32 v[76:77], v[32:33], v[108:109], v[76:77]
	v_pk_fma_f32 v[74:75], v[30:31], v[108:109], v[74:75]
	v_pk_fma_f32 v[130:131], v[28:29], v[108:109], v[130:131]
	v_pk_fma_f32 v[72:73], v[26:27], v[108:109], v[72:73]
	v_pk_fma_f32 v[100:101], v[24:25], v[108:109], v[100:101]
	v_pk_fma_f32 v[102:103], v[54:55], v[114:115], v[102:103]
	v_pk_fma_f32 v[98:99], v[50:51], v[114:115], v[98:99]
	v_pk_fma_f32 v[108:109], v[64:65], v[110:111], v[66:67]
	v_pk_fma_f32 v[106:107], v[62:63], v[110:111], v[106:107]
	v_pk_fma_f32 v[104:105], v[60:61], v[110:111], v[104:105]
	v_pk_fma_f32 v[132:133], v[56:57], v[110:111], v[132:133]
	v_pk_fma_f32 v[96:97], v[52:53], v[110:111], v[96:97]
	v_pk_fma_f32 v[94:95], v[50:51], v[110:111], v[94:95]
	v_pk_fma_f32 v[92:93], v[48:49], v[110:111], v[92:93]
	v_pk_fma_f32 v[88:89], v[46:47], v[110:111], v[88:89]
	v_pk_fma_f32 v[90:91], v[44:45], v[110:111], v[90:91]
	v_pk_fma_f32 v[86:87], v[42:43], v[110:111], v[86:87]
	v_pk_fma_f32 v[84:85], v[40:41], v[110:111], v[84:85]
	v_pk_fma_f32 v[82:83], v[38:39], v[110:111], v[82:83]
	v_pk_fma_f32 v[80:81], v[34:35], v[110:111], v[80:81]
	v_pk_fma_f32 v[78:79], v[32:33], v[110:111], v[78:79]
	v_pk_fma_f32 v[76:77], v[30:31], v[110:111], v[76:77]
	v_pk_fma_f32 v[74:75], v[28:29], v[110:111], v[74:75]
	v_pk_fma_f32 v[130:131], v[26:27], v[110:111], v[130:131]
	v_pk_fma_f32 v[72:73], v[24:25], v[110:111], v[72:73]
	v_pk_fma_f32 v[100:101], v[22:23], v[110:111], v[100:101]
	v_pk_fma_f32 v[102:103], v[52:53], v[116:117], v[102:103]
	v_pk_fma_f32 v[98:99], v[48:49], v[116:117], v[98:99]
	v_pk_fma_f32 v[110:111], v[64:65], v[112:113], v[66:67]
	v_pk_fma_f32 v[108:109], v[62:63], v[112:113], v[108:109]
	v_pk_fma_f32 v[106:107], v[60:61], v[112:113], v[106:107]
	v_pk_fma_f32 v[104:105], v[58:59], v[112:113], v[104:105]
	v_pk_fma_f32 v[132:133], v[54:55], v[112:113], v[132:133]
	v_pk_fma_f32 v[96:97], v[50:51], v[112:113], v[96:97]
	v_pk_fma_f32 v[94:95], v[48:49], v[112:113], v[94:95]
	v_pk_fma_f32 v[92:93], v[46:47], v[112:113], v[92:93]
	v_pk_fma_f32 v[88:89], v[44:45], v[112:113], v[88:89]
	v_pk_fma_f32 v[90:91], v[42:43], v[112:113], v[90:91]
	v_pk_fma_f32 v[86:87], v[40:41], v[112:113], v[86:87]
	v_pk_fma_f32 v[84:85], v[38:39], v[112:113], v[84:85]
	v_pk_fma_f32 v[82:83], v[34:35], v[112:113], v[82:83]
	v_pk_fma_f32 v[80:81], v[32:33], v[112:113], v[80:81]
	v_pk_fma_f32 v[78:79], v[30:31], v[112:113], v[78:79]
	v_pk_fma_f32 v[76:77], v[28:29], v[112:113], v[76:77]
	v_pk_fma_f32 v[74:75], v[26:27], v[112:113], v[74:75]
	v_pk_fma_f32 v[130:131], v[24:25], v[112:113], v[130:131]
	v_pk_fma_f32 v[72:73], v[22:23], v[112:113], v[72:73]
	v_pk_fma_f32 v[100:101], v[20:21], v[112:113], v[100:101]
	v_pk_fma_f32 v[102:103], v[50:51], v[118:119], v[102:103]
	v_pk_fma_f32 v[98:99], v[46:47], v[118:119], v[98:99]
	v_pk_fma_f32 v[112:113], v[64:65], v[114:115], v[66:67]
	v_pk_fma_f32 v[110:111], v[62:63], v[114:115], v[110:111]
	v_pk_fma_f32 v[108:109], v[60:61], v[114:115], v[108:109]
; __device__ __forceinline__ float bflo(unsigned w) { return __uint_as_float(w << 16); }
; __device__ __forceinline__ float bfhi(unsigned w) { return __uint_as_float(w & 0xffff0000u); }
; __device__ __forceinline__ void conf_unit(const Frame& F, int l, int unit) {
;     ...
;     for (int sg = 0; sg < 64; sg += 16) {
;         f32x2 xg[16];
; #pragma unroll
;         for (int k = 0; k < 16; ++k) { const int s = sg + k; if (s < 62) {
;             const int tg = t0 - 30 + s; f32x2 x;
;             if (tg >= 0) { const unsigned u = *(const unsigned*)(GLU + (size_t)(r0 - 30 + s) * WL + tid2); x = (f32x2){bflo(u), bfhi(u)}; }
;             else if (samp) x = *(const f32x2*)(A.in[I_SCC] + ((size_t)(l * DB + ri.b) * 30 + (30 + tg)) * WL + tid2);
;             else x = (f32x2){0.f, 0.f};
;             xg[k] = x; } }
; #pragma unroll
;         for (int k = 0; k < 16; ++k) { const int s = sg + k; if (s < 62) {
; #pragma unroll
;             for (int j = 0; j < 31; ++j) { const int t = s - j; if (t >= 0 && t < 32) acc[t] += w[j] * xg[k]; } } }
;         asm volatile("" ::: "memory");
;     }
	v_pk_fma_f32 v[106:107], v[58:59], v[114:115], v[106:107]
	v_pk_fma_f32 v[104:105], v[56:57], v[114:115], v[104:105]
	v_pk_fma_f32 v[132:133], v[52:53], v[114:115], v[132:133]
	v_pk_fma_f32 v[96:97], v[48:49], v[114:115], v[96:97]
	v_pk_fma_f32 v[94:95], v[46:47], v[114:115], v[94:95]
	v_pk_fma_f32 v[92:93], v[44:45], v[114:115], v[92:93]
	v_pk_fma_f32 v[88:89], v[42:43], v[114:115], v[88:89]
	v_pk_fma_f32 v[90:91], v[40:41], v[114:115], v[90:91]
	v_pk_fma_f32 v[86:87], v[38:39], v[114:115], v[86:87]
	v_pk_fma_f32 v[84:85], v[34:35], v[114:115], v[84:85]
	v_pk_fma_f32 v[82:83], v[32:33], v[114:115], v[82:83]
	v_pk_fma_f32 v[80:81], v[30:31], v[114:115], v[80:81]
	v_pk_fma_f32 v[78:79], v[28:29], v[114:115], v[78:79]
	v_pk_fma_f32 v[76:77], v[26:27], v[114:115], v[76:77]
	v_pk_fma_f32 v[74:75], v[24:25], v[114:115], v[74:75]
	v_pk_fma_f32 v[130:131], v[22:23], v[114:115], v[130:131]
	v_pk_fma_f32 v[72:73], v[20:21], v[114:115], v[72:73]
	v_pk_fma_f32 v[100:101], v[18:19], v[114:115], v[100:101]
	v_pk_fma_f32 v[102:103], v[48:49], v[120:121], v[102:103]
	v_pk_fma_f32 v[98:99], v[44:45], v[120:121], v[98:99]
	v_pk_fma_f32 v[114:115], v[64:65], v[116:117], v[66:67]
	v_pk_fma_f32 v[112:113], v[62:63], v[116:117], v[112:113]
	v_pk_fma_f32 v[110:111], v[60:61], v[116:117], v[110:111]
	v_pk_fma_f32 v[108:109], v[58:59], v[116:117], v[108:109]
	v_pk_fma_f32 v[106:107], v[56:57], v[116:117], v[106:107]
	v_pk_fma_f32 v[104:105], v[54:55], v[116:117], v[104:105]
	v_pk_fma_f32 v[132:133], v[50:51], v[116:117], v[132:133]
	v_pk_fma_f32 v[96:97], v[46:47], v[116:117], v[96:97]
	v_pk_fma_f32 v[94:95], v[44:45], v[116:117], v[94:95]
	v_pk_fma_f32 v[92:93], v[42:43], v[116:117], v[92:93]
	v_pk_fma_f32 v[88:89], v[40:41], v[116:117], v[88:89]
	v_pk_fma_f32 v[90:91], v[38:39], v[116:117], v[90:91]
	v_pk_fma_f32 v[86:87], v[34:35], v[116:117], v[86:87]
	v_pk_fma_f32 v[84:85], v[32:33], v[116:117], v[84:85]
	v_pk_fma_f32 v[82:83], v[30:31], v[116:117], v[82:83]
	v_pk_fma_f32 v[80:81], v[28:29], v[116:117], v[80:81]
	v_pk_fma_f32 v[78:79], v[26:27], v[116:117], v[78:79]
	v_pk_fma_f32 v[76:77], v[24:25], v[116:117], v[76:77]
	v_pk_fma_f32 v[74:75], v[22:23], v[116:117], v[74:75]
	v_pk_fma_f32 v[130:131], v[20:21], v[116:117], v[130:131]
	v_pk_fma_f32 v[72:73], v[18:19], v[116:117], v[72:73]
	v_pk_fma_f32 v[100:101], v[16:17], v[116:117], v[100:101]
	v_pk_fma_f32 v[102:103], v[46:47], v[122:123], v[102:103]
	v_pk_fma_f32 v[98:99], v[42:43], v[122:123], v[98:99]
	s_or_b32 s4, s20, 2
	v_pk_fma_f32 v[116:117], v[64:65], v[118:119], v[66:67]
	v_pk_fma_f32 v[114:115], v[62:63], v[118:119], v[114:115]
	v_pk_fma_f32 v[112:113], v[60:61], v[118:119], v[112:113]
	v_pk_fma_f32 v[110:111], v[58:59], v[118:119], v[110:111]
	v_pk_fma_f32 v[108:109], v[56:57], v[118:119], v[108:109]
	v_pk_fma_f32 v[106:107], v[54:55], v[118:119], v[106:107]
	v_pk_fma_f32 v[104:105], v[52:53], v[118:119], v[104:105]
	v_pk_fma_f32 v[132:133], v[48:49], v[118:119], v[132:133]
	v_pk_fma_f32 v[96:97], v[44:45], v[118:119], v[96:97]
	v_pk_fma_f32 v[94:95], v[42:43], v[118:119], v[94:95]
	v_pk_fma_f32 v[92:93], v[40:41], v[118:119], v[92:93]
	v_pk_fma_f32 v[88:89], v[38:39], v[118:119], v[88:89]
	v_pk_fma_f32 v[90:91], v[34:35], v[118:119], v[90:91]
	v_pk_fma_f32 v[86:87], v[32:33], v[118:119], v[86:87]
	v_pk_fma_f32 v[84:85], v[30:31], v[118:119], v[84:85]
	v_pk_fma_f32 v[82:83], v[28:29], v[118:119], v[82:83]
	v_pk_fma_f32 v[80:81], v[26:27], v[118:119], v[80:81]
	v_pk_fma_f32 v[78:79], v[24:25], v[118:119], v[78:79]
	v_pk_fma_f32 v[76:77], v[22:23], v[118:119], v[76:77]
	v_pk_fma_f32 v[74:75], v[20:21], v[118:119], v[74:75]
	v_pk_fma_f32 v[130:131], v[18:19], v[118:119], v[130:131]
	v_pk_fma_f32 v[72:73], v[16:17], v[118:119], v[72:73]
	v_pk_fma_f32 v[100:101], v[12:13], v[118:119], v[100:101]
	v_pk_fma_f32 v[102:103], v[44:45], v[124:125], v[102:103]
	v_pk_fma_f32 v[98:99], v[40:41], v[124:125], v[98:99]
	s_ashr_i32 s5, s4, 31
	v_pk_fma_f32 v[118:119], v[64:65], v[120:121], v[66:67]
	v_pk_fma_f32 v[116:117], v[62:63], v[120:121], v[116:117]
	v_pk_fma_f32 v[114:115], v[60:61], v[120:121], v[114:115]
	v_pk_fma_f32 v[112:113], v[58:59], v[120:121], v[112:113]
	v_pk_fma_f32 v[110:111], v[56:57], v[120:121], v[110:111]
	v_pk_fma_f32 v[108:109], v[54:55], v[120:121], v[108:109]
	v_pk_fma_f32 v[106:107], v[52:53], v[120:121], v[106:107]
	v_pk_fma_f32 v[104:105], v[50:51], v[120:121], v[104:105]
	v_pk_fma_f32 v[132:133], v[46:47], v[120:121], v[132:133]
	v_pk_fma_f32 v[96:97], v[42:43], v[120:121], v[96:97]
	v_pk_fma_f32 v[94:95], v[40:41], v[120:121], v[94:95]
	v_pk_fma_f32 v[92:93], v[38:39], v[120:121], v[92:93]
	v_pk_fma_f32 v[88:89], v[34:35], v[120:121], v[88:89]
	v_pk_fma_f32 v[90:91], v[32:33], v[120:121], v[90:91]
	v_pk_fma_f32 v[86:87], v[30:31], v[120:121], v[86:87]
	v_pk_fma_f32 v[84:85], v[28:29], v[120:121], v[84:85]
	v_pk_fma_f32 v[82:83], v[26:27], v[120:121], v[82:83]
	v_pk_fma_f32 v[80:81], v[24:25], v[120:121], v[80:81]
	v_pk_fma_f32 v[78:79], v[22:23], v[120:121], v[78:79]
	v_pk_fma_f32 v[76:77], v[20:21], v[120:121], v[76:77]
	v_pk_fma_f32 v[74:75], v[18:19], v[120:121], v[74:75]
	v_pk_fma_f32 v[130:131], v[16:17], v[120:121], v[130:131]
	v_pk_fma_f32 v[72:73], v[12:13], v[120:121], v[72:73]
	v_pk_fma_f32 v[100:101], v[14:15], v[120:121], v[100:101]
	v_pk_fma_f32 v[102:103], v[42:43], v[126:127], v[102:103]
	v_pk_fma_f32 v[136:137], v[38:39], v[126:127], v[98:99]
	s_lshl_b64 s[4:5], s[4:5], 11
	v_pk_fma_f32 v[120:121], v[64:65], v[122:123], v[66:67]
	v_pk_fma_f32 v[118:119], v[62:63], v[122:123], v[118:119]
	v_pk_fma_f32 v[116:117], v[60:61], v[122:123], v[116:117]
; __device__ __forceinline__ float bflo(unsigned w) { return __uint_as_float(w << 16); }
; __device__ __forceinline__ float bfhi(unsigned w) { return __uint_as_float(w & 0xffff0000u); }
; __device__ __forceinline__ void conf_unit(const Frame& F, int l, int unit) {
;     ...
;     for (int sg = 0; sg < 64; sg += 16) {
;         f32x2 xg[16];
; #pragma unroll
;         for (int k = 0; k < 16; ++k) { const int s = sg + k; if (s < 62) {
;             const int tg = t0 - 30 + s; f32x2 x;
;             if (tg >= 0) { const unsigned u = *(const unsigned*)(GLU + (size_t)(r0 - 30 + s) * WL + tid2); x = (f32x2){bflo(u), bfhi(u)}; }
;             else if (samp) x = *(const f32x2*)(A.in[I_SCC] + ((size_t)(l * DB + ri.b) * 30 + (30 + tg)) * WL + tid2);
;             else x = (f32x2){0.f, 0.f};
;             xg[k] = x; } }
; #pragma unroll
;         for (int k = 0; k < 16; ++k) { const int s = sg + k; if (s < 62) {
; #pragma unroll
;             for (int j = 0; j < 31; ++j) { const int t = s - j; if (t >= 0 && t < 32) acc[t] += w[j] * xg[k]; } } }
;         asm volatile("" ::: "memory");
;     }
	v_pk_fma_f32 v[114:115], v[58:59], v[122:123], v[114:115]
	v_pk_fma_f32 v[112:113], v[56:57], v[122:123], v[112:113]
	v_pk_fma_f32 v[110:111], v[54:55], v[122:123], v[110:111]
	v_pk_fma_f32 v[108:109], v[52:53], v[122:123], v[108:109]
	v_pk_fma_f32 v[106:107], v[50:51], v[122:123], v[106:107]
	v_pk_fma_f32 v[104:105], v[48:49], v[122:123], v[104:105]
	v_pk_fma_f32 v[132:133], v[44:45], v[122:123], v[132:133]
	v_pk_fma_f32 v[96:97], v[40:41], v[122:123], v[96:97]
	v_pk_fma_f32 v[94:95], v[38:39], v[122:123], v[94:95]
	v_pk_fma_f32 v[92:93], v[34:35], v[122:123], v[92:93]
	v_pk_fma_f32 v[88:89], v[32:33], v[122:123], v[88:89]
	v_pk_fma_f32 v[90:91], v[30:31], v[122:123], v[90:91]
	v_pk_fma_f32 v[86:87], v[28:29], v[122:123], v[86:87]
	v_pk_fma_f32 v[84:85], v[26:27], v[122:123], v[84:85]
	v_pk_fma_f32 v[82:83], v[24:25], v[122:123], v[82:83]
	v_pk_fma_f32 v[80:81], v[22:23], v[122:123], v[80:81]
	v_pk_fma_f32 v[78:79], v[20:21], v[122:123], v[78:79]
	v_pk_fma_f32 v[76:77], v[18:19], v[122:123], v[76:77]
	v_pk_fma_f32 v[74:75], v[16:17], v[122:123], v[74:75]
	v_pk_fma_f32 v[130:131], v[12:13], v[122:123], v[130:131]
	v_pk_fma_f32 v[72:73], v[14:15], v[122:123], v[72:73]
	v_pk_fma_f32 v[100:101], v[10:11], v[122:123], v[100:101]
	v_pk_fma_f32 v[98:99], v[40:41], v[128:129], v[102:103]
	v_pk_fma_f32 v[102:103], v[34:35], v[128:129], v[136:137]
	v_lshl_add_u64 v[136:137], v[36:37], 0, s[4:5]
	s_or_b32 s4, s20, 3
	v_pk_fma_f32 v[122:123], v[64:65], v[124:125], v[66:67]
	v_pk_fma_f32 v[120:121], v[62:63], v[124:125], v[120:121]
	v_pk_fma_f32 v[118:119], v[60:61], v[124:125], v[118:119]
	v_pk_fma_f32 v[116:117], v[58:59], v[124:125], v[116:117]
	v_pk_fma_f32 v[114:115], v[56:57], v[124:125], v[114:115]
	v_pk_fma_f32 v[112:113], v[54:55], v[124:125], v[112:113]
	v_pk_fma_f32 v[110:111], v[52:53], v[124:125], v[110:111]
	v_pk_fma_f32 v[108:109], v[50:51], v[124:125], v[108:109]
	v_pk_fma_f32 v[106:107], v[48:49], v[124:125], v[106:107]
	v_pk_fma_f32 v[104:105], v[46:47], v[124:125], v[104:105]
	v_pk_fma_f32 v[132:133], v[42:43], v[124:125], v[132:133]
	v_pk_fma_f32 v[96:97], v[38:39], v[124:125], v[96:97]
	v_pk_fma_f32 v[94:95], v[34:35], v[124:125], v[94:95]
	v_pk_fma_f32 v[92:93], v[32:33], v[124:125], v[92:93]
	v_pk_fma_f32 v[88:89], v[30:31], v[124:125], v[88:89]
	v_pk_fma_f32 v[90:91], v[28:29], v[124:125], v[90:91]
	v_pk_fma_f32 v[86:87], v[26:27], v[124:125], v[86:87]
	v_pk_fma_f32 v[84:85], v[24:25], v[124:125], v[84:85]
	v_pk_fma_f32 v[82:83], v[22:23], v[124:125], v[82:83]
	v_pk_fma_f32 v[80:81], v[20:21], v[124:125], v[80:81]
	v_pk_fma_f32 v[78:79], v[18:19], v[124:125], v[78:79]
	v_pk_fma_f32 v[76:77], v[16:17], v[124:125], v[76:77]
	v_pk_fma_f32 v[74:75], v[12:13], v[124:125], v[74:75]
	v_pk_fma_f32 v[130:131], v[14:15], v[124:125], v[130:131]
	v_pk_fma_f32 v[72:73], v[10:11], v[124:125], v[72:73]
	v_pk_fma_f32 v[100:101], v[6:7], v[124:125], v[100:101]
	s_ashr_i32 s5, s4, 31
	v_pk_fma_f32 v[124:125], v[64:65], v[126:127], v[66:67]
	v_pk_fma_f32 v[122:123], v[62:63], v[126:127], v[122:123]
	v_pk_fma_f32 v[120:121], v[60:61], v[126:127], v[120:121]
	v_pk_fma_f32 v[118:119], v[58:59], v[126:127], v[118:119]
	v_pk_fma_f32 v[116:117], v[56:57], v[126:127], v[116:117]
	v_pk_fma_f32 v[114:115], v[54:55], v[126:127], v[114:115]
	v_pk_fma_f32 v[112:113], v[52:53], v[126:127], v[112:113]
	v_pk_fma_f32 v[110:111], v[50:51], v[126:127], v[110:111]
	v_pk_fma_f32 v[108:109], v[48:49], v[126:127], v[108:109]
	v_pk_fma_f32 v[106:107], v[46:47], v[126:127], v[106:107]
	v_pk_fma_f32 v[104:105], v[44:45], v[126:127], v[104:105]
	v_pk_fma_f32 v[132:133], v[40:41], v[126:127], v[132:133]
	v_pk_fma_f32 v[96:97], v[34:35], v[126:127], v[96:97]
	v_pk_fma_f32 v[94:95], v[32:33], v[126:127], v[94:95]
	v_pk_fma_f32 v[92:93], v[30:31], v[126:127], v[92:93]
	v_pk_fma_f32 v[88:89], v[28:29], v[126:127], v[88:89]
	v_pk_fma_f32 v[90:91], v[26:27], v[126:127], v[90:91]
	v_pk_fma_f32 v[86:87], v[24:25], v[126:127], v[86:87]
	v_pk_fma_f32 v[84:85], v[22:23], v[126:127], v[84:85]
	v_pk_fma_f32 v[82:83], v[20:21], v[126:127], v[82:83]
	v_pk_fma_f32 v[80:81], v[18:19], v[126:127], v[80:81]
	v_pk_fma_f32 v[78:79], v[16:17], v[126:127], v[78:79]
	v_pk_fma_f32 v[76:77], v[12:13], v[126:127], v[76:77]
	v_pk_fma_f32 v[74:75], v[14:15], v[126:127], v[74:75]
	v_pk_fma_f32 v[130:131], v[10:11], v[126:127], v[130:131]
	v_pk_fma_f32 v[72:73], v[6:7], v[126:127], v[72:73]
	v_pk_fma_f32 v[138:139], v[2:3], v[126:127], v[100:101]
	s_lshl_b64 s[4:5], s[4:5], 11
	v_pk_fma_f32 v[140:141], v[64:65], v[128:129], v[66:67]
	v_pk_fma_f32 v[142:143], v[62:63], v[128:129], v[124:125]
	v_pk_fma_f32 v[144:145], v[60:61], v[128:129], v[122:123]
	v_pk_fma_f32 v[146:147], v[58:59], v[128:129], v[120:121]
	v_pk_fma_f32 v[148:149], v[56:57], v[128:129], v[118:119]
	v_pk_fma_f32 v[150:151], v[54:55], v[128:129], v[116:117]
	v_pk_fma_f32 v[152:153], v[52:53], v[128:129], v[114:115]
	v_pk_fma_f32 v[154:155], v[50:51], v[128:129], v[112:113]
	v_pk_fma_f32 v[156:157], v[48:49], v[128:129], v[110:111]
	v_pk_fma_f32 v[158:159], v[46:47], v[128:129], v[108:109]
	v_pk_fma_f32 v[160:161], v[44:45], v[128:129], v[106:107]
	v_pk_fma_f32 v[162:163], v[42:43], v[128:129], v[104:105]
	v_pk_fma_f32 v[100:101], v[38:39], v[128:129], v[132:133]
	v_pk_fma_f32 v[104:105], v[32:33], v[128:129], v[96:97]
	v_pk_fma_f32 v[106:107], v[30:31], v[128:129], v[94:95]
	v_pk_fma_f32 v[108:109], v[28:29], v[128:129], v[92:93]
	v_pk_fma_f32 v[110:111], v[26:27], v[128:129], v[88:89]
	v_pk_fma_f32 v[112:113], v[24:25], v[128:129], v[90:91]
	v_pk_fma_f32 v[114:115], v[22:23], v[128:129], v[86:87]
	v_pk_fma_f32 v[116:117], v[20:21], v[128:129], v[84:85]
; __device__ __forceinline__ float bflo(unsigned w) { return __uint_as_float(w << 16); }
; __device__ __forceinline__ float bfhi(unsigned w) { return __uint_as_float(w & 0xffff0000u); }
; __device__ __forceinline__ void conf_unit(const Frame& F, int l, int unit) {
;     ...
;     for (int sg = 0; sg < 64; sg += 16) {
;         f32x2 xg[16];
; #pragma unroll
;         for (int k = 0; k < 16; ++k) { const int s = sg + k; if (s < 62) {
;             const int tg = t0 - 30 + s; f32x2 x;
;             if (tg >= 0) { const unsigned u = *(const unsigned*)(GLU + (size_t)(r0 - 30 + s) * WL + tid2); x = (f32x2){bflo(u), bfhi(u)}; }
;             else if (samp) x = *(const f32x2*)(A.in[I_SCC] + ((size_t)(l * DB + ri.b) * 30 + (30 + tg)) * WL + tid2);
;             else x = (f32x2){0.f, 0.f};
;             xg[k] = x; } }
; #pragma unroll
;         for (int k = 0; k < 16; ++k) { const int s = sg + k; if (s < 62) {
; #pragma unroll
;             for (int j = 0; j < 31; ++j) { const int t = s - j; if (t >= 0 && t < 32) acc[t] += w[j] * xg[k]; } } }
;         asm volatile("" ::: "memory");
;     }
	v_pk_fma_f32 v[118:119], v[18:19], v[128:129], v[82:83]
	v_pk_fma_f32 v[120:121], v[16:17], v[128:129], v[80:81]
	v_pk_fma_f32 v[122:123], v[12:13], v[128:129], v[78:79]
	v_pk_fma_f32 v[124:125], v[14:15], v[128:129], v[76:77]
	v_pk_fma_f32 v[126:127], v[10:11], v[128:129], v[74:75]
	v_pk_fma_f32 v[130:131], v[6:7], v[128:129], v[130:131]
	v_pk_fma_f32 v[132:133], v[2:3], v[128:129], v[72:73]
	v_pk_fma_f32 v[128:129], v[8:9], v[128:129], v[138:139]
	v_lshl_add_u64 v[138:139], v[36:37], 0, s[4:5]
	s_or_b32 s4, s20, 4
	s_ashr_i32 s5, s4, 31
	v_lshlrev_b32_e32 v68, 16, v1
	v_and_b32_e32 v69, 0xffff0000, v1
	s_lshl_b64 s[4:5], s[4:5], 11
	v_pk_fma_f32 v[74:75], v[62:63], v[68:69], v[140:141]
	v_lshl_add_u64 v[140:141], v[36:37], 0, s[4:5]
	s_or_b32 s4, s20, 5
	s_ashr_i32 s5, s4, 31
	s_lshl_b64 s[4:5], s[4:5], 11
	v_pk_fma_f32 v[76:77], v[60:61], v[68:69], v[142:143]
	v_lshl_add_u64 v[142:143], v[36:37], 0, s[4:5]
	s_or_b32 s4, s20, 6
	s_ashr_i32 s5, s4, 31
	s_lshl_b64 s[4:5], s[4:5], 11
	v_pk_fma_f32 v[78:79], v[58:59], v[68:69], v[144:145]
	v_lshl_add_u64 v[144:145], v[36:37], 0, s[4:5]
	s_or_b32 s4, s20, 7
	s_ashr_i32 s5, s4, 31
	s_lshl_b64 s[4:5], s[4:5], 11
	v_pk_fma_f32 v[80:81], v[56:57], v[68:69], v[146:147]
	v_lshl_add_u64 v[146:147], v[36:37], 0, s[4:5]
	s_or_b32 s4, s20, 8
	s_ashr_i32 s5, s4, 31
	s_lshl_b64 s[4:5], s[4:5], 11
	v_pk_fma_f32 v[82:83], v[54:55], v[68:69], v[148:149]
	v_lshl_add_u64 v[148:149], v[36:37], 0, s[4:5]
	s_or_b32 s4, s20, 9
	s_ashr_i32 s5, s4, 31
	s_lshl_b64 s[4:5], s[4:5], 11
	v_pk_fma_f32 v[84:85], v[52:53], v[68:69], v[150:151]
	v_lshl_add_u64 v[150:151], v[36:37], 0, s[4:5]
	s_or_b32 s4, s20, 10
	s_ashr_i32 s5, s4, 31
	s_lshl_b64 s[4:5], s[4:5], 11
	v_pk_fma_f32 v[86:87], v[50:51], v[68:69], v[152:153]
	v_pk_fma_f32 v[88:89], v[48:49], v[68:69], v[154:155]
	v_pk_fma_f32 v[90:91], v[46:47], v[68:69], v[156:157]
	v_pk_fma_f32 v[92:93], v[44:45], v[68:69], v[158:159]
	global_load_dword v1, v[136:137], off
	global_load_dword v135, v[138:139], off
	global_load_dword v152, v[140:141], off
	global_load_dword v153, v[142:143], off
	global_load_dword v154, v[144:145], off
	global_load_dword v155, v[146:147], off
	global_load_dword v157, v[148:149], off
	global_load_dword v159, v[150:151], off
	v_lshl_add_u64 v[136:137], v[36:37], 0, s[4:5]
	s_or_b32 s4, s20, 11
	s_ashr_i32 s5, s4, 31
	s_lshl_b64 s[4:5], s[4:5], 11
	v_lshl_add_u64 v[138:139], v[36:37], 0, s[4:5]
	s_or_b32 s4, s20, 12
	s_ashr_i32 s5, s4, 31
	s_lshl_b64 s[4:5], s[4:5], 11
	v_lshl_add_u64 v[140:141], v[36:37], 0, s[4:5]
	s_or_b32 s4, s20, 13
	s_ashr_i32 s5, s4, 31
	s_lshl_b64 s[4:5], s[4:5], 11
	v_pk_fma_f32 v[94:95], v[42:43], v[68:69], v[160:161]
	v_pk_fma_f32 v[96:97], v[40:41], v[68:69], v[162:163]
	global_load_dword v161, v[136:137], off
	global_load_dword v162, v[138:139], off
	global_load_dword v163, v[140:141], off
	v_lshl_add_u64 v[136:137], v[36:37], 0, s[4:5]
	s_or_b32 s4, s20, 14
	s_ashr_i32 s5, s4, 31
	s_lshl_b64 s[4:5], s[4:5], 11
	v_lshl_add_u64 v[138:139], v[36:37], 0, s[4:5]
	s_or_b32 s4, s20, 15
	s_ashr_i32 s5, s4, 31
	s_lshl_b64 s[4:5], s[4:5], 11
	v_lshl_add_u64 v[140:141], v[36:37], 0, s[4:5]
	s_or_b32 s4, s20, 16
	s_ashr_i32 s5, s4, 31
	s_lshl_b64 s[4:5], s[4:5], 11
	v_lshl_add_u64 v[142:143], v[36:37], 0, s[4:5]
	global_load_dword v164, v[136:137], off
	global_load_dword v165, v[138:139], off
	global_load_dword v166, v[140:141], off
	global_load_dword v167, v[142:143], off
	s_or_b32 s4, s20, 17
	s_ashr_i32 s5, s4, 31
	s_lshl_b64 s[4:5], s[4:5], 11
	v_pk_fma_f32 v[72:73], v[64:65], v[68:69], v[66:67]
	v_lshl_add_u64 v[136:137], v[36:37], 0, s[4:5]
	v_pk_fma_f32 v[132:133], v[8:9], v[68:69], v[132:133]
	global_load_dword v168, v[136:137], off
	v_pk_fma_f32 v[98:99], v[38:39], v[68:69], v[98:99]
	v_pk_fma_f32 v[100:101], v[34:35], v[68:69], v[100:101]
	v_pk_fma_f32 v[102:103], v[32:33], v[68:69], v[102:103]
	v_pk_fma_f32 v[104:105], v[30:31], v[68:69], v[104:105]
	v_pk_fma_f32 v[106:107], v[28:29], v[68:69], v[106:107]
	v_pk_fma_f32 v[108:109], v[26:27], v[68:69], v[108:109]
	v_pk_fma_f32 v[110:111], v[24:25], v[68:69], v[110:111]
	v_pk_fma_f32 v[112:113], v[22:23], v[68:69], v[112:113]
	v_pk_fma_f32 v[114:115], v[20:21], v[68:69], v[114:115]
	v_pk_fma_f32 v[116:117], v[18:19], v[68:69], v[116:117]
	v_pk_fma_f32 v[118:119], v[16:17], v[68:69], v[118:119]
	v_pk_fma_f32 v[120:121], v[12:13], v[68:69], v[120:121]
	v_pk_fma_f32 v[122:123], v[14:15], v[68:69], v[122:123]
	v_pk_fma_f32 v[124:125], v[10:11], v[68:69], v[124:125]
	v_pk_fma_f32 v[126:127], v[6:7], v[68:69], v[126:127]
	v_pk_fma_f32 v[130:131], v[2:3], v[68:69], v[130:131]
	v_pk_fma_f32 v[68:69], v[4:5], v[68:69], v[128:129]
	v_pk_fma_f32 v[128:129], v[64:65], v[70:71], v[66:67]
	v_pk_fma_f32 v[136:137], v[62:63], v[70:71], v[72:73]
	v_pk_fma_f32 v[138:139], v[60:61], v[70:71], v[74:75]
	v_pk_fma_f32 v[140:141], v[58:59], v[70:71], v[76:77]
	v_pk_fma_f32 v[64:65], v[4:5], v[70:71], v[132:133]
	v_pk_fma_f32 v[142:143], v[56:57], v[70:71], v[78:79]
	v_pk_fma_f32 v[144:145], v[54:55], v[70:71], v[80:81]
	v_pk_fma_f32 v[82:83], v[52:53], v[70:71], v[82:83]
	v_pk_fma_f32 v[84:85], v[50:51], v[70:71], v[84:85]
	v_pk_fma_f32 v[86:87], v[48:49], v[70:71], v[86:87]
	v_pk_fma_f32 v[88:89], v[46:47], v[70:71], v[88:89]
	v_pk_fma_f32 v[90:91], v[44:45], v[70:71], v[90:91]
	v_pk_fma_f32 v[92:93], v[42:43], v[70:71], v[92:93]
	v_pk_fma_f32 v[94:95], v[40:41], v[70:71], v[94:95]
	v_pk_fma_f32 v[96:97], v[38:39], v[70:71], v[96:97]
	v_pk_fma_f32 v[98:99], v[34:35], v[70:71], v[98:99]
	v_pk_fma_f32 v[100:101], v[32:33], v[70:71], v[100:101]
	v_pk_fma_f32 v[102:103], v[30:31], v[70:71], v[102:103]
	v_pk_fma_f32 v[104:105], v[28:29], v[70:71], v[104:105]
	s_waitcnt vmcnt(15)
; __device__ __forceinline__ float bflo(unsigned w) { return __uint_as_float(w << 16); }
; __device__ __forceinline__ float bfhi(unsigned w) { return __uint_as_float(w & 0xffff0000u); }
; __device__ __forceinline__ void conf_unit(const Frame& F, int l, int unit) {
;     ...
;     for (int sg = 0; sg < 64; sg += 16) {
;         f32x2 xg[16];
; #pragma unroll
;         for (int k = 0; k < 16; ++k) { const int s = sg + k; if (s < 62) {
;             const int tg = t0 - 30 + s; f32x2 x;
;             if (tg >= 0) { const unsigned u = *(const unsigned*)(GLU + (size_t)(r0 - 30 + s) * WL + tid2); x = (f32x2){bflo(u), bfhi(u)}; }
;             else if (samp) x = *(const f32x2*)(A.in[I_SCC] + ((size_t)(l * DB + ri.b) * 30 + (30 + tg)) * WL + tid2);
;             else x = (f32x2){0.f, 0.f};
;             xg[k] = x; } }
; #pragma unroll
;         for (int k = 0; k < 16; ++k) { const int s = sg + k; if (s < 62) {
; #pragma unroll
;             for (int j = 0; j < 31; ++j) { const int t = s - j; if (t >= 0 && t < 32) acc[t] += w[j] * xg[k]; } } }
;         asm volatile("" ::: "memory");
;     }
	v_lshlrev_b32_e32 v132, 16, v1
	v_and_b32_e32 v133, 0xffff0000, v1
	v_pk_fma_f32 v[106:107], v[26:27], v[70:71], v[106:107]
	v_pk_fma_f32 v[108:109], v[24:25], v[70:71], v[108:109]
	v_pk_fma_f32 v[110:111], v[22:23], v[70:71], v[110:111]
	v_pk_fma_f32 v[112:113], v[20:21], v[70:71], v[112:113]
	v_pk_fma_f32 v[114:115], v[18:19], v[70:71], v[114:115]
	v_pk_fma_f32 v[116:117], v[16:17], v[70:71], v[116:117]
	v_pk_fma_f32 v[118:119], v[12:13], v[70:71], v[118:119]
	v_pk_fma_f32 v[120:121], v[14:15], v[70:71], v[120:121]
	v_pk_fma_f32 v[122:123], v[10:11], v[70:71], v[122:123]
	v_pk_fma_f32 v[124:125], v[6:7], v[70:71], v[124:125]
	v_pk_fma_f32 v[126:127], v[2:3], v[70:71], v[126:127]
	v_pk_fma_f32 v[130:131], v[8:9], v[70:71], v[130:131]
	s_waitcnt vmcnt(14)
	v_lshlrev_b32_e32 v146, 16, v135
	v_and_b32_e32 v147, 0xffff0000, v135
	v_pk_fma_f32 v[128:129], v[62:63], v[132:133], v[128:129]
	v_pk_fma_f32 v[136:137], v[60:61], v[132:133], v[136:137]
	v_pk_fma_f32 v[138:139], v[58:59], v[132:133], v[138:139]
	v_pk_fma_f32 v[140:141], v[56:57], v[132:133], v[140:141]
	s_waitcnt vmcnt(13)
	v_lshlrev_b32_e32 v148, 16, v152
	v_and_b32_e32 v149, 0xffff0000, v152
	v_pk_fma_f32 v[142:143], v[54:55], v[132:133], v[142:143]
	v_pk_fma_f32 v[144:145], v[52:53], v[132:133], v[144:145]
	v_pk_fma_f32 v[82:83], v[50:51], v[132:133], v[82:83]
	v_pk_fma_f32 v[84:85], v[48:49], v[132:133], v[84:85]
	v_pk_fma_f32 v[86:87], v[46:47], v[132:133], v[86:87]
	v_pk_fma_f32 v[88:89], v[44:45], v[132:133], v[88:89]
	v_pk_fma_f32 v[90:91], v[42:43], v[132:133], v[90:91]
	v_pk_fma_f32 v[92:93], v[40:41], v[132:133], v[92:93]
	v_pk_fma_f32 v[94:95], v[38:39], v[132:133], v[94:95]
	v_pk_fma_f32 v[96:97], v[34:35], v[132:133], v[96:97]
	v_pk_fma_f32 v[98:99], v[32:33], v[132:133], v[98:99]
	v_pk_fma_f32 v[100:101], v[30:31], v[132:133], v[100:101]
	v_pk_fma_f32 v[102:103], v[28:29], v[132:133], v[102:103]
	v_pk_fma_f32 v[104:105], v[26:27], v[132:133], v[104:105]
	v_pk_fma_f32 v[106:107], v[24:25], v[132:133], v[106:107]
	v_pk_fma_f32 v[108:109], v[22:23], v[132:133], v[108:109]
	v_pk_fma_f32 v[110:111], v[20:21], v[132:133], v[110:111]
	v_pk_fma_f32 v[112:113], v[18:19], v[132:133], v[112:113]
	v_pk_fma_f32 v[114:115], v[16:17], v[132:133], v[114:115]
	v_pk_fma_f32 v[116:117], v[12:13], v[132:133], v[116:117]
	v_pk_fma_f32 v[118:119], v[14:15], v[132:133], v[118:119]
	v_pk_fma_f32 v[120:121], v[10:11], v[132:133], v[120:121]
	v_pk_fma_f32 v[122:123], v[6:7], v[132:133], v[122:123]
	v_pk_fma_f32 v[124:125], v[2:3], v[132:133], v[124:125]
	v_pk_fma_f32 v[126:127], v[8:9], v[132:133], v[126:127]
	v_pk_fma_f32 v[62:63], v[4:5], v[132:133], v[130:131]
	v_pk_fma_f32 v[128:129], v[60:61], v[146:147], v[128:129]
	v_pk_fma_f32 v[130:131], v[58:59], v[146:147], v[136:137]
	v_pk_fma_f32 v[132:133], v[56:57], v[146:147], v[138:139]
	v_pk_fma_f32 v[136:137], v[54:55], v[146:147], v[140:141]
	s_waitcnt vmcnt(12)
	v_lshlrev_b32_e32 v150, 16, v153
	v_and_b32_e32 v151, 0xffff0000, v153
	v_pk_fma_f32 v[138:139], v[52:53], v[146:147], v[142:143]
	v_pk_fma_f32 v[140:141], v[50:51], v[146:147], v[144:145]
	v_pk_fma_f32 v[82:83], v[48:49], v[146:147], v[82:83]
	v_pk_fma_f32 v[84:85], v[46:47], v[146:147], v[84:85]
	v_pk_fma_f32 v[86:87], v[44:45], v[146:147], v[86:87]
	v_pk_fma_f32 v[88:89], v[42:43], v[146:147], v[88:89]
	v_pk_fma_f32 v[90:91], v[40:41], v[146:147], v[90:91]
	v_pk_fma_f32 v[92:93], v[38:39], v[146:147], v[92:93]
	v_pk_fma_f32 v[94:95], v[34:35], v[146:147], v[94:95]
	v_pk_fma_f32 v[96:97], v[32:33], v[146:147], v[96:97]
	v_pk_fma_f32 v[98:99], v[30:31], v[146:147], v[98:99]
	v_pk_fma_f32 v[100:101], v[28:29], v[146:147], v[100:101]
	v_pk_fma_f32 v[102:103], v[26:27], v[146:147], v[102:103]
	v_pk_fma_f32 v[104:105], v[24:25], v[146:147], v[104:105]
	v_pk_fma_f32 v[106:107], v[22:23], v[146:147], v[106:107]
	v_pk_fma_f32 v[108:109], v[20:21], v[146:147], v[108:109]
	v_pk_fma_f32 v[110:111], v[18:19], v[146:147], v[110:111]
	v_pk_fma_f32 v[112:113], v[16:17], v[146:147], v[112:113]
	v_pk_fma_f32 v[114:115], v[12:13], v[146:147], v[114:115]
	v_pk_fma_f32 v[116:117], v[14:15], v[146:147], v[116:117]
	v_pk_fma_f32 v[118:119], v[10:11], v[146:147], v[118:119]
	v_pk_fma_f32 v[120:121], v[6:7], v[146:147], v[120:121]
	v_pk_fma_f32 v[122:123], v[2:3], v[146:147], v[122:123]
	v_pk_fma_f32 v[124:125], v[8:9], v[146:147], v[124:125]
	v_pk_fma_f32 v[60:61], v[4:5], v[146:147], v[126:127]
	v_pk_fma_f32 v[126:127], v[58:59], v[148:149], v[128:129]
	v_pk_fma_f32 v[128:129], v[56:57], v[148:149], v[130:131]
	v_pk_fma_f32 v[130:131], v[54:55], v[148:149], v[132:133]
	v_pk_fma_f32 v[132:133], v[52:53], v[148:149], v[136:137]
	s_waitcnt vmcnt(11)
	v_lshlrev_b32_e32 v152, 16, v154
	v_and_b32_e32 v153, 0xffff0000, v154
	v_pk_fma_f32 v[136:137], v[50:51], v[148:149], v[138:139]
	v_pk_fma_f32 v[138:139], v[48:49], v[148:149], v[140:141]
	v_pk_fma_f32 v[82:83], v[46:47], v[148:149], v[82:83]
	v_pk_fma_f32 v[84:85], v[44:45], v[148:149], v[84:85]
	v_pk_fma_f32 v[86:87], v[42:43], v[148:149], v[86:87]
	v_pk_fma_f32 v[88:89], v[40:41], v[148:149], v[88:89]
	v_pk_fma_f32 v[90:91], v[38:39], v[148:149], v[90:91]
	v_pk_fma_f32 v[92:93], v[34:35], v[148:149], v[92:93]
	v_pk_fma_f32 v[94:95], v[32:33], v[148:149], v[94:95]
	v_pk_fma_f32 v[96:97], v[30:31], v[148:149], v[96:97]
	v_pk_fma_f32 v[98:99], v[28:29], v[148:149], v[98:99]
	v_pk_fma_f32 v[100:101], v[26:27], v[148:149], v[100:101]
	v_pk_fma_f32 v[102:103], v[24:25], v[148:149], v[102:103]
	v_pk_fma_f32 v[104:105], v[22:23], v[148:149], v[104:105]
	v_pk_fma_f32 v[106:107], v[20:21], v[148:149], v[106:107]
	v_pk_fma_f32 v[108:109], v[18:19], v[148:149], v[108:109]
	v_pk_fma_f32 v[110:111], v[16:17], v[148:149], v[110:111]
	v_pk_fma_f32 v[112:113], v[12:13], v[148:149], v[112:113]
	v_pk_fma_f32 v[114:115], v[14:15], v[148:149], v[114:115]
	v_pk_fma_f32 v[116:117], v[10:11], v[148:149], v[116:117]
	v_pk_fma_f32 v[118:119], v[6:7], v[148:149], v[118:119]
	v_pk_fma_f32 v[120:121], v[2:3], v[148:149], v[120:121]
	v_pk_fma_f32 v[122:123], v[8:9], v[148:149], v[122:123]
	v_pk_fma_f32 v[58:59], v[4:5], v[148:149], v[124:125]
	v_pk_fma_f32 v[124:125], v[56:57], v[150:151], v[126:127]
	v_pk_fma_f32 v[126:127], v[54:55], v[150:151], v[128:129]
	v_pk_fma_f32 v[128:129], v[52:53], v[150:151], v[130:131]
	v_pk_fma_f32 v[130:131], v[50:51], v[150:151], v[132:133]
	s_waitcnt vmcnt(10)
; __device__ __forceinline__ float bflo(unsigned w) { return __uint_as_float(w << 16); }
; __device__ __forceinline__ float bfhi(unsigned w) { return __uint_as_float(w & 0xffff0000u); }
; __device__ __forceinline__ void conf_unit(const Frame& F, int l, int unit) {
;     ...
;     for (int sg = 0; sg < 64; sg += 16) {
;         f32x2 xg[16];
; #pragma unroll
;         for (int k = 0; k < 16; ++k) { const int s = sg + k; if (s < 62) {
;             const int tg = t0 - 30 + s; f32x2 x;
;             if (tg >= 0) { const unsigned u = *(const unsigned*)(GLU + (size_t)(r0 - 30 + s) * WL + tid2); x = (f32x2){bflo(u), bfhi(u)}; }
;             else if (samp) x = *(const f32x2*)(A.in[I_SCC] + ((size_t)(l * DB + ri.b) * 30 + (30 + tg)) * WL + tid2);
;             else x = (f32x2){0.f, 0.f};
;             xg[k] = x; } }
; #pragma unroll
;         for (int k = 0; k < 16; ++k) { const int s = sg + k; if (s < 62) {
; #pragma unroll
;             for (int j = 0; j < 31; ++j) { const int t = s - j; if (t >= 0 && t < 32) acc[t] += w[j] * xg[k]; } } }
;         asm volatile("" ::: "memory");
;     }
	v_lshlrev_b32_e32 v154, 16, v155
	v_and_b32_e32 v155, 0xffff0000, v155
	v_pk_fma_f32 v[132:133], v[48:49], v[150:151], v[136:137]
	v_pk_fma_f32 v[136:137], v[46:47], v[150:151], v[138:139]
	v_pk_fma_f32 v[82:83], v[44:45], v[150:151], v[82:83]
	v_pk_fma_f32 v[84:85], v[42:43], v[150:151], v[84:85]
	v_pk_fma_f32 v[86:87], v[40:41], v[150:151], v[86:87]
	v_pk_fma_f32 v[88:89], v[38:39], v[150:151], v[88:89]
	v_pk_fma_f32 v[90:91], v[34:35], v[150:151], v[90:91]
	v_pk_fma_f32 v[92:93], v[32:33], v[150:151], v[92:93]
	v_pk_fma_f32 v[94:95], v[30:31], v[150:151], v[94:95]
	v_pk_fma_f32 v[96:97], v[28:29], v[150:151], v[96:97]
	v_pk_fma_f32 v[98:99], v[26:27], v[150:151], v[98:99]
	v_pk_fma_f32 v[100:101], v[24:25], v[150:151], v[100:101]
	v_pk_fma_f32 v[102:103], v[22:23], v[150:151], v[102:103]
	v_pk_fma_f32 v[104:105], v[20:21], v[150:151], v[104:105]
	v_pk_fma_f32 v[106:107], v[18:19], v[150:151], v[106:107]
	v_pk_fma_f32 v[108:109], v[16:17], v[150:151], v[108:109]
	v_pk_fma_f32 v[110:111], v[12:13], v[150:151], v[110:111]
	v_pk_fma_f32 v[112:113], v[14:15], v[150:151], v[112:113]
	v_pk_fma_f32 v[114:115], v[10:11], v[150:151], v[114:115]
	v_pk_fma_f32 v[116:117], v[6:7], v[150:151], v[116:117]
	v_pk_fma_f32 v[118:119], v[2:3], v[150:151], v[118:119]
	v_pk_fma_f32 v[120:121], v[8:9], v[150:151], v[120:121]
	v_pk_fma_f32 v[56:57], v[4:5], v[150:151], v[122:123]
	v_pk_fma_f32 v[122:123], v[54:55], v[152:153], v[124:125]
	v_pk_fma_f32 v[124:125], v[52:53], v[152:153], v[126:127]
	v_pk_fma_f32 v[126:127], v[50:51], v[152:153], v[128:129]
	v_pk_fma_f32 v[128:129], v[48:49], v[152:153], v[130:131]
	s_waitcnt vmcnt(9)
	v_lshlrev_b32_e32 v156, 16, v157
	v_and_b32_e32 v157, 0xffff0000, v157
	v_pk_fma_f32 v[130:131], v[46:47], v[152:153], v[132:133]
	v_pk_fma_f32 v[132:133], v[44:45], v[152:153], v[136:137]
	v_pk_fma_f32 v[82:83], v[42:43], v[152:153], v[82:83]
	v_pk_fma_f32 v[84:85], v[40:41], v[152:153], v[84:85]
	v_pk_fma_f32 v[86:87], v[38:39], v[152:153], v[86:87]
	v_pk_fma_f32 v[88:89], v[34:35], v[152:153], v[88:89]
	v_pk_fma_f32 v[90:91], v[32:33], v[152:153], v[90:91]
	v_pk_fma_f32 v[92:93], v[30:31], v[152:153], v[92:93]
	v_pk_fma_f32 v[94:95], v[28:29], v[152:153], v[94:95]
	v_pk_fma_f32 v[96:97], v[26:27], v[152:153], v[96:97]
	v_pk_fma_f32 v[98:99], v[24:25], v[152:153], v[98:99]
	v_pk_fma_f32 v[100:101], v[22:23], v[152:153], v[100:101]
	v_pk_fma_f32 v[102:103], v[20:21], v[152:153], v[102:103]
	v_pk_fma_f32 v[104:105], v[18:19], v[152:153], v[104:105]
	v_pk_fma_f32 v[106:107], v[16:17], v[152:153], v[106:107]
	v_pk_fma_f32 v[108:109], v[12:13], v[152:153], v[108:109]
	v_pk_fma_f32 v[110:111], v[14:15], v[152:153], v[110:111]
	v_pk_fma_f32 v[112:113], v[10:11], v[152:153], v[112:113]
	v_pk_fma_f32 v[114:115], v[6:7], v[152:153], v[114:115]
	v_pk_fma_f32 v[116:117], v[2:3], v[152:153], v[116:117]
	v_pk_fma_f32 v[118:119], v[8:9], v[152:153], v[118:119]
	v_pk_fma_f32 v[54:55], v[4:5], v[152:153], v[120:121]
	v_pk_fma_f32 v[120:121], v[52:53], v[154:155], v[122:123]
	v_pk_fma_f32 v[122:123], v[50:51], v[154:155], v[124:125]
	v_pk_fma_f32 v[124:125], v[48:49], v[154:155], v[126:127]
	v_pk_fma_f32 v[126:127], v[46:47], v[154:155], v[128:129]
	s_waitcnt vmcnt(8)
	v_lshlrev_b32_e32 v158, 16, v159
	v_and_b32_e32 v159, 0xffff0000, v159
	v_pk_fma_f32 v[128:129], v[44:45], v[154:155], v[130:131]
	v_pk_fma_f32 v[130:131], v[42:43], v[154:155], v[132:133]
	v_pk_fma_f32 v[82:83], v[40:41], v[154:155], v[82:83]
	v_pk_fma_f32 v[84:85], v[38:39], v[154:155], v[84:85]
	v_pk_fma_f32 v[86:87], v[34:35], v[154:155], v[86:87]
	v_pk_fma_f32 v[88:89], v[32:33], v[154:155], v[88:89]
	v_pk_fma_f32 v[90:91], v[30:31], v[154:155], v[90:91]
	v_pk_fma_f32 v[92:93], v[28:29], v[154:155], v[92:93]
	v_pk_fma_f32 v[94:95], v[26:27], v[154:155], v[94:95]
	v_pk_fma_f32 v[96:97], v[24:25], v[154:155], v[96:97]
	v_pk_fma_f32 v[98:99], v[22:23], v[154:155], v[98:99]
	v_pk_fma_f32 v[100:101], v[20:21], v[154:155], v[100:101]
	v_pk_fma_f32 v[102:103], v[18:19], v[154:155], v[102:103]
	v_pk_fma_f32 v[104:105], v[16:17], v[154:155], v[104:105]
	v_pk_fma_f32 v[106:107], v[12:13], v[154:155], v[106:107]
	v_pk_fma_f32 v[108:109], v[14:15], v[154:155], v[108:109]
	v_pk_fma_f32 v[110:111], v[10:11], v[154:155], v[110:111]
	v_pk_fma_f32 v[112:113], v[6:7], v[154:155], v[112:113]
	v_pk_fma_f32 v[114:115], v[2:3], v[154:155], v[114:115]
	v_pk_fma_f32 v[116:117], v[8:9], v[154:155], v[116:117]
	v_pk_fma_f32 v[52:53], v[4:5], v[154:155], v[118:119]
	v_pk_fma_f32 v[118:119], v[50:51], v[156:157], v[120:121]
	v_pk_fma_f32 v[120:121], v[48:49], v[156:157], v[122:123]
	v_pk_fma_f32 v[122:123], v[46:47], v[156:157], v[124:125]
	v_pk_fma_f32 v[124:125], v[44:45], v[156:157], v[126:127]
	s_waitcnt vmcnt(7)
	v_lshlrev_b32_e32 v160, 16, v161
	v_and_b32_e32 v161, 0xffff0000, v161
	v_pk_fma_f32 v[126:127], v[42:43], v[156:157], v[128:129]
	v_pk_fma_f32 v[128:129], v[40:41], v[156:157], v[130:131]
	v_pk_fma_f32 v[82:83], v[38:39], v[156:157], v[82:83]
	v_pk_fma_f32 v[84:85], v[34:35], v[156:157], v[84:85]
	v_pk_fma_f32 v[86:87], v[32:33], v[156:157], v[86:87]
	v_pk_fma_f32 v[88:89], v[30:31], v[156:157], v[88:89]
	v_pk_fma_f32 v[90:91], v[28:29], v[156:157], v[90:91]
	v_pk_fma_f32 v[92:93], v[26:27], v[156:157], v[92:93]
	v_pk_fma_f32 v[94:95], v[24:25], v[156:157], v[94:95]
	v_pk_fma_f32 v[96:97], v[22:23], v[156:157], v[96:97]
	v_pk_fma_f32 v[98:99], v[20:21], v[156:157], v[98:99]
	v_pk_fma_f32 v[100:101], v[18:19], v[156:157], v[100:101]
	v_pk_fma_f32 v[102:103], v[16:17], v[156:157], v[102:103]
	v_pk_fma_f32 v[104:105], v[12:13], v[156:157], v[104:105]
	v_pk_fma_f32 v[106:107], v[14:15], v[156:157], v[106:107]
	v_pk_fma_f32 v[108:109], v[10:11], v[156:157], v[108:109]
	v_pk_fma_f32 v[110:111], v[6:7], v[156:157], v[110:111]
	v_pk_fma_f32 v[112:113], v[2:3], v[156:157], v[112:113]
	v_pk_fma_f32 v[114:115], v[8:9], v[156:157], v[114:115]
	v_pk_fma_f32 v[50:51], v[4:5], v[156:157], v[116:117]
	v_pk_fma_f32 v[116:117], v[48:49], v[158:159], v[118:119]
	v_pk_fma_f32 v[118:119], v[46:47], v[158:159], v[120:121]
	v_pk_fma_f32 v[120:121], v[44:45], v[158:159], v[122:123]
	v_pk_fma_f32 v[122:123], v[42:43], v[158:159], v[124:125]
	s_waitcnt vmcnt(6)
; __device__ __forceinline__ float bflo(unsigned w) { return __uint_as_float(w << 16); }
; __device__ __forceinline__ float bfhi(unsigned w) { return __uint_as_float(w & 0xffff0000u); }
; __device__ __forceinline__ void conf_unit(const Frame& F, int l, int unit) {
;     ...
;     for (int sg = 0; sg < 64; sg += 16) {
;         f32x2 xg[16];
; #pragma unroll
;         for (int k = 0; k < 16; ++k) { const int s = sg + k; if (s < 62) {
;             const int tg = t0 - 30 + s; f32x2 x;
;             if (tg >= 0) { const unsigned u = *(const unsigned*)(GLU + (size_t)(r0 - 30 + s) * WL + tid2); x = (f32x2){bflo(u), bfhi(u)}; }
;             else if (samp) x = *(const f32x2*)(A.in[I_SCC] + ((size_t)(l * DB + ri.b) * 30 + (30 + tg)) * WL + tid2);
;             else x = (f32x2){0.f, 0.f};
;             xg[k] = x; } }
; #pragma unroll
;         for (int k = 0; k < 16; ++k) { const int s = sg + k; if (s < 62) {
; #pragma unroll
;             for (int j = 0; j < 31; ++j) { const int t = s - j; if (t >= 0 && t < 32) acc[t] += w[j] * xg[k]; } } }
;         asm volatile("" ::: "memory");
;     }
	v_lshlrev_b32_e32 v80, 16, v162
	v_and_b32_e32 v81, 0xffff0000, v162
	v_pk_fma_f32 v[124:125], v[40:41], v[158:159], v[126:127]
	v_pk_fma_f32 v[126:127], v[38:39], v[158:159], v[128:129]
	v_pk_fma_f32 v[82:83], v[34:35], v[158:159], v[82:83]
	v_pk_fma_f32 v[84:85], v[32:33], v[158:159], v[84:85]
	v_pk_fma_f32 v[86:87], v[30:31], v[158:159], v[86:87]
	v_pk_fma_f32 v[88:89], v[28:29], v[158:159], v[88:89]
	v_pk_fma_f32 v[90:91], v[26:27], v[158:159], v[90:91]
	v_pk_fma_f32 v[92:93], v[24:25], v[158:159], v[92:93]
	v_pk_fma_f32 v[94:95], v[22:23], v[158:159], v[94:95]
	v_pk_fma_f32 v[96:97], v[20:21], v[158:159], v[96:97]
	v_pk_fma_f32 v[98:99], v[18:19], v[158:159], v[98:99]
	v_pk_fma_f32 v[100:101], v[16:17], v[158:159], v[100:101]
	v_pk_fma_f32 v[102:103], v[12:13], v[158:159], v[102:103]
	v_pk_fma_f32 v[104:105], v[14:15], v[158:159], v[104:105]
	v_pk_fma_f32 v[106:107], v[10:11], v[158:159], v[106:107]
	v_pk_fma_f32 v[108:109], v[6:7], v[158:159], v[108:109]
	v_pk_fma_f32 v[110:111], v[2:3], v[158:159], v[110:111]
	v_pk_fma_f32 v[112:113], v[8:9], v[158:159], v[112:113]
	v_pk_fma_f32 v[48:49], v[4:5], v[158:159], v[114:115]
	v_pk_fma_f32 v[114:115], v[46:47], v[160:161], v[116:117]
	v_pk_fma_f32 v[116:117], v[44:45], v[160:161], v[118:119]
	v_pk_fma_f32 v[118:119], v[42:43], v[160:161], v[120:121]
	v_pk_fma_f32 v[120:121], v[40:41], v[160:161], v[122:123]
	s_waitcnt vmcnt(5)
	v_lshlrev_b32_e32 v78, 16, v163
	v_and_b32_e32 v79, 0xffff0000, v163
	v_pk_fma_f32 v[122:123], v[38:39], v[160:161], v[124:125]
	v_pk_fma_f32 v[124:125], v[34:35], v[160:161], v[126:127]
	v_pk_fma_f32 v[82:83], v[32:33], v[160:161], v[82:83]
	v_pk_fma_f32 v[84:85], v[30:31], v[160:161], v[84:85]
	v_pk_fma_f32 v[86:87], v[28:29], v[160:161], v[86:87]
	v_pk_fma_f32 v[88:89], v[26:27], v[160:161], v[88:89]
	v_pk_fma_f32 v[90:91], v[24:25], v[160:161], v[90:91]
	v_pk_fma_f32 v[92:93], v[22:23], v[160:161], v[92:93]
	v_pk_fma_f32 v[94:95], v[20:21], v[160:161], v[94:95]
	v_pk_fma_f32 v[96:97], v[18:19], v[160:161], v[96:97]
	v_pk_fma_f32 v[98:99], v[16:17], v[160:161], v[98:99]
	v_pk_fma_f32 v[100:101], v[12:13], v[160:161], v[100:101]
	v_pk_fma_f32 v[102:103], v[14:15], v[160:161], v[102:103]
	v_pk_fma_f32 v[104:105], v[10:11], v[160:161], v[104:105]
	v_pk_fma_f32 v[106:107], v[6:7], v[160:161], v[106:107]
	v_pk_fma_f32 v[108:109], v[2:3], v[160:161], v[108:109]
	v_pk_fma_f32 v[110:111], v[8:9], v[160:161], v[110:111]
	v_pk_fma_f32 v[46:47], v[4:5], v[160:161], v[112:113]
	v_pk_fma_f32 v[112:113], v[44:45], v[80:81], v[114:115]
	v_pk_fma_f32 v[114:115], v[42:43], v[80:81], v[116:117]
	v_pk_fma_f32 v[116:117], v[40:41], v[80:81], v[118:119]
	v_pk_fma_f32 v[118:119], v[38:39], v[80:81], v[120:121]
	s_or_b32 s4, s20, 18
	s_waitcnt vmcnt(4)
	v_lshlrev_b32_e32 v76, 16, v164
	v_and_b32_e32 v77, 0xffff0000, v164
	v_pk_fma_f32 v[120:121], v[34:35], v[80:81], v[122:123]
	v_pk_fma_f32 v[122:123], v[32:33], v[80:81], v[124:125]
	v_pk_fma_f32 v[82:83], v[30:31], v[80:81], v[82:83]
	v_pk_fma_f32 v[84:85], v[28:29], v[80:81], v[84:85]
	v_pk_fma_f32 v[86:87], v[26:27], v[80:81], v[86:87]
	v_pk_fma_f32 v[88:89], v[24:25], v[80:81], v[88:89]
	v_pk_fma_f32 v[90:91], v[22:23], v[80:81], v[90:91]
	v_pk_fma_f32 v[92:93], v[20:21], v[80:81], v[92:93]
	v_pk_fma_f32 v[94:95], v[18:19], v[80:81], v[94:95]
	v_pk_fma_f32 v[96:97], v[16:17], v[80:81], v[96:97]
	v_pk_fma_f32 v[98:99], v[12:13], v[80:81], v[98:99]
	v_pk_fma_f32 v[100:101], v[14:15], v[80:81], v[100:101]
	v_pk_fma_f32 v[102:103], v[10:11], v[80:81], v[102:103]
	v_pk_fma_f32 v[104:105], v[6:7], v[80:81], v[104:105]
	v_pk_fma_f32 v[106:107], v[2:3], v[80:81], v[106:107]
	v_pk_fma_f32 v[108:109], v[8:9], v[80:81], v[108:109]
	v_pk_fma_f32 v[44:45], v[4:5], v[80:81], v[110:111]
	v_pk_fma_f32 v[80:81], v[42:43], v[78:79], v[112:113]
	v_pk_fma_f32 v[110:111], v[40:41], v[78:79], v[114:115]
	v_pk_fma_f32 v[114:115], v[34:35], v[78:79], v[118:119]
	s_ashr_i32 s5, s4, 31
	s_waitcnt vmcnt(3)
	v_lshlrev_b32_e32 v74, 16, v165
	v_and_b32_e32 v75, 0xffff0000, v165
	v_pk_fma_f32 v[112:113], v[38:39], v[78:79], v[116:117]
	v_pk_fma_f32 v[116:117], v[32:33], v[78:79], v[120:121]
	v_pk_fma_f32 v[118:119], v[30:31], v[78:79], v[122:123]
	v_pk_fma_f32 v[82:83], v[28:29], v[78:79], v[82:83]
	v_pk_fma_f32 v[84:85], v[26:27], v[78:79], v[84:85]
	v_pk_fma_f32 v[86:87], v[24:25], v[78:79], v[86:87]
	v_pk_fma_f32 v[88:89], v[22:23], v[78:79], v[88:89]
	v_pk_fma_f32 v[90:91], v[20:21], v[78:79], v[90:91]
	v_pk_fma_f32 v[92:93], v[18:19], v[78:79], v[92:93]
	v_pk_fma_f32 v[94:95], v[16:17], v[78:79], v[94:95]
	v_pk_fma_f32 v[96:97], v[12:13], v[78:79], v[96:97]
	v_pk_fma_f32 v[98:99], v[14:15], v[78:79], v[98:99]
	v_pk_fma_f32 v[100:101], v[10:11], v[78:79], v[100:101]
	v_pk_fma_f32 v[102:103], v[6:7], v[78:79], v[102:103]
	v_pk_fma_f32 v[104:105], v[2:3], v[78:79], v[104:105]
	v_pk_fma_f32 v[106:107], v[8:9], v[78:79], v[106:107]
	v_pk_fma_f32 v[42:43], v[4:5], v[78:79], v[108:109]
	v_pk_fma_f32 v[78:79], v[40:41], v[76:77], v[80:81]
	v_pk_fma_f32 v[80:81], v[38:39], v[76:77], v[110:111]
	v_pk_fma_f32 v[110:111], v[32:33], v[76:77], v[114:115]
	s_lshl_b64 s[4:5], s[4:5], 11
	v_pk_fma_f32 v[108:109], v[34:35], v[76:77], v[112:113]
	v_pk_fma_f32 v[112:113], v[30:31], v[76:77], v[116:117]
	v_pk_fma_f32 v[114:115], v[28:29], v[76:77], v[118:119]
	v_pk_fma_f32 v[82:83], v[26:27], v[76:77], v[82:83]
	v_pk_fma_f32 v[84:85], v[24:25], v[76:77], v[84:85]
	v_pk_fma_f32 v[86:87], v[22:23], v[76:77], v[86:87]
	v_pk_fma_f32 v[88:89], v[20:21], v[76:77], v[88:89]
	v_pk_fma_f32 v[90:91], v[18:19], v[76:77], v[90:91]
	v_pk_fma_f32 v[92:93], v[16:17], v[76:77], v[92:93]
; __device__ __forceinline__ float bflo(unsigned w) { return __uint_as_float(w << 16); }
; __device__ __forceinline__ float bfhi(unsigned w) { return __uint_as_float(w & 0xffff0000u); }
; __device__ __forceinline__ void conf_unit(const Frame& F, int l, int unit) {
;     ...
;     for (int sg = 0; sg < 64; sg += 16) {
;         f32x2 xg[16];
; #pragma unroll
;         for (int k = 0; k < 16; ++k) { const int s = sg + k; if (s < 62) {
;             const int tg = t0 - 30 + s; f32x2 x;
;             if (tg >= 0) { const unsigned u = *(const unsigned*)(GLU + (size_t)(r0 - 30 + s) * WL + tid2); x = (f32x2){bflo(u), bfhi(u)}; }
;             else if (samp) x = *(const f32x2*)(A.in[I_SCC] + ((size_t)(l * DB + ri.b) * 30 + (30 + tg)) * WL + tid2);
;             else x = (f32x2){0.f, 0.f};
;             xg[k] = x; } }
; #pragma unroll
;         for (int k = 0; k < 16; ++k) { const int s = sg + k; if (s < 62) {
; #pragma unroll
;             for (int j = 0; j < 31; ++j) { const int t = s - j; if (t >= 0 && t < 32) acc[t] += w[j] * xg[k]; } } }
;         asm volatile("" ::: "memory");
;     }
	v_pk_fma_f32 v[94:95], v[12:13], v[76:77], v[94:95]
	v_pk_fma_f32 v[96:97], v[14:15], v[76:77], v[96:97]
	v_pk_fma_f32 v[98:99], v[10:11], v[76:77], v[98:99]
	v_pk_fma_f32 v[100:101], v[6:7], v[76:77], v[100:101]
	v_pk_fma_f32 v[102:103], v[2:3], v[76:77], v[102:103]
	v_pk_fma_f32 v[104:105], v[8:9], v[76:77], v[104:105]
	v_pk_fma_f32 v[40:41], v[4:5], v[76:77], v[106:107]
	v_pk_fma_f32 v[76:77], v[34:35], v[74:75], v[80:81]
	v_pk_fma_f32 v[80:81], v[30:31], v[74:75], v[110:111]
	v_lshl_add_u64 v[110:111], v[36:37], 0, s[4:5]
	s_or_b32 s4, s20, 19
	s_ashr_i32 s5, s4, 31
	s_lshl_b64 s[4:5], s[4:5], 11
	v_pk_fma_f32 v[106:107], v[28:29], v[74:75], v[112:113]
	v_lshl_add_u64 v[112:113], v[36:37], 0, s[4:5]
	s_or_b32 s4, s20, 20
	s_ashr_i32 s5, s4, 31
	s_lshl_b64 s[4:5], s[4:5], 11
	v_pk_fma_f32 v[38:39], v[38:39], v[74:75], v[78:79]
	v_pk_fma_f32 v[78:79], v[32:33], v[74:75], v[108:109]
	v_pk_fma_f32 v[108:109], v[26:27], v[74:75], v[114:115]
	v_lshl_add_u64 v[114:115], v[36:37], 0, s[4:5]
	s_or_b32 s4, s20, 21
	s_ashr_i32 s5, s4, 31
	s_lshl_b64 s[4:5], s[4:5], 11
	v_lshl_add_u64 v[116:117], v[36:37], 0, s[4:5]
	s_or_b32 s4, s20, 22
	s_ashr_i32 s5, s4, 31
	s_lshl_b64 s[4:5], s[4:5], 11
	v_lshl_add_u64 v[118:119], v[36:37], 0, s[4:5]
	s_or_b32 s4, s20, 23
	s_ashr_i32 s5, s4, 31
	s_lshl_b64 s[4:5], s[4:5], 11
	v_lshl_add_u64 v[120:121], v[36:37], 0, s[4:5]
	s_or_b32 s4, s20, 24
	s_ashr_i32 s5, s4, 31
	s_lshl_b64 s[4:5], s[4:5], 11
	v_lshl_add_u64 v[122:123], v[36:37], 0, s[4:5]
	s_or_b32 s4, s20, 25
	s_ashr_i32 s5, s4, 31
	s_lshl_b64 s[4:5], s[4:5], 11
	v_lshl_add_u64 v[124:125], v[36:37], 0, s[4:5]
	s_or_b32 s4, s20, 26
	s_ashr_i32 s5, s4, 31
	s_lshl_b64 s[4:5], s[4:5], 11
	global_load_dword v1, v[110:111], off
	global_load_dword v126, v[112:113], off
	global_load_dword v127, v[114:115], off
	global_load_dword v128, v[116:117], off
	s_nop 0
	global_load_dword v118, v[118:119], off
	s_nop 0
	global_load_dword v119, v[120:121], off
	s_nop 0
	global_load_dword v120, v[122:123], off
	global_load_dword v121, v[124:125], off
	v_lshl_add_u64 v[110:111], v[36:37], 0, s[4:5]
	s_or_b32 s4, s20, 27
	s_ashr_i32 s5, s4, 31
	s_lshl_b64 s[4:5], s[4:5], 11
	global_load_dword v122, v[110:111], off
	v_lshl_add_u64 v[110:111], v[36:37], 0, s[4:5]
	s_or_b32 s4, s20, 28
	s_ashr_i32 s5, s4, 31
	s_lshl_b64 s[4:5], s[4:5], 11
	v_lshl_add_u64 v[112:113], v[36:37], 0, s[4:5]
	s_or_b32 s4, s20, 29
	s_ashr_i32 s5, s4, 31
	s_lshl_b64 s[4:5], s[4:5], 11
	v_lshl_add_u64 v[114:115], v[36:37], 0, s[4:5]
	s_or_b32 s4, s20, 30
	s_ashr_i32 s5, s4, 31
	s_lshl_b64 s[4:5], s[4:5], 11
	v_lshl_add_u64 v[116:117], v[36:37], 0, s[4:5]
	s_or_b32 s4, s20, 31
	s_ashr_i32 s5, s4, 31
	s_lshl_b64 s[4:5], s[4:5], 11
	global_load_dword v123, v[110:111], off
	global_load_dword v124, v[112:113], off
	global_load_dword v125, v[114:115], off
	global_load_dword v129, v[116:117], off
	v_lshl_add_u64 v[36:37], v[36:37], 0, s[4:5]
	global_load_dword v130, v[36:37], off
	s_waitcnt vmcnt(16)
	v_lshlrev_b32_e32 v72, 16, v166
	v_and_b32_e32 v73, 0xffff0000, v166
	v_pk_fma_f32 v[82:83], v[24:25], v[74:75], v[82:83]
	v_pk_fma_f32 v[84:85], v[22:23], v[74:75], v[84:85]
	v_pk_fma_f32 v[86:87], v[20:21], v[74:75], v[86:87]
	v_pk_fma_f32 v[88:89], v[18:19], v[74:75], v[88:89]
	v_pk_fma_f32 v[90:91], v[16:17], v[74:75], v[90:91]
	v_pk_fma_f32 v[92:93], v[12:13], v[74:75], v[92:93]
	v_pk_fma_f32 v[94:95], v[14:15], v[74:75], v[94:95]
	s_waitcnt vmcnt(15)
	v_lshlrev_b32_e32 v70, 16, v167
	v_and_b32_e32 v71, 0xffff0000, v167
	v_pk_fma_f32 v[36:37], v[10:11], v[74:75], v[96:97]
	v_pk_fma_f32 v[96:97], v[6:7], v[74:75], v[98:99]
	v_pk_fma_f32 v[98:99], v[2:3], v[74:75], v[100:101]
	v_pk_fma_f32 v[100:101], v[8:9], v[74:75], v[102:103]
	v_pk_fma_f32 v[34:35], v[34:35], v[72:73], v[38:39]
	v_pk_fma_f32 v[38:39], v[32:33], v[72:73], v[76:77]
	v_pk_fma_f32 v[76:77], v[30:31], v[72:73], v[78:79]
	v_pk_fma_f32 v[78:79], v[28:29], v[72:73], v[80:81]
	v_pk_fma_f32 v[80:81], v[26:27], v[72:73], v[106:107]
	v_pk_fma_f32 v[102:103], v[24:25], v[72:73], v[108:109]
	v_pk_fma_f32 v[82:83], v[22:23], v[72:73], v[82:83]
	v_pk_fma_f32 v[84:85], v[20:21], v[72:73], v[84:85]
	v_pk_fma_f32 v[86:87], v[18:19], v[72:73], v[86:87]
	v_pk_fma_f32 v[88:89], v[16:17], v[72:73], v[88:89]
	v_pk_fma_f32 v[90:91], v[12:13], v[72:73], v[90:91]
	v_pk_fma_f32 v[92:93], v[14:15], v[72:73], v[92:93]
	v_pk_fma_f32 v[94:95], v[10:11], v[72:73], v[94:95]
	s_waitcnt vmcnt(14)
	v_lshlrev_b32_e32 v66, 16, v168
	v_and_b32_e32 v67, 0xffff0000, v168
	v_pk_fma_f32 v[36:37], v[6:7], v[72:73], v[36:37]
	v_pk_fma_f32 v[96:97], v[2:3], v[72:73], v[96:97]
	v_pk_fma_f32 v[98:99], v[8:9], v[72:73], v[98:99]
	v_pk_fma_f32 v[32:33], v[32:33], v[70:71], v[34:35]
	v_pk_fma_f32 v[34:35], v[30:31], v[70:71], v[38:39]
	v_pk_fma_f32 v[38:39], v[28:29], v[70:71], v[76:77]
	v_pk_fma_f32 v[76:77], v[26:27], v[70:71], v[78:79]
	v_pk_fma_f32 v[78:79], v[24:25], v[70:71], v[80:81]
	v_pk_fma_f32 v[80:81], v[22:23], v[70:71], v[102:103]
	v_pk_fma_f32 v[82:83], v[20:21], v[70:71], v[82:83]
	v_pk_fma_f32 v[84:85], v[18:19], v[70:71], v[84:85]
	v_pk_fma_f32 v[86:87], v[16:17], v[70:71], v[86:87]
	v_pk_fma_f32 v[88:89], v[12:13], v[70:71], v[88:89]
	v_pk_fma_f32 v[90:91], v[14:15], v[70:71], v[90:91]
	v_pk_fma_f32 v[92:93], v[10:11], v[70:71], v[92:93]
	v_pk_fma_f32 v[94:95], v[6:7], v[70:71], v[94:95]
	v_lshl_add_u32 v0, v0, 2, 0
	v_pk_fma_f32 v[36:37], v[2:3], v[70:71], v[36:37]
	v_pk_fma_f32 v[96:97], v[8:9], v[70:71], v[96:97]
	v_pk_fma_f32 v[70:71], v[4:5], v[70:71], v[98:99]
	v_pk_fma_f32 v[30:31], v[30:31], v[66:67], v[32:33]
	v_pk_fma_f32 v[32:33], v[28:29], v[66:67], v[34:35]
	v_pk_fma_f32 v[34:35], v[26:27], v[66:67], v[38:39]
	v_pk_fma_f32 v[38:39], v[24:25], v[66:67], v[76:77]
	v_pk_fma_f32 v[76:77], v[22:23], v[66:67], v[78:79]
	v_pk_fma_f32 v[78:79], v[20:21], v[66:67], v[80:81]
	v_pk_fma_f32 v[80:81], v[18:19], v[66:67], v[82:83]
	v_pk_fma_f32 v[82:83], v[16:17], v[66:67], v[84:85]
	v_pk_fma_f32 v[84:85], v[12:13], v[66:67], v[86:87]
	v_pk_fma_f32 v[86:87], v[14:15], v[66:67], v[88:89]
	v_pk_fma_f32 v[88:89], v[10:11], v[66:67], v[90:91]
	v_pk_fma_f32 v[90:91], v[6:7], v[66:67], v[92:93]
	v_pk_fma_f32 v[92:93], v[2:3], v[66:67], v[94:95]
	s_waitcnt vmcnt(13)
; #define LAS __attribute__((address_space(3)))
; __device__ __forceinline__ float bflo(unsigned w) { return __uint_as_float(w << 16); }
; __device__ __forceinline__ float bfhi(unsigned w) { return __uint_as_float(w & 0xffff0000u); }
; __device__ __forceinline__ void conf_unit(const Frame& F, int l, int unit) {
;     ...
;     for (int sg = 0; sg < 64; sg += 16) {
;         f32x2 xg[16];
; #pragma unroll
;         for (int k = 0; k < 16; ++k) { const int s = sg + k; if (s < 62) {
;             const int tg = t0 - 30 + s; f32x2 x;
;             if (tg >= 0) { const unsigned u = *(const unsigned*)(GLU + (size_t)(r0 - 30 + s) * WL + tid2); x = (f32x2){bflo(u), bfhi(u)}; }
;             else if (samp) x = *(const f32x2*)(A.in[I_SCC] + ((size_t)(l * DB + ri.b) * 30 + (30 + tg)) * WL + tid2);
;             else x = (f32x2){0.f, 0.f};
;             xg[k] = x; } }
; #pragma unroll
;         for (int k = 0; k < 16; ++k) { const int s = sg + k; if (s < 62) {
; #pragma unroll
;             for (int j = 0; j < 31; ++j) { const int t = s - j; if (t >= 0 && t < 32) acc[t] += w[j] * xg[k]; } } }
;         asm volatile("" ::: "memory");
;     }
;     LAS float* CB = (LAS float*)F.lds;
; #pragma unroll
;     for (int t = 0; t < 32; ++t) *(LAS f32x2*)(CB + t * 1024 + tid2) = acc[t];
	v_lshlrev_b32_e32 v94, 16, v1
	v_and_b32_e32 v95, 0xffff0000, v1
	v_add_u32_e32 v1, 0x10000, v0
	v_pk_fma_f32 v[74:75], v[4:5], v[74:75], v[104:105]
	v_pk_fma_f32 v[72:73], v[4:5], v[72:73], v[100:101]
	v_pk_fma_f32 v[36:37], v[8:9], v[66:67], v[36:37]
	v_pk_fma_f32 v[66:67], v[4:5], v[66:67], v[96:97]
	s_waitcnt vmcnt(12)
	v_lshlrev_b32_e32 v96, 16, v126
	v_and_b32_e32 v97, 0xffff0000, v126
	v_pk_fma_f32 v[28:29], v[28:29], v[94:95], v[30:31]
	ds_write2st64_b64 v0, v[68:69], v[64:65] offset1:8
	ds_write2st64_b64 v0, v[62:63], v[60:61] offset0:16 offset1:24
	ds_write2st64_b64 v0, v[58:59], v[56:57] offset0:32 offset1:40
	ds_write2st64_b64 v0, v[54:55], v[52:53] offset0:48 offset1:56
	ds_write2st64_b64 v0, v[50:51], v[48:49] offset0:64 offset1:72
	ds_write2st64_b64 v0, v[46:47], v[44:45] offset0:80 offset1:88
	ds_write2st64_b64 v0, v[42:43], v[40:41] offset0:96 offset1:104
	ds_write2st64_b64 v0, v[74:75], v[72:73] offset0:112 offset1:120
	ds_write_b64 v1, v[70:71]
	v_add_u32_e32 v1, 0x11000, v0
	s_waitcnt vmcnt(11)
	v_lshlrev_b32_e32 v98, 16, v127
	v_and_b32_e32 v99, 0xffff0000, v127
	v_pk_fma_f32 v[30:31], v[26:27], v[94:95], v[32:33]
	v_pk_fma_f32 v[32:33], v[24:25], v[94:95], v[34:35]
	v_pk_fma_f32 v[34:35], v[22:23], v[94:95], v[38:39]
	v_pk_fma_f32 v[38:39], v[20:21], v[94:95], v[76:77]
	v_pk_fma_f32 v[76:77], v[18:19], v[94:95], v[78:79]
	v_pk_fma_f32 v[78:79], v[16:17], v[94:95], v[80:81]
	v_pk_fma_f32 v[80:81], v[12:13], v[94:95], v[82:83]
	v_pk_fma_f32 v[82:83], v[14:15], v[94:95], v[84:85]
	v_pk_fma_f32 v[84:85], v[10:11], v[94:95], v[86:87]
	v_pk_fma_f32 v[86:87], v[6:7], v[94:95], v[88:89]
	v_pk_fma_f32 v[88:89], v[2:3], v[94:95], v[90:91]
	v_pk_fma_f32 v[90:91], v[8:9], v[94:95], v[92:93]
	v_pk_fma_f32 v[36:37], v[4:5], v[94:95], v[36:37]
	v_pk_fma_f32 v[26:27], v[26:27], v[96:97], v[28:29]
	ds_write_b64 v1, v[66:67]
	v_add_u32_e32 v1, 0x12000, v0
	s_waitcnt vmcnt(10)
	v_lshlrev_b32_e32 v100, 16, v128
	v_and_b32_e32 v101, 0xffff0000, v128
	v_pk_fma_f32 v[28:29], v[24:25], v[96:97], v[30:31]
	v_pk_fma_f32 v[30:31], v[22:23], v[96:97], v[32:33]
	v_pk_fma_f32 v[32:33], v[20:21], v[96:97], v[34:35]
	v_pk_fma_f32 v[34:35], v[18:19], v[96:97], v[38:39]
	v_pk_fma_f32 v[38:39], v[16:17], v[96:97], v[76:77]
	v_pk_fma_f32 v[76:77], v[12:13], v[96:97], v[78:79]
	v_pk_fma_f32 v[78:79], v[14:15], v[96:97], v[80:81]
	v_pk_fma_f32 v[80:81], v[10:11], v[96:97], v[82:83]
	v_pk_fma_f32 v[82:83], v[6:7], v[96:97], v[84:85]
	v_pk_fma_f32 v[84:85], v[2:3], v[96:97], v[86:87]
	v_pk_fma_f32 v[86:87], v[8:9], v[96:97], v[88:89]
	v_pk_fma_f32 v[88:89], v[4:5], v[96:97], v[90:91]
	v_pk_fma_f32 v[24:25], v[24:25], v[98:99], v[26:27]
	ds_write_b64 v1, v[36:37]
	v_add_u32_e32 v1, 0x13000, v0
	s_waitcnt vmcnt(9)
	v_lshlrev_b32_e32 v102, 16, v118
	v_and_b32_e32 v103, 0xffff0000, v118
	v_pk_fma_f32 v[26:27], v[22:23], v[98:99], v[28:29]
	v_pk_fma_f32 v[28:29], v[20:21], v[98:99], v[30:31]
	v_pk_fma_f32 v[30:31], v[18:19], v[98:99], v[32:33]
	v_pk_fma_f32 v[32:33], v[16:17], v[98:99], v[34:35]
	v_pk_fma_f32 v[34:35], v[12:13], v[98:99], v[38:39]
	v_pk_fma_f32 v[38:39], v[14:15], v[98:99], v[76:77]
	v_pk_fma_f32 v[76:77], v[10:11], v[98:99], v[78:79]
	v_pk_fma_f32 v[78:79], v[6:7], v[98:99], v[80:81]
	v_pk_fma_f32 v[80:81], v[2:3], v[98:99], v[82:83]
	v_pk_fma_f32 v[82:83], v[8:9], v[98:99], v[84:85]
	v_pk_fma_f32 v[84:85], v[4:5], v[98:99], v[86:87]
	v_pk_fma_f32 v[22:23], v[22:23], v[100:101], v[24:25]
	ds_write_b64 v1, v[88:89]
	v_add_u32_e32 v1, 0x14000, v0
	s_waitcnt vmcnt(8)
	v_lshlrev_b32_e32 v104, 16, v119
	v_and_b32_e32 v105, 0xffff0000, v119
	v_pk_fma_f32 v[24:25], v[20:21], v[100:101], v[26:27]
	v_pk_fma_f32 v[26:27], v[18:19], v[100:101], v[28:29]
	v_pk_fma_f32 v[28:29], v[16:17], v[100:101], v[30:31]
	v_pk_fma_f32 v[30:31], v[12:13], v[100:101], v[32:33]
	v_pk_fma_f32 v[32:33], v[14:15], v[100:101], v[34:35]
	v_pk_fma_f32 v[34:35], v[10:11], v[100:101], v[38:39]
	v_pk_fma_f32 v[38:39], v[6:7], v[100:101], v[76:77]
	v_pk_fma_f32 v[76:77], v[2:3], v[100:101], v[78:79]
	v_pk_fma_f32 v[78:79], v[8:9], v[100:101], v[80:81]
	v_pk_fma_f32 v[80:81], v[4:5], v[100:101], v[82:83]
	v_pk_fma_f32 v[20:21], v[20:21], v[102:103], v[22:23]
	ds_write_b64 v1, v[84:85]
	v_add_u32_e32 v1, 0x15000, v0
	s_waitcnt vmcnt(7)
	v_lshlrev_b32_e32 v106, 16, v120
	v_and_b32_e32 v107, 0xffff0000, v120
	v_pk_fma_f32 v[22:23], v[18:19], v[102:103], v[24:25]
	v_pk_fma_f32 v[24:25], v[16:17], v[102:103], v[26:27]
	v_pk_fma_f32 v[26:27], v[12:13], v[102:103], v[28:29]
	v_pk_fma_f32 v[28:29], v[14:15], v[102:103], v[30:31]
	v_pk_fma_f32 v[30:31], v[10:11], v[102:103], v[32:33]
	v_pk_fma_f32 v[32:33], v[6:7], v[102:103], v[34:35]
	v_pk_fma_f32 v[34:35], v[2:3], v[102:103], v[38:39]
	v_pk_fma_f32 v[38:39], v[8:9], v[102:103], v[76:77]
	v_pk_fma_f32 v[76:77], v[4:5], v[102:103], v[78:79]
	v_pk_fma_f32 v[18:19], v[18:19], v[104:105], v[20:21]
	ds_write_b64 v1, v[80:81]
	v_add_u32_e32 v1, 0x16000, v0
	s_waitcnt vmcnt(6)
	v_lshlrev_b32_e32 v108, 16, v121
	v_and_b32_e32 v109, 0xffff0000, v121
	v_pk_fma_f32 v[20:21], v[16:17], v[104:105], v[22:23]
	v_pk_fma_f32 v[22:23], v[12:13], v[104:105], v[24:25]
	v_pk_fma_f32 v[24:25], v[14:15], v[104:105], v[26:27]
	v_pk_fma_f32 v[26:27], v[10:11], v[104:105], v[28:29]
	v_pk_fma_f32 v[28:29], v[6:7], v[104:105], v[30:31]
	v_pk_fma_f32 v[30:31], v[2:3], v[104:105], v[32:33]
	v_pk_fma_f32 v[32:33], v[8:9], v[104:105], v[34:35]
	v_pk_fma_f32 v[34:35], v[4:5], v[104:105], v[38:39]
	v_pk_fma_f32 v[16:17], v[16:17], v[106:107], v[18:19]
	ds_write_b64 v1, v[76:77]
	v_add_u32_e32 v1, 0x17000, v0
	s_waitcnt vmcnt(5)
; #define LAS __attribute__((address_space(3)))
; __device__ __forceinline__ void conf_unit(const Frame& F, int l, int unit) {
;     ...
;         for (int k = 0; k < 16; ++k) { const int s = sg + k; if (s < 62) {
; #pragma unroll
;             for (int j = 0; j < 31; ++j) { const int t = s - j; if (t >= 0 && t < 32) acc[t] += w[j] * xg[k]; } } }
;         asm volatile("" ::: "memory");
;     }
;     LAS float* CB = (LAS float*)F.lds;
; #pragma unroll
;     for (int t = 0; t < 32; ++t) *(LAS f32x2*)(CB + t * 1024 + tid2) = acc[t];
;     __syncthreads();
;     const float* lg = A.in[I_CLG] + l * WL; const float* lb = A.in[I_CLB] + l * WL; unsigned char* YB = ws + WS_Y + (size_t)M * WL;
;     f32x4 lgv[4], lbv[4];
; #pragma unroll
;     for (int j = 0; j < 4; ++j) { lgv[j] = *(const f32x4*)(lg + 256 * j + 4 * lane); lbv[j] = *(const f32x4*)(lb + 256 * j + 4 * lane); }
; #pragma unroll
;     for (int k = 0; k < 4; ++k) { const int t = 4 * wave + k; f32x4 v[4]; float s = 0.f;
; #pragma unroll
;         for (int j = 0; j < 4; ++j) { v[j] = *(const LAS f32x4*)(CB + t * 1024 + 256 * j + 4 * lane); s += (v[j][0] + v[j][1]) + (v[j][2] + v[j][3]); }
;         const float mean = wave_sum(s) * (1.0f / 1024.0f); float q = 0.f;
	v_lshlrev_b32_e32 v110, 16, v122
	v_and_b32_e32 v111, 0xffff0000, v122
	v_pk_fma_f32 v[18:19], v[12:13], v[106:107], v[20:21]
	v_pk_fma_f32 v[20:21], v[14:15], v[106:107], v[22:23]
	v_pk_fma_f32 v[22:23], v[10:11], v[106:107], v[24:25]
	v_pk_fma_f32 v[24:25], v[6:7], v[106:107], v[26:27]
	v_pk_fma_f32 v[26:27], v[2:3], v[106:107], v[28:29]
	v_pk_fma_f32 v[28:29], v[8:9], v[106:107], v[30:31]
	v_pk_fma_f32 v[30:31], v[4:5], v[106:107], v[32:33]
	v_pk_fma_f32 v[12:13], v[12:13], v[108:109], v[16:17]
	ds_write_b64 v1, v[34:35]
	v_add_u32_e32 v1, 0x18000, v0
	s_waitcnt vmcnt(4)
	v_lshlrev_b32_e32 v112, 16, v123
	v_and_b32_e32 v113, 0xffff0000, v123
	v_pk_fma_f32 v[16:17], v[14:15], v[108:109], v[18:19]
	v_pk_fma_f32 v[18:19], v[10:11], v[108:109], v[20:21]
	v_pk_fma_f32 v[20:21], v[6:7], v[108:109], v[22:23]
	v_pk_fma_f32 v[22:23], v[2:3], v[108:109], v[24:25]
	v_pk_fma_f32 v[24:25], v[8:9], v[108:109], v[26:27]
	v_pk_fma_f32 v[26:27], v[4:5], v[108:109], v[28:29]
	v_pk_fma_f32 v[12:13], v[14:15], v[110:111], v[12:13]
	ds_write_b64 v1, v[30:31]
	v_add_u32_e32 v1, 0x19000, v0
	s_waitcnt vmcnt(3)
	v_lshlrev_b32_e32 v114, 16, v124
	v_and_b32_e32 v115, 0xffff0000, v124
	v_pk_fma_f32 v[14:15], v[10:11], v[110:111], v[16:17]
	v_pk_fma_f32 v[16:17], v[6:7], v[110:111], v[18:19]
	v_pk_fma_f32 v[18:19], v[2:3], v[110:111], v[20:21]
	v_pk_fma_f32 v[20:21], v[8:9], v[110:111], v[22:23]
	v_pk_fma_f32 v[22:23], v[4:5], v[110:111], v[24:25]
	v_pk_fma_f32 v[10:11], v[10:11], v[112:113], v[12:13]
	ds_write_b64 v1, v[26:27]
	v_add_u32_e32 v1, 0x1a000, v0
	s_waitcnt vmcnt(2)
	v_lshlrev_b32_e32 v116, 16, v125
	v_and_b32_e32 v117, 0xffff0000, v125
	v_pk_fma_f32 v[12:13], v[6:7], v[112:113], v[14:15]
	v_pk_fma_f32 v[14:15], v[2:3], v[112:113], v[16:17]
	v_pk_fma_f32 v[16:17], v[8:9], v[112:113], v[18:19]
	v_pk_fma_f32 v[18:19], v[4:5], v[112:113], v[20:21]
	v_pk_fma_f32 v[6:7], v[6:7], v[114:115], v[10:11]
	ds_write_b64 v1, v[22:23]
	v_add_u32_e32 v1, 0x1b000, v0
	s_waitcnt vmcnt(1)
	v_lshlrev_b32_e32 v118, 16, v129
	v_and_b32_e32 v119, 0xffff0000, v129
	v_pk_fma_f32 v[10:11], v[2:3], v[114:115], v[12:13]
	v_pk_fma_f32 v[12:13], v[8:9], v[114:115], v[14:15]
	v_pk_fma_f32 v[14:15], v[4:5], v[114:115], v[16:17]
	v_pk_fma_f32 v[2:3], v[2:3], v[116:117], v[6:7]
	ds_write_b64 v1, v[18:19]
	v_add_u32_e32 v1, 0x1c000, v0
	s_waitcnt vmcnt(0)
	v_lshlrev_b32_e32 v120, 16, v130
	v_and_b32_e32 v121, 0xffff0000, v130
	v_pk_fma_f32 v[6:7], v[8:9], v[116:117], v[10:11]
	v_pk_fma_f32 v[10:11], v[4:5], v[116:117], v[12:13]
	v_pk_fma_f32 v[2:3], v[8:9], v[118:119], v[2:3]
	ds_write_b64 v1, v[14:15]
	v_add_u32_e32 v1, 0x1d000, v0
	s_add_u32 s4, s8, s0
	v_lshlrev_b32_e32 v40, 2, v134
	v_pk_fma_f32 v[6:7], v[4:5], v[118:119], v[6:7]
	v_pk_fma_f32 v[2:3], v[4:5], v[120:121], v[2:3]
	ds_write_b64 v1, v[10:11]
	v_add_u32_e32 v1, 0x1e000, v0
	v_add_u32_e32 v0, 0x1f000, v0
	s_addc_u32 s5, s9, s1
	v_ashrrev_i32_e32 v41, 31, v40
	ds_write_b64 v1, v[6:7]
	ds_write_b64 v0, v[2:3]
	s_add_u32 s0, s10, s0
	v_lshlrev_b64 v[0:1], 2, v[40:41]
	v_lshl_add_u32 v42, v134, 4, 0
	s_addc_u32 s1, s11, s1
	v_lshl_add_u64 v[2:3], s[4:5], 0, v[0:1]
	v_add_u32_e32 v43, s17, v42
	s_waitcnt lgkmcnt(0)
	s_barrier
	v_lshl_add_u64 v[4:5], s[0:1], 0, v[0:1]
	global_load_dwordx4 v[24:27], v[2:3], off
	global_load_dwordx4 v[16:19], v[2:3], off offset:1024
	global_load_dwordx4 v[28:31], v[4:5], off
	global_load_dwordx4 v[20:23], v[4:5], off offset:1024
	ds_read_b128 v[44:47], v43
	global_load_dwordx4 v[8:11], v[2:3], off offset:2048
	s_nop 0
	global_load_dwordx4 v[0:3], v[2:3], off offset:3072
	s_nop 0
	global_load_dwordx4 v[12:15], v[4:5], off offset:2048
	s_nop 0
	global_load_dwordx4 v[4:7], v[4:5], off offset:3072
	ds_read_b128 v[48:51], v43 offset:1024
	ds_read_b128 v[36:39], v43 offset:2048
	s_add_u32 s4, s22, 0x3b5d0000
	s_waitcnt lgkmcnt(2)
	v_mov_b32_e32 v32, v45
	v_mov_b32_e32 v33, v46
	v_mov_b32_e32 v34, v44
	v_mov_b32_e32 v35, v47
	v_pk_add_f32 v[32:33], v[32:33], v[34:35]
	s_waitcnt lgkmcnt(1)
	v_mov_b32_e32 v54, v49
	v_add_f32_e32 v32, v32, v33
	v_add_f32_e32 v52, 0, v32
	ds_read_b128 v[32:35], v43 offset:3072
	v_mov_b32_e32 v55, v50
	v_mov_b32_e32 v56, v48
	v_mov_b32_e32 v57, v51
	v_pk_add_f32 v[54:55], v[54:55], v[56:57]
	s_waitcnt lgkmcnt(1)
	v_add_f32_e32 v56, v36, v37
	v_pk_add_f32 v[54:55], v[54:55], v[54:55] op_sel:[0,1] op_sel_hi:[1,0]
	v_add_f32_e32 v58, v38, v39
	s_waitcnt lgkmcnt(0)
	v_mov_b32_e32 v53, v32
	v_mov_b32_e32 v55, v33
	v_mov_b32_e32 v57, v34
	v_mov_b32_e32 v59, v35
	v_pk_add_f32 v[52:53], v[52:53], v[54:55]
	v_pk_add_f32 v[54:55], v[56:57], v[58:59]
	s_addc_u32 s5, s23, 0
	v_pk_add_f32 v[52:53], v[52:53], v[54:55]
	s_nop 0
	v_add_f32_e32 v43, v52, v53
	v_mbcnt_lo_u32_b32 v52, -1, 0
	v_mbcnt_hi_u32_b32 v52, -1, v52
	s_nop 0
	v_lshlrev_b32_e32 v52, 2, v52
	v_xor_b32_e32 v53, 4, v52
	ds_bpermute_b32 v53, v53, v43
	s_waitcnt lgkmcnt(0)
	v_add_f32_e32 v43, v43, v53
	v_xor_b32_e32 v53, 8, v52
	ds_bpermute_b32 v53, v53, v43
	s_waitcnt lgkmcnt(0)
	v_add_f32_e32 v43, v43, v53
	v_xor_b32_e32 v53, 16, v52
	ds_bpermute_b32 v53, v53, v43
	s_waitcnt lgkmcnt(0)
	v_add_f32_e32 v43, v43, v53
	v_xor_b32_e32 v53, 32, v52
	ds_bpermute_b32 v53, v53, v43
	s_waitcnt lgkmcnt(0)
	v_add_f32_e32 v43, v43, v53
	v_xor_b32_e32 v53, 64, v52
	ds_bpermute_b32 v53, v53, v43
	v_xor_b32_e32 v52, 0x80, v52
	s_waitcnt lgkmcnt(0)
	v_add_f32_e32 v43, v43, v53
	ds_bpermute_b32 v52, v52, v43
	s_waitcnt lgkmcnt(0)
; #define LAS __attribute__((address_space(3)))
; __device__ __forceinline__ unsigned pk4_fp8(f32x4 v) { int w = 0; w = __builtin_amdgcn_cvt_pk_fp8_f32(v[0], v[1], w, false); w = __builtin_amdgcn_cvt_pk_fp8_f32(v[2], v[3], w, true); return (unsigned)w; }
; __device__ __forceinline__ float sigmoidf_(float x) { return frcp(1.0f + __expf(-x)); }
; __device__ __forceinline__ void conf_unit(const Frame& F, int l, int unit) {
;     ...
;     for (int k = 0; k < 4; ++k) { const int t = 4 * wave + k; f32x4 v[4]; float s = 0.f;
; #pragma unroll
;         for (int j = 0; j < 4; ++j) { v[j] = *(const LAS f32x4*)(CB + t * 1024 + 256 * j + 4 * lane); s += (v[j][0] + v[j][1]) + (v[j][2] + v[j][3]); }
;         const float mean = wave_sum(s) * (1.0f / 1024.0f); float q = 0.f;
; #pragma unroll
;         for (int j = 0; j < 4; ++j) { v[j] = v[j] - mean; q += (v[j][0] * v[j][0] + v[j][1] * v[j][1]) + (v[j][2] * v[j][2] + v[j][3] * v[j][3]); }
;         const float rstd = 1.0f / sqrtf(wave_sum(q) * (1.0f / 1024.0f) + LN_EPS);
; #pragma unroll
;         for (int j = 0; j < 4; ++j) { const int cix = 256 * j + 4 * lane; const f32x4 gg = lgv[j], bb = lbv[j]; f32x4 y = v[j] * rstd * gg + bb;
; #pragma unroll
;             for (int e = 0; e < 4; ++e) y[e] = y[e] * sigmoidf_(y[e]);
;             *(unsigned*)(YB + (size_t)(r0 + t) * WL + cix) = pk4_fp8(y); } }
	v_add_f32_e32 v43, v43, v52
	v_fmamk_f32 v45, v43, 0xba800000, v45
	v_fmamk_f32 v44, v43, 0xba800000, v44
	v_fmamk_f32 v47, v43, 0xba800000, v47
	v_fmac_f32_e32 v46, 0xba800000, v43
	v_pk_mul_f32 v[52:53], v[46:47], v[46:47]
	v_pk_mul_f32 v[54:55], v[44:45], v[44:45]
	v_fmamk_f32 v49, v43, 0xba800000, v49
	v_pk_mov_b32 v[56:57], v[54:55], v[52:53] op_sel:[1,0]
	v_mov_b32_e32 v55, v53
	v_pk_add_f32 v[52:53], v[56:57], v[54:55]
	v_fmamk_f32 v48, v43, 0xba800000, v48
	v_fmamk_f32 v51, v43, 0xba800000, v51
	v_fmac_f32_e32 v50, 0xba800000, v43
	v_pk_add_f32 v[52:53], v[52:53], v[52:53] op_sel_hi:[0,1]
	v_pk_mul_f32 v[54:55], v[50:51], v[50:51]
	v_pk_mul_f32 v[56:57], v[48:49], v[48:49]
	v_fmamk_f32 v36, v43, 0xba800000, v36
	v_pk_mov_b32 v[58:59], v[56:57], v[54:55] op_sel:[1,0]
	v_mov_b32_e32 v57, v55
	v_fmamk_f32 v37, v43, 0xba800000, v37
	v_fmac_f32_e32 v38, 0xba800000, v43
	v_mul_f32_e32 v52, v36, v36
	v_pk_add_f32 v[54:55], v[58:59], v[56:57]
	v_fmamk_f32 v39, v43, 0xba800000, v39
	v_pk_fma_f32 v[56:57], v[36:37], v[36:37], v[52:53] op_sel_hi:[1,1,0]
	v_mul_f32_e32 v52, v38, v38
	v_pk_add_f32 v[54:55], v[54:55], v[54:55] op_sel_hi:[0,1]
	v_pk_fma_f32 v[58:59], v[38:39], v[38:39], v[52:53] op_sel_hi:[1,1,0]
	v_fmamk_f32 v35, v43, 0xba800000, v35
	v_fmamk_f32 v34, v43, 0xba800000, v34
	v_fmamk_f32 v33, v43, 0xba800000, v33
	v_fmac_f32_e32 v32, 0xba800000, v43
	v_mul_f32_e32 v56, v32, v32
	v_mul_f32_e32 v58, v33, v33
	v_mul_f32_e32 v52, v34, v34
	v_mul_f32_e32 v54, v35, v35
	v_pk_add_f32 v[56:57], v[56:57], v[58:59]
	v_pk_add_f32 v[52:53], v[52:53], v[54:55]
	s_nop 0
	v_pk_add_f32 v[52:53], v[56:57], v[52:53]
	s_nop 0
	v_add_f32_e32 v43, v52, v53
	v_mbcnt_lo_u32_b32 v52, -1, 0
	v_mbcnt_hi_u32_b32 v52, -1, v52
	s_nop 0
	v_lshlrev_b32_e32 v52, 2, v52
	v_xor_b32_e32 v53, 4, v52
	ds_bpermute_b32 v53, v53, v43
	s_waitcnt lgkmcnt(0)
	v_add_f32_e32 v43, v43, v53
	v_xor_b32_e32 v53, 8, v52
	ds_bpermute_b32 v53, v53, v43
	s_waitcnt lgkmcnt(0)
	v_add_f32_e32 v43, v43, v53
	v_xor_b32_e32 v53, 16, v52
	ds_bpermute_b32 v53, v53, v43
	s_waitcnt lgkmcnt(0)
	v_add_f32_e32 v43, v43, v53
	v_xor_b32_e32 v53, 32, v52
	ds_bpermute_b32 v53, v53, v43
	s_waitcnt lgkmcnt(0)
	v_add_f32_e32 v43, v43, v53
	v_xor_b32_e32 v53, 64, v52
	ds_bpermute_b32 v53, v53, v43
	v_xor_b32_e32 v52, 0x80, v52
	s_waitcnt lgkmcnt(0)
	v_add_f32_e32 v43, v43, v53
	ds_bpermute_b32 v52, v52, v43
	s_waitcnt lgkmcnt(0)
	v_add_f32_e32 v43, v43, v52
	v_fmamk_f32 v43, v43, 0x3a800000, v232
	v_mul_f32_e32 v52, 0x4f800000, v43
	v_cmp_gt_f32_e32 vcc, s89, v43
	s_nop 1
	v_cndmask_b32_e32 v43, v43, v52, vcc
	v_sqrt_f32_e32 v52, v43
	s_nop 0
	v_add_u32_e32 v53, -1, v52
	v_fma_f32 v54, -v53, v52, v43
	v_cmp_ge_f32_e64 s[0:1], 0, v54
	v_add_u32_e32 v54, 1, v52
	s_nop 0
	v_cndmask_b32_e64 v53, v52, v53, s[0:1]
	v_fma_f32 v52, -v54, v52, v43
	v_cmp_lt_f32_e64 s[0:1], 0, v52
	s_nop 1
	v_cndmask_b32_e64 v52, v53, v54, s[0:1]
	v_mul_f32_e32 v53, 0x37800000, v52
	v_cndmask_b32_e32 v52, v52, v53, vcc
	v_cmp_class_f32_e32 vcc, v43, v223
	s_nop 1
	v_cndmask_b32_e32 v43, v52, v43, vcc
	v_div_scale_f32 v52, s[0:1], v43, v43, 1.0
	v_rcp_f32_e32 v53, v52
	s_add_i32 s0, s20, s16
	s_ashr_i32 s1, s0, 31
	s_lshl_b64 s[0:1], s[0:1], 10
	v_fma_f32 v54, -v52, v53, 1.0
	v_fmac_f32_e32 v53, v54, v53
	v_div_scale_f32 v54, vcc, 1.0, v43, 1.0
	v_mul_f32_e32 v55, v54, v53
	v_fma_f32 v56, -v52, v55, v54
	v_fmac_f32_e32 v55, v56, v53
	v_fma_f32 v52, -v52, v55, v54
	v_div_fmas_f32 v52, v52, v53, v55
	v_div_fixup_f32 v52, v52, v43, 1.0
	v_pk_mul_f32 v[44:45], v[44:45], v[52:53] op_sel_hi:[1,0]
	v_mov_b32_e32 v56, v201
	s_waitcnt vmcnt(5)
	v_pk_fma_f32 v[44:45], v[24:25], v[44:45], v[28:29]
	s_add_u32 s0, s4, s0
	v_mul_f32_e32 v43, 0xbfb8aa3b, v44
	v_exp_f32_e32 v43, v43
	v_mul_f32_e32 v53, 0xbfb8aa3b, v45
	v_exp_f32_e32 v53, v53
	s_addc_u32 s1, s5, s1
	v_add_f32_e32 v43, 1.0, v43
	v_rcp_f32_e32 v43, v43
	v_pk_mul_f32 v[46:47], v[46:47], v[52:53] op_sel_hi:[1,0]
	v_mul_f32_e32 v43, v44, v43
	v_pk_fma_f32 v[46:47], v[26:27], v[46:47], v[30:31]
	v_add_f32_e32 v44, 1.0, v53
	v_mul_f32_e32 v53, 0xbfb8aa3b, v46
	v_mul_f32_e32 v54, 0xbfb8aa3b, v47
	v_rcp_f32_e32 v44, v44
	v_exp_f32_e32 v53, v53
	v_exp_f32_e32 v54, v54
	v_mul_f32_e32 v44, v45, v44
	v_add_f32_e32 v45, 1.0, v53
	v_add_f32_e32 v53, 1.0, v54
	v_rcp_f32_e32 v45, v45
	v_rcp_f32_e32 v53, v53
	v_cvt_pk_fp8_f32 v56, v43, v44
	v_lshl_add_u64 v[54:55], s[0:1], 0, v[40:41]
	v_mul_f32_e32 v43, v46, v45
	v_mul_f32_e32 v44, v47, v53
	v_cvt_pk_fp8_f32 v56, v43, v44 op_sel:[0,0,1]
	v_pk_mul_f32 v[44:45], v[48:49], v[52:53] op_sel_hi:[1,0]
	v_pk_mul_f32 v[46:47], v[50:51], v[52:53] op_sel_hi:[1,0]
	s_waitcnt vmcnt(4)
	v_pk_fma_f32 v[44:45], v[16:17], v[44:45], v[20:21]
	v_pk_fma_f32 v[46:47], v[18:19], v[46:47], v[22:23]
	v_mul_f32_e32 v43, 0xbfb8aa3b, v44
	v_mul_f32_e32 v48, 0xbfb8aa3b, v45
	v_exp_f32_e32 v43, v43
	v_exp_f32_e32 v48, v48
	v_mul_f32_e32 v49, 0xbfb8aa3b, v46
	v_mul_f32_e32 v50, 0xbfb8aa3b, v47
	v_add_f32_e32 v43, 1.0, v43
	v_add_f32_e32 v48, 1.0, v48
	v_rcp_f32_e32 v43, v43
	v_exp_f32_e32 v49, v49
	v_exp_f32_e32 v50, v50
	v_rcp_f32_e32 v48, v48
	v_pk_mul_f32 v[36:37], v[36:37], v[52:53] op_sel_hi:[1,0]
	v_add_f32_e32 v49, 1.0, v49
	v_add_f32_e32 v50, 1.0, v50
	v_mul_f32_e32 v43, v44, v43
	v_mul_f32_e32 v44, v45, v48
	v_mov_b32_e32 v48, v201
	s_waitcnt vmcnt(1)
; #define LAS __attribute__((address_space(3)))
; __device__ __forceinline__ unsigned pk4_fp8(f32x4 v) { int w = 0; w = __builtin_amdgcn_cvt_pk_fp8_f32(v[0], v[1], w, false); w = __builtin_amdgcn_cvt_pk_fp8_f32(v[2], v[3], w, true); return (unsigned)w; }
; __device__ __forceinline__ float sigmoidf_(float x) { return frcp(1.0f + __expf(-x)); }
; __device__ __forceinline__ void conf_unit(const Frame& F, int l, int unit) {
;     ...
;     for (int k = 0; k < 4; ++k) { const int t = 4 * wave + k; f32x4 v[4]; float s = 0.f;
; #pragma unroll
;         for (int j = 0; j < 4; ++j) { v[j] = *(const LAS f32x4*)(CB + t * 1024 + 256 * j + 4 * lane); s += (v[j][0] + v[j][1]) + (v[j][2] + v[j][3]); }
;         const float mean = wave_sum(s) * (1.0f / 1024.0f); float q = 0.f;
; #pragma unroll
;         for (int j = 0; j < 4; ++j) { v[j] = v[j] - mean; q += (v[j][0] * v[j][0] + v[j][1] * v[j][1]) + (v[j][2] * v[j][2] + v[j][3] * v[j][3]); }
;         const float rstd = 1.0f / sqrtf(wave_sum(q) * (1.0f / 1024.0f) + LN_EPS);
; #pragma unroll
;         for (int j = 0; j < 4; ++j) { const int cix = 256 * j + 4 * lane; const f32x4 gg = lgv[j], bb = lbv[j]; f32x4 y = v[j] * rstd * gg + bb;
; #pragma unroll
;             for (int e = 0; e < 4; ++e) y[e] = y[e] * sigmoidf_(y[e]);
;             *(unsigned*)(YB + (size_t)(r0 + t) * WL + cix) = pk4_fp8(y); } }
	v_pk_fma_f32 v[36:37], v[8:9], v[36:37], v[12:13]
	v_rcp_f32_e32 v49, v49
	v_rcp_f32_e32 v50, v50
	v_cvt_pk_fp8_f32 v48, v43, v44
	v_mul_f32_e32 v43, 0xbfb8aa3b, v36
	v_exp_f32_e32 v43, v43
	v_mul_f32_e32 v44, 0xbfb8aa3b, v37
	v_exp_f32_e32 v44, v44
	v_pk_mul_f32 v[38:39], v[38:39], v[52:53] op_sel_hi:[1,0]
	v_mul_f32_e32 v45, v46, v49
	v_mul_f32_e32 v46, v47, v50
	v_pk_fma_f32 v[38:39], v[10:11], v[38:39], v[14:15]
	v_cvt_pk_fp8_f32 v48, v45, v46 op_sel:[0,0,1]
	v_add_f32_e32 v43, 1.0, v43
	v_mul_f32_e32 v46, 0xbfb8aa3b, v39
	v_rcp_f32_e32 v43, v43
	v_add_f32_e32 v44, 1.0, v44
	v_exp_f32_e32 v46, v46
	v_rcp_f32_e32 v44, v44
	v_pk_mul_f32 v[32:33], v[32:33], v[52:53] op_sel_hi:[1,0]
	v_mul_f32_e32 v36, v36, v43
	v_add_f32_e32 v43, 1.0, v46
	s_waitcnt vmcnt(0)
	v_pk_fma_f32 v[32:33], v[0:1], v[32:33], v[4:5]
	v_mul_f32_e32 v37, v37, v44
	v_rcp_f32_e32 v43, v43
	v_mul_f32_e32 v44, 0xbfb8aa3b, v32
	v_exp_f32_e32 v44, v44
	v_pk_mul_f32 v[34:35], v[34:35], v[52:53] op_sel_hi:[1,0]
	v_mul_f32_e32 v39, v39, v43
	v_mov_b32_e32 v43, v201
	v_cvt_pk_fp8_f32 v43, v36, v37
	v_add_f32_e32 v36, 1.0, v44
	v_mul_f32_e32 v37, 0xbfb8aa3b, v33
	v_rcp_f32_e32 v36, v36
	v_exp_f32_e32 v37, v37
	v_mul_f32_e32 v45, 0xbfb8aa3b, v38
	v_pk_fma_f32 v[34:35], v[2:3], v[34:35], v[6:7]
	v_exp_f32_e32 v45, v45
	v_mul_f32_e32 v32, v32, v36
	v_add_f32_e32 v36, 1.0, v37
	v_mul_f32_e32 v37, 0xbfb8aa3b, v34
	v_mul_f32_e32 v44, 0xbfb8aa3b, v35
	v_rcp_f32_e32 v36, v36
	v_exp_f32_e32 v37, v37
	v_exp_f32_e32 v44, v44
	v_add_f32_e32 v45, 1.0, v45
	v_rcp_f32_e32 v45, v45
	v_mul_f32_e32 v33, v33, v36
	v_add_f32_e32 v36, 1.0, v37
	v_add_f32_e32 v37, 1.0, v44
	v_rcp_f32_e32 v36, v36
	v_rcp_f32_e32 v37, v37
	v_mov_b32_e32 v49, v201
	v_cvt_pk_fp8_f32 v49, v32, v33
	v_add_u32_e32 v53, s25, v42
	v_mul_f32_e32 v38, v38, v45
	ds_read_b128 v[44:47], v53
	v_cvt_pk_fp8_f32 v43, v38, v39 op_sel:[0,0,1]
	v_mul_f32_e32 v32, v34, v36
	v_mul_f32_e32 v33, v35, v37
	v_cvt_pk_fp8_f32 v49, v32, v33 op_sel:[0,0,1]
	global_store_dword v[54:55], v56, off
	global_store_dword v[54:55], v48, off offset:256
	global_store_dword v[54:55], v43, off offset:512
	global_store_dword v[54:55], v49, off offset:768
	ds_read_b128 v[48:51], v53 offset:1024
	ds_read_b128 v[36:39], v53 offset:2048
	s_waitcnt lgkmcnt(2)
	v_mov_b32_e32 v32, v45
	v_mov_b32_e32 v33, v46
	v_mov_b32_e32 v34, v44
	v_mov_b32_e32 v35, v47
	v_pk_add_f32 v[32:33], v[32:33], v[34:35]
	s_waitcnt lgkmcnt(1)
	v_mov_b32_e32 v54, v49
	v_add_f32_e32 v32, v32, v33
	v_add_f32_e32 v52, 0, v32
	ds_read_b128 v[32:35], v53 offset:3072
	v_mov_b32_e32 v55, v50
	v_mov_b32_e32 v56, v48
	v_mov_b32_e32 v57, v51
	v_pk_add_f32 v[54:55], v[54:55], v[56:57]
	s_waitcnt lgkmcnt(1)
	v_add_f32_e32 v56, v36, v37
	v_pk_add_f32 v[54:55], v[54:55], v[54:55] op_sel:[0,1] op_sel_hi:[1,0]
	v_add_f32_e32 v58, v38, v39
	s_waitcnt lgkmcnt(0)
	v_mov_b32_e32 v53, v32
	v_mov_b32_e32 v55, v33
	v_mov_b32_e32 v57, v34
	v_mov_b32_e32 v59, v35
	v_pk_add_f32 v[52:53], v[52:53], v[54:55]
	v_pk_add_f32 v[54:55], v[56:57], v[58:59]
	s_nop 0
	v_pk_add_f32 v[52:53], v[52:53], v[54:55]
	s_nop 0
	v_add_f32_e32 v43, v52, v53
	v_mbcnt_lo_u32_b32 v52, -1, 0
	v_mbcnt_hi_u32_b32 v52, -1, v52
	s_nop 0
	v_lshlrev_b32_e32 v52, 2, v52
	v_xor_b32_e32 v53, 4, v52
	ds_bpermute_b32 v53, v53, v43
	s_waitcnt lgkmcnt(0)
	v_add_f32_e32 v43, v43, v53
	v_xor_b32_e32 v53, 8, v52
	ds_bpermute_b32 v53, v53, v43
	s_waitcnt lgkmcnt(0)
	v_add_f32_e32 v43, v43, v53
	v_xor_b32_e32 v53, 16, v52
	ds_bpermute_b32 v53, v53, v43
	s_waitcnt lgkmcnt(0)
	v_add_f32_e32 v43, v43, v53
	v_xor_b32_e32 v53, 32, v52
	ds_bpermute_b32 v53, v53, v43
	s_waitcnt lgkmcnt(0)
	v_add_f32_e32 v43, v43, v53
	v_xor_b32_e32 v53, 64, v52
	ds_bpermute_b32 v53, v53, v43
	v_xor_b32_e32 v52, 0x80, v52
	s_waitcnt lgkmcnt(0)
	v_add_f32_e32 v43, v43, v53
	ds_bpermute_b32 v52, v52, v43
	s_waitcnt lgkmcnt(0)
	v_add_f32_e32 v43, v43, v52
	v_fmamk_f32 v45, v43, 0xba800000, v45
	v_fmamk_f32 v44, v43, 0xba800000, v44
	v_fmamk_f32 v47, v43, 0xba800000, v47
	v_fmac_f32_e32 v46, 0xba800000, v43
	v_pk_mul_f32 v[52:53], v[46:47], v[46:47]
	v_pk_mul_f32 v[54:55], v[44:45], v[44:45]
	v_fmamk_f32 v49, v43, 0xba800000, v49
	v_pk_mov_b32 v[56:57], v[54:55], v[52:53] op_sel:[1,0]
	v_mov_b32_e32 v55, v53
	v_pk_add_f32 v[52:53], v[56:57], v[54:55]
	v_fmamk_f32 v48, v43, 0xba800000, v48
	v_fmamk_f32 v51, v43, 0xba800000, v51
	v_fmac_f32_e32 v50, 0xba800000, v43
	v_pk_add_f32 v[52:53], v[52:53], v[52:53] op_sel_hi:[0,1]
	v_pk_mul_f32 v[54:55], v[50:51], v[50:51]
	v_pk_mul_f32 v[56:57], v[48:49], v[48:49]
	v_fmamk_f32 v36, v43, 0xba800000, v36
	v_pk_mov_b32 v[58:59], v[56:57], v[54:55] op_sel:[1,0]
	v_mov_b32_e32 v57, v55
	v_fmamk_f32 v37, v43, 0xba800000, v37
	v_fmac_f32_e32 v38, 0xba800000, v43
	v_mul_f32_e32 v52, v36, v36
	v_pk_add_f32 v[54:55], v[58:59], v[56:57]
	v_fmamk_f32 v39, v43, 0xba800000, v39
	v_pk_fma_f32 v[56:57], v[36:37], v[36:37], v[52:53] op_sel_hi:[1,1,0]
	v_mul_f32_e32 v52, v38, v38
	v_pk_add_f32 v[54:55], v[54:55], v[54:55] op_sel_hi:[0,1]
	v_pk_fma_f32 v[58:59], v[38:39], v[38:39], v[52:53] op_sel_hi:[1,1,0]
	v_fmamk_f32 v35, v43, 0xba800000, v35
	v_fmamk_f32 v34, v43, 0xba800000, v34
	v_fmamk_f32 v33, v43, 0xba800000, v33
	v_fmac_f32_e32 v32, 0xba800000, v43
	v_mul_f32_e32 v56, v32, v32
	v_mul_f32_e32 v58, v33, v33
	v_mul_f32_e32 v52, v34, v34
	v_mul_f32_e32 v54, v35, v35
	v_pk_add_f32 v[56:57], v[56:57], v[58:59]
	v_pk_add_f32 v[52:53], v[52:53], v[54:55]
	s_nop 0
	v_pk_add_f32 v[52:53], v[56:57], v[52:53]
	s_nop 0
	v_add_f32_e32 v43, v52, v53
	v_mbcnt_lo_u32_b32 v52, -1, 0
	v_mbcnt_hi_u32_b32 v52, -1, v52
	s_nop 0
	v_lshlrev_b32_e32 v52, 2, v52
	v_xor_b32_e32 v53, 4, v52
	ds_bpermute_b32 v53, v53, v43
	s_waitcnt lgkmcnt(0)
; #define LAS __attribute__((address_space(3)))
; __device__ __forceinline__ unsigned pk4_fp8(f32x4 v) { int w = 0; w = __builtin_amdgcn_cvt_pk_fp8_f32(v[0], v[1], w, false); w = __builtin_amdgcn_cvt_pk_fp8_f32(v[2], v[3], w, true); return (unsigned)w; }
; __device__ __forceinline__ float sigmoidf_(float x) { return frcp(1.0f + __expf(-x)); }
; __device__ __forceinline__ void conf_unit(const Frame& F, int l, int unit) {
;     ...
;     for (int k = 0; k < 4; ++k) { const int t = 4 * wave + k; f32x4 v[4]; float s = 0.f;
; #pragma unroll
;         for (int j = 0; j < 4; ++j) { v[j] = *(const LAS f32x4*)(CB + t * 1024 + 256 * j + 4 * lane); s += (v[j][0] + v[j][1]) + (v[j][2] + v[j][3]); }
;         const float mean = wave_sum(s) * (1.0f / 1024.0f); float q = 0.f;
; #pragma unroll
;         for (int j = 0; j < 4; ++j) { v[j] = v[j] - mean; q += (v[j][0] * v[j][0] + v[j][1] * v[j][1]) + (v[j][2] * v[j][2] + v[j][3] * v[j][3]); }
;         const float rstd = 1.0f / sqrtf(wave_sum(q) * (1.0f / 1024.0f) + LN_EPS);
; #pragma unroll
;         for (int j = 0; j < 4; ++j) { const int cix = 256 * j + 4 * lane; const f32x4 gg = lgv[j], bb = lbv[j]; f32x4 y = v[j] * rstd * gg + bb;
; #pragma unroll
;             for (int e = 0; e < 4; ++e) y[e] = y[e] * sigmoidf_(y[e]);
;             *(unsigned*)(YB + (size_t)(r0 + t) * WL + cix) = pk4_fp8(y); } }
	v_add_f32_e32 v43, v43, v53
	v_xor_b32_e32 v53, 8, v52
	ds_bpermute_b32 v53, v53, v43
	s_waitcnt lgkmcnt(0)
	v_add_f32_e32 v43, v43, v53
	v_xor_b32_e32 v53, 16, v52
	ds_bpermute_b32 v53, v53, v43
	s_waitcnt lgkmcnt(0)
	v_add_f32_e32 v43, v43, v53
	v_xor_b32_e32 v53, 32, v52
	ds_bpermute_b32 v53, v53, v43
	s_waitcnt lgkmcnt(0)
	v_add_f32_e32 v43, v43, v53
	v_xor_b32_e32 v53, 64, v52
	ds_bpermute_b32 v53, v53, v43
	v_xor_b32_e32 v52, 0x80, v52
	s_waitcnt lgkmcnt(0)
	v_add_f32_e32 v43, v43, v53
	ds_bpermute_b32 v52, v52, v43
	s_waitcnt lgkmcnt(0)
	v_add_f32_e32 v43, v43, v52
	v_fmamk_f32 v43, v43, 0x3a800000, v232
	v_mul_f32_e32 v52, 0x4f800000, v43
	v_cmp_gt_f32_e32 vcc, s89, v43
	s_nop 1
	v_cndmask_b32_e32 v43, v43, v52, vcc
	v_sqrt_f32_e32 v52, v43
	s_nop 0
	v_add_u32_e32 v53, -1, v52
	v_fma_f32 v54, -v53, v52, v43
	v_cmp_ge_f32_e64 s[0:1], 0, v54
	v_add_u32_e32 v54, 1, v52
	s_nop 0
	v_cndmask_b32_e64 v53, v52, v53, s[0:1]
	v_fma_f32 v52, -v54, v52, v43
	v_cmp_lt_f32_e64 s[0:1], 0, v52
	s_nop 1
	v_cndmask_b32_e64 v52, v53, v54, s[0:1]
	v_mul_f32_e32 v53, 0x37800000, v52
	v_cndmask_b32_e32 v52, v52, v53, vcc
	v_cmp_class_f32_e32 vcc, v43, v223
	s_nop 1
	v_cndmask_b32_e32 v43, v52, v43, vcc
	v_div_scale_f32 v52, s[0:1], v43, v43, 1.0
	v_rcp_f32_e32 v53, v52
	s_add_i32 s0, s20, s24
	s_ashr_i32 s1, s0, 31
	s_lshl_b64 s[0:1], s[0:1], 10
	v_fma_f32 v54, -v52, v53, 1.0
	v_fmac_f32_e32 v53, v54, v53
	v_div_scale_f32 v54, vcc, 1.0, v43, 1.0
	v_mul_f32_e32 v55, v54, v53
	v_fma_f32 v56, -v52, v55, v54
	v_fmac_f32_e32 v55, v56, v53
	v_fma_f32 v52, -v52, v55, v54
	v_div_fmas_f32 v52, v52, v53, v55
	v_div_fixup_f32 v52, v52, v43, 1.0
	v_pk_mul_f32 v[44:45], v[44:45], v[52:53] op_sel_hi:[1,0]
	v_mov_b32_e32 v56, v201
	v_pk_fma_f32 v[44:45], v[24:25], v[44:45], v[28:29]
	s_add_u32 s0, s4, s0
	v_mul_f32_e32 v43, 0xbfb8aa3b, v44
	v_exp_f32_e32 v43, v43
	v_mul_f32_e32 v53, 0xbfb8aa3b, v45
	v_exp_f32_e32 v53, v53
	s_addc_u32 s1, s5, s1
	v_add_f32_e32 v43, 1.0, v43
	v_rcp_f32_e32 v43, v43
	v_pk_mul_f32 v[46:47], v[46:47], v[52:53] op_sel_hi:[1,0]
	v_mul_f32_e32 v43, v44, v43
	v_pk_fma_f32 v[46:47], v[26:27], v[46:47], v[30:31]
	v_add_f32_e32 v44, 1.0, v53
	v_mul_f32_e32 v53, 0xbfb8aa3b, v46
	v_mul_f32_e32 v54, 0xbfb8aa3b, v47
	v_rcp_f32_e32 v44, v44
	v_exp_f32_e32 v53, v53
	v_exp_f32_e32 v54, v54
	v_mul_f32_e32 v44, v45, v44
	v_add_f32_e32 v45, 1.0, v53
	v_add_f32_e32 v53, 1.0, v54
	v_rcp_f32_e32 v45, v45
	v_rcp_f32_e32 v53, v53
	v_cvt_pk_fp8_f32 v56, v43, v44
	v_lshl_add_u64 v[54:55], s[0:1], 0, v[40:41]
	v_mul_f32_e32 v43, v46, v45
	v_mul_f32_e32 v44, v47, v53
	v_cvt_pk_fp8_f32 v56, v43, v44 op_sel:[0,0,1]
	v_pk_mul_f32 v[44:45], v[48:49], v[52:53] op_sel_hi:[1,0]
	v_pk_mul_f32 v[46:47], v[50:51], v[52:53] op_sel_hi:[1,0]
	v_pk_fma_f32 v[44:45], v[16:17], v[44:45], v[20:21]
	v_pk_fma_f32 v[46:47], v[18:19], v[46:47], v[22:23]
	v_mul_f32_e32 v43, 0xbfb8aa3b, v44
	v_mul_f32_e32 v48, 0xbfb8aa3b, v45
	v_exp_f32_e32 v43, v43
	v_exp_f32_e32 v48, v48
	v_mul_f32_e32 v49, 0xbfb8aa3b, v46
	v_mul_f32_e32 v50, 0xbfb8aa3b, v47
	v_add_f32_e32 v43, 1.0, v43
	v_add_f32_e32 v48, 1.0, v48
	v_rcp_f32_e32 v43, v43
	v_exp_f32_e32 v49, v49
	v_exp_f32_e32 v50, v50
	v_rcp_f32_e32 v48, v48
	v_pk_mul_f32 v[36:37], v[36:37], v[52:53] op_sel_hi:[1,0]
	v_add_f32_e32 v49, 1.0, v49
	v_add_f32_e32 v50, 1.0, v50
	v_mul_f32_e32 v43, v44, v43
	v_mul_f32_e32 v44, v45, v48
	v_mov_b32_e32 v48, v201
	v_pk_fma_f32 v[36:37], v[8:9], v[36:37], v[12:13]
	v_rcp_f32_e32 v49, v49
	v_rcp_f32_e32 v50, v50
	v_cvt_pk_fp8_f32 v48, v43, v44
	v_mul_f32_e32 v43, 0xbfb8aa3b, v36
	v_exp_f32_e32 v43, v43
	v_mul_f32_e32 v44, 0xbfb8aa3b, v37
	v_exp_f32_e32 v44, v44
	v_pk_mul_f32 v[38:39], v[38:39], v[52:53] op_sel_hi:[1,0]
	v_mul_f32_e32 v45, v46, v49
	v_mul_f32_e32 v46, v47, v50
	v_pk_fma_f32 v[38:39], v[10:11], v[38:39], v[14:15]
	v_cvt_pk_fp8_f32 v48, v45, v46 op_sel:[0,0,1]
	v_add_f32_e32 v43, 1.0, v43
	v_mul_f32_e32 v46, 0xbfb8aa3b, v39
	v_rcp_f32_e32 v43, v43
	v_add_f32_e32 v44, 1.0, v44
	v_exp_f32_e32 v46, v46
	v_rcp_f32_e32 v44, v44
	v_pk_mul_f32 v[32:33], v[32:33], v[52:53] op_sel_hi:[1,0]
	v_mul_f32_e32 v36, v36, v43
	v_add_f32_e32 v43, 1.0, v46
	v_pk_fma_f32 v[32:33], v[0:1], v[32:33], v[4:5]
	v_mul_f32_e32 v37, v37, v44
	v_rcp_f32_e32 v43, v43
	v_mul_f32_e32 v44, 0xbfb8aa3b, v32
	v_exp_f32_e32 v44, v44
	v_pk_mul_f32 v[34:35], v[34:35], v[52:53] op_sel_hi:[1,0]
	v_mul_f32_e32 v39, v39, v43
	v_mov_b32_e32 v43, v201
	v_cvt_pk_fp8_f32 v43, v36, v37
	v_add_f32_e32 v36, 1.0, v44
	v_mul_f32_e32 v37, 0xbfb8aa3b, v33
	v_rcp_f32_e32 v36, v36
	v_exp_f32_e32 v37, v37
	v_mul_f32_e32 v45, 0xbfb8aa3b, v38
	v_pk_fma_f32 v[34:35], v[2:3], v[34:35], v[6:7]
	v_exp_f32_e32 v45, v45
	v_mul_f32_e32 v32, v32, v36
	v_add_f32_e32 v36, 1.0, v37
	v_mul_f32_e32 v37, 0xbfb8aa3b, v34
	v_mul_f32_e32 v44, 0xbfb8aa3b, v35
	v_rcp_f32_e32 v36, v36
	v_exp_f32_e32 v37, v37
	v_exp_f32_e32 v44, v44
	v_add_f32_e32 v45, 1.0, v45
	v_rcp_f32_e32 v45, v45
	v_mul_f32_e32 v33, v33, v36
	v_add_f32_e32 v36, 1.0, v37
	v_add_f32_e32 v37, 1.0, v44
	v_rcp_f32_e32 v36, v36
	v_rcp_f32_e32 v37, v37
	v_mov_b32_e32 v49, v201
	v_cvt_pk_fp8_f32 v49, v32, v33
	v_add_u32_e32 v53, s27, v42
	v_mul_f32_e32 v38, v38, v45
	ds_read_b128 v[44:47], v53
	v_cvt_pk_fp8_f32 v43, v38, v39 op_sel:[0,0,1]
	v_mul_f32_e32 v32, v34, v36
	v_mul_f32_e32 v33, v35, v37
	v_cvt_pk_fp8_f32 v49, v32, v33 op_sel:[0,0,1]
	global_store_dword v[54:55], v56, off
	global_store_dword v[54:55], v48, off offset:256
	global_store_dword v[54:55], v43, off offset:512
	global_store_dword v[54:55], v49, off offset:768
	ds_read_b128 v[48:51], v53 offset:1024
	ds_read_b128 v[36:39], v53 offset:2048
	s_waitcnt lgkmcnt(2)
; #define LAS __attribute__((address_space(3)))
; __device__ __forceinline__ unsigned pk4_fp8(f32x4 v) { int w = 0; w = __builtin_amdgcn_cvt_pk_fp8_f32(v[0], v[1], w, false); w = __builtin_amdgcn_cvt_pk_fp8_f32(v[2], v[3], w, true); return (unsigned)w; }
; __device__ __forceinline__ float sigmoidf_(float x) { return frcp(1.0f + __expf(-x)); }
; __device__ __forceinline__ void conf_unit(const Frame& F, int l, int unit) {
;     ...
;     for (int k = 0; k < 4; ++k) { const int t = 4 * wave + k; f32x4 v[4]; float s = 0.f;
; #pragma unroll
;         for (int j = 0; j < 4; ++j) { v[j] = *(const LAS f32x4*)(CB + t * 1024 + 256 * j + 4 * lane); s += (v[j][0] + v[j][1]) + (v[j][2] + v[j][3]); }
;         const float mean = wave_sum(s) * (1.0f / 1024.0f); float q = 0.f;
; #pragma unroll
;         for (int j = 0; j < 4; ++j) { v[j] = v[j] - mean; q += (v[j][0] * v[j][0] + v[j][1] * v[j][1]) + (v[j][2] * v[j][2] + v[j][3] * v[j][3]); }
;         const float rstd = 1.0f / sqrtf(wave_sum(q) * (1.0f / 1024.0f) + LN_EPS);
; #pragma unroll
;         for (int j = 0; j < 4; ++j) { const int cix = 256 * j + 4 * lane; const f32x4 gg = lgv[j], bb = lbv[j]; f32x4 y = v[j] * rstd * gg + bb;
; #pragma unroll
;             for (int e = 0; e < 4; ++e) y[e] = y[e] * sigmoidf_(y[e]);
;             *(unsigned*)(YB + (size_t)(r0 + t) * WL + cix) = pk4_fp8(y); } }
	v_mov_b32_e32 v32, v45
	v_mov_b32_e32 v33, v46
	v_mov_b32_e32 v34, v44
	v_mov_b32_e32 v35, v47
	v_pk_add_f32 v[32:33], v[32:33], v[34:35]
	s_waitcnt lgkmcnt(1)
	v_mov_b32_e32 v54, v49
	v_add_f32_e32 v32, v32, v33
	v_add_f32_e32 v52, 0, v32
	ds_read_b128 v[32:35], v53 offset:3072
	v_mov_b32_e32 v55, v50
	v_mov_b32_e32 v56, v48
	v_mov_b32_e32 v57, v51
	v_pk_add_f32 v[54:55], v[54:55], v[56:57]
	s_waitcnt lgkmcnt(1)
	v_add_f32_e32 v56, v36, v37
	v_pk_add_f32 v[54:55], v[54:55], v[54:55] op_sel:[0,1] op_sel_hi:[1,0]
	v_add_f32_e32 v58, v38, v39
	s_waitcnt lgkmcnt(0)
	v_mov_b32_e32 v53, v32
	v_mov_b32_e32 v55, v33
	v_mov_b32_e32 v57, v34
	v_mov_b32_e32 v59, v35
	v_pk_add_f32 v[52:53], v[52:53], v[54:55]
	v_pk_add_f32 v[54:55], v[56:57], v[58:59]
	s_nop 0
	v_pk_add_f32 v[52:53], v[52:53], v[54:55]
	s_nop 0
	v_add_f32_e32 v43, v52, v53
	v_mbcnt_lo_u32_b32 v52, -1, 0
	v_mbcnt_hi_u32_b32 v52, -1, v52
	s_nop 0
	v_lshlrev_b32_e32 v52, 2, v52
	v_xor_b32_e32 v53, 4, v52
	ds_bpermute_b32 v53, v53, v43
	s_waitcnt lgkmcnt(0)
	v_add_f32_e32 v43, v43, v53
	v_xor_b32_e32 v53, 8, v52
	ds_bpermute_b32 v53, v53, v43
	s_waitcnt lgkmcnt(0)
	v_add_f32_e32 v43, v43, v53
	v_xor_b32_e32 v53, 16, v52
	ds_bpermute_b32 v53, v53, v43
	s_waitcnt lgkmcnt(0)
	v_add_f32_e32 v43, v43, v53
	v_xor_b32_e32 v53, 32, v52
	ds_bpermute_b32 v53, v53, v43
	s_waitcnt lgkmcnt(0)
	v_add_f32_e32 v43, v43, v53
	v_xor_b32_e32 v53, 64, v52
	ds_bpermute_b32 v53, v53, v43
	v_xor_b32_e32 v52, 0x80, v52
	s_waitcnt lgkmcnt(0)
	v_add_f32_e32 v43, v43, v53
	ds_bpermute_b32 v52, v52, v43
	s_waitcnt lgkmcnt(0)
	v_add_f32_e32 v43, v43, v52
	v_fmamk_f32 v45, v43, 0xba800000, v45
	v_fmamk_f32 v44, v43, 0xba800000, v44
	v_fmamk_f32 v47, v43, 0xba800000, v47
	v_fmac_f32_e32 v46, 0xba800000, v43
	v_pk_mul_f32 v[52:53], v[46:47], v[46:47]
	v_pk_mul_f32 v[54:55], v[44:45], v[44:45]
	v_fmamk_f32 v49, v43, 0xba800000, v49
	v_pk_mov_b32 v[56:57], v[54:55], v[52:53] op_sel:[1,0]
	v_mov_b32_e32 v55, v53
	v_pk_add_f32 v[52:53], v[56:57], v[54:55]
	v_fmamk_f32 v48, v43, 0xba800000, v48
	v_fmamk_f32 v51, v43, 0xba800000, v51
	v_fmac_f32_e32 v50, 0xba800000, v43
	v_pk_add_f32 v[52:53], v[52:53], v[52:53] op_sel_hi:[0,1]
	v_pk_mul_f32 v[54:55], v[50:51], v[50:51]
	v_pk_mul_f32 v[56:57], v[48:49], v[48:49]
	v_fmamk_f32 v36, v43, 0xba800000, v36
	v_pk_mov_b32 v[58:59], v[56:57], v[54:55] op_sel:[1,0]
	v_mov_b32_e32 v57, v55
	v_fmamk_f32 v37, v43, 0xba800000, v37
	v_fmac_f32_e32 v38, 0xba800000, v43
	v_mul_f32_e32 v52, v36, v36
	v_pk_add_f32 v[54:55], v[58:59], v[56:57]
	v_fmamk_f32 v39, v43, 0xba800000, v39
	v_pk_fma_f32 v[56:57], v[36:37], v[36:37], v[52:53] op_sel_hi:[1,1,0]
	v_mul_f32_e32 v52, v38, v38
	v_pk_add_f32 v[54:55], v[54:55], v[54:55] op_sel_hi:[0,1]
	v_pk_fma_f32 v[58:59], v[38:39], v[38:39], v[52:53] op_sel_hi:[1,1,0]
	v_fmamk_f32 v35, v43, 0xba800000, v35
	v_fmamk_f32 v34, v43, 0xba800000, v34
	v_fmamk_f32 v33, v43, 0xba800000, v33
	v_fmac_f32_e32 v32, 0xba800000, v43
	v_mul_f32_e32 v56, v32, v32
	v_mul_f32_e32 v58, v33, v33
	v_mul_f32_e32 v52, v34, v34
	v_mul_f32_e32 v54, v35, v35
	v_pk_add_f32 v[56:57], v[56:57], v[58:59]
	v_pk_add_f32 v[52:53], v[52:53], v[54:55]
	s_nop 0
	v_pk_add_f32 v[52:53], v[56:57], v[52:53]
	s_nop 0
	v_add_f32_e32 v43, v52, v53
	v_mbcnt_lo_u32_b32 v52, -1, 0
	v_mbcnt_hi_u32_b32 v52, -1, v52
	s_nop 0
	v_lshlrev_b32_e32 v52, 2, v52
	v_xor_b32_e32 v53, 4, v52
	ds_bpermute_b32 v53, v53, v43
	s_waitcnt lgkmcnt(0)
	v_add_f32_e32 v43, v43, v53
	v_xor_b32_e32 v53, 8, v52
	ds_bpermute_b32 v53, v53, v43
	s_waitcnt lgkmcnt(0)
	v_add_f32_e32 v43, v43, v53
	v_xor_b32_e32 v53, 16, v52
	ds_bpermute_b32 v53, v53, v43
	s_waitcnt lgkmcnt(0)
	v_add_f32_e32 v43, v43, v53
	v_xor_b32_e32 v53, 32, v52
	ds_bpermute_b32 v53, v53, v43
	s_waitcnt lgkmcnt(0)
	v_add_f32_e32 v43, v43, v53
	v_xor_b32_e32 v53, 64, v52
	ds_bpermute_b32 v53, v53, v43
	v_xor_b32_e32 v52, 0x80, v52
	s_waitcnt lgkmcnt(0)
	v_add_f32_e32 v43, v43, v53
	ds_bpermute_b32 v52, v52, v43
	s_waitcnt lgkmcnt(0)
	v_add_f32_e32 v43, v43, v52
	v_fmamk_f32 v43, v43, 0x3a800000, v232
	v_mul_f32_e32 v52, 0x4f800000, v43
	v_cmp_gt_f32_e32 vcc, s89, v43
	s_nop 1
	v_cndmask_b32_e32 v43, v43, v52, vcc
	v_sqrt_f32_e32 v52, v43
	s_nop 0
	v_add_u32_e32 v53, -1, v52
	v_fma_f32 v54, -v53, v52, v43
	v_cmp_ge_f32_e64 s[0:1], 0, v54
	v_add_u32_e32 v54, 1, v52
	s_nop 0
	v_cndmask_b32_e64 v53, v52, v53, s[0:1]
	v_fma_f32 v52, -v54, v52, v43
	v_cmp_lt_f32_e64 s[0:1], 0, v52
	s_nop 1
	v_cndmask_b32_e64 v52, v53, v54, s[0:1]
	v_mul_f32_e32 v53, 0x37800000, v52
	v_cndmask_b32_e32 v52, v52, v53, vcc
	v_cmp_class_f32_e32 vcc, v43, v223
	s_nop 1
	v_cndmask_b32_e32 v43, v52, v43, vcc
	v_div_scale_f32 v52, s[0:1], v43, v43, 1.0
	v_rcp_f32_e32 v53, v52
	s_add_i32 s0, s20, s26
	s_ashr_i32 s1, s0, 31
	s_lshl_b64 s[0:1], s[0:1], 10
	v_fma_f32 v54, -v52, v53, 1.0
	v_fmac_f32_e32 v53, v54, v53
	v_div_scale_f32 v54, vcc, 1.0, v43, 1.0
	v_mul_f32_e32 v55, v54, v53
	v_fma_f32 v56, -v52, v55, v54
	v_fmac_f32_e32 v55, v56, v53
	v_fma_f32 v52, -v52, v55, v54
	v_div_fmas_f32 v52, v52, v53, v55
	v_div_fixup_f32 v52, v52, v43, 1.0
	v_pk_mul_f32 v[44:45], v[44:45], v[52:53] op_sel_hi:[1,0]
	s_add_u32 s0, s4, s0
	v_pk_fma_f32 v[44:45], v[24:25], v[44:45], v[28:29]
	s_addc_u32 s1, s5, s1
	v_mul_f32_e32 v43, 0xbfb8aa3b, v44
	v_exp_f32_e32 v43, v43
	v_mul_f32_e32 v53, 0xbfb8aa3b, v45
	v_exp_f32_e32 v53, v53
	v_add_f32_e32 v43, 1.0, v43
	v_rcp_f32_e32 v43, v43
	v_pk_mul_f32 v[46:47], v[46:47], v[52:53] op_sel_hi:[1,0]
	v_mul_f32_e32 v43, v44, v43
	v_pk_fma_f32 v[46:47], v[26:27], v[46:47], v[30:31]
	v_add_f32_e32 v44, 1.0, v53
	v_mul_f32_e32 v53, 0xbfb8aa3b, v46
	v_mul_f32_e32 v54, 0xbfb8aa3b, v47
; #define LAS __attribute__((address_space(3)))
; __device__ __forceinline__ unsigned pk4_fp8(f32x4 v) { int w = 0; w = __builtin_amdgcn_cvt_pk_fp8_f32(v[0], v[1], w, false); w = __builtin_amdgcn_cvt_pk_fp8_f32(v[2], v[3], w, true); return (unsigned)w; }
; __device__ __forceinline__ float sigmoidf_(float x) { return frcp(1.0f + __expf(-x)); }
; __device__ __forceinline__ void conf_unit(const Frame& F, int l, int unit) {
;     ...
;     for (int k = 0; k < 4; ++k) { const int t = 4 * wave + k; f32x4 v[4]; float s = 0.f;
; #pragma unroll
;         for (int j = 0; j < 4; ++j) { v[j] = *(const LAS f32x4*)(CB + t * 1024 + 256 * j + 4 * lane); s += (v[j][0] + v[j][1]) + (v[j][2] + v[j][3]); }
;         const float mean = wave_sum(s) * (1.0f / 1024.0f); float q = 0.f;
; #pragma unroll
;         for (int j = 0; j < 4; ++j) { v[j] = v[j] - mean; q += (v[j][0] * v[j][0] + v[j][1] * v[j][1]) + (v[j][2] * v[j][2] + v[j][3] * v[j][3]); }
;         const float rstd = 1.0f / sqrtf(wave_sum(q) * (1.0f / 1024.0f) + LN_EPS);
; #pragma unroll
;         for (int j = 0; j < 4; ++j) { const int cix = 256 * j + 4 * lane; const f32x4 gg = lgv[j], bb = lbv[j]; f32x4 y = v[j] * rstd * gg + bb;
; #pragma unroll
;             for (int e = 0; e < 4; ++e) y[e] = y[e] * sigmoidf_(y[e]);
;             *(unsigned*)(YB + (size_t)(r0 + t) * WL + cix) = pk4_fp8(y); } }
	v_rcp_f32_e32 v44, v44
	v_exp_f32_e32 v53, v53
	v_exp_f32_e32 v54, v54
	v_mul_f32_e32 v44, v45, v44
	v_add_f32_e32 v45, 1.0, v53
	v_add_f32_e32 v53, 1.0, v54
	v_rcp_f32_e32 v45, v45
	v_rcp_f32_e32 v53, v53
	v_mov_b32_e32 v54, v201
	v_cvt_pk_fp8_f32 v54, v43, v44
	v_mul_f32_e32 v43, v46, v45
	v_mul_f32_e32 v44, v47, v53
	v_lshl_add_u64 v[46:47], s[0:1], 0, v[40:41]
	v_cvt_pk_fp8_f32 v54, v43, v44 op_sel:[0,0,1]
	v_pk_mul_f32 v[44:45], v[48:49], v[52:53] op_sel_hi:[1,0]
	v_pk_mul_f32 v[48:49], v[50:51], v[52:53] op_sel_hi:[1,0]
	v_pk_fma_f32 v[44:45], v[16:17], v[44:45], v[20:21]
	v_pk_fma_f32 v[48:49], v[18:19], v[48:49], v[22:23]
	v_mul_f32_e32 v43, 0xbfb8aa3b, v44
	v_mul_f32_e32 v53, 0xbfb8aa3b, v49
	v_mul_f32_e32 v50, 0xbfb8aa3b, v45
	v_mul_f32_e32 v51, 0xbfb8aa3b, v48
	v_exp_f32_e32 v53, v53
	v_exp_f32_e32 v43, v43
	v_exp_f32_e32 v50, v50
	v_exp_f32_e32 v51, v51
	v_add_f32_e32 v53, 1.0, v53
	v_add_f32_e32 v43, 1.0, v43
	v_add_f32_e32 v50, 1.0, v50
	v_add_f32_e32 v51, 1.0, v51
	v_rcp_f32_e32 v53, v53
	v_rcp_f32_e32 v43, v43
	v_rcp_f32_e32 v50, v50
	v_rcp_f32_e32 v51, v51
	v_pk_mul_f32 v[36:37], v[36:37], v[52:53] op_sel_hi:[1,0]
	v_mul_f32_e32 v43, v44, v43
	v_mul_f32_e32 v44, v45, v50
	v_mul_f32_e32 v45, v48, v51
	v_mul_f32_e32 v48, v49, v53
	v_mov_b32_e32 v49, v201
	v_pk_fma_f32 v[36:37], v[8:9], v[36:37], v[12:13]
	v_cvt_pk_fp8_f32 v49, v43, v44
	v_mul_f32_e32 v44, 0xbfb8aa3b, v37
	v_exp_f32_e32 v44, v44
	v_mul_f32_e32 v43, 0xbfb8aa3b, v36
	v_exp_f32_e32 v43, v43
	v_pk_mul_f32 v[38:39], v[38:39], v[52:53] op_sel_hi:[1,0]
	v_add_f32_e32 v44, 1.0, v44
	v_rcp_f32_e32 v44, v44
	v_pk_fma_f32 v[38:39], v[10:11], v[38:39], v[14:15]
	v_pk_mul_f32 v[32:33], v[32:33], v[52:53] op_sel_hi:[1,0]
	v_cvt_pk_fp8_f32 v49, v45, v48 op_sel:[0,0,1]
	v_add_f32_e32 v43, 1.0, v43
	v_mul_f32_e32 v48, 0xbfb8aa3b, v39
	v_pk_fma_f32 v[32:33], v[0:1], v[32:33], v[4:5]
	v_rcp_f32_e32 v43, v43
	v_exp_f32_e32 v48, v48
	v_mul_f32_e32 v37, v37, v44
	v_mul_f32_e32 v44, 0xbfb8aa3b, v32
	v_exp_f32_e32 v44, v44
	v_mul_f32_e32 v36, v36, v43
	v_add_f32_e32 v43, 1.0, v48
	v_mov_b32_e32 v48, v201
	v_cvt_pk_fp8_f32 v48, v36, v37
	v_add_f32_e32 v36, 1.0, v44
	v_mul_f32_e32 v37, 0xbfb8aa3b, v33
	v_rcp_f32_e32 v43, v43
	v_rcp_f32_e32 v36, v36
	v_exp_f32_e32 v37, v37
	v_pk_mul_f32 v[34:35], v[34:35], v[52:53] op_sel_hi:[1,0]
	v_mul_f32_e32 v45, 0xbfb8aa3b, v38
	v_pk_fma_f32 v[34:35], v[2:3], v[34:35], v[6:7]
	v_exp_f32_e32 v45, v45
	v_mul_f32_e32 v39, v39, v43
	v_mul_f32_e32 v32, v32, v36
	v_add_f32_e32 v36, 1.0, v37
	v_mul_f32_e32 v37, 0xbfb8aa3b, v34
	v_mul_f32_e32 v43, 0xbfb8aa3b, v35
	v_rcp_f32_e32 v36, v36
	v_exp_f32_e32 v37, v37
	v_exp_f32_e32 v43, v43
	v_add_f32_e32 v45, 1.0, v45
	v_rcp_f32_e32 v45, v45
	v_mul_f32_e32 v33, v33, v36
	v_add_f32_e32 v36, 1.0, v37
	v_add_f32_e32 v37, 1.0, v43
	v_rcp_f32_e32 v36, v36
	v_rcp_f32_e32 v37, v37
	v_mov_b32_e32 v50, v201
	v_cvt_pk_fp8_f32 v50, v32, v33
	v_add_u32_e32 v51, s29, v42
	v_mul_f32_e32 v38, v38, v45
	ds_read_b128 v[42:45], v51
	v_cvt_pk_fp8_f32 v48, v38, v39 op_sel:[0,0,1]
	v_mul_f32_e32 v32, v34, v36
	v_mul_f32_e32 v33, v35, v37
	v_cvt_pk_fp8_f32 v50, v32, v33 op_sel:[0,0,1]
	global_store_dword v[46:47], v54, off
	global_store_dword v[46:47], v49, off offset:256
	global_store_dword v[46:47], v48, off offset:512
	global_store_dword v[46:47], v50, off offset:768
	ds_read_b128 v[46:49], v51 offset:1024
	ds_read_b128 v[36:39], v51 offset:2048
	s_waitcnt lgkmcnt(2)
	v_mov_b32_e32 v32, v43
	v_mov_b32_e32 v33, v44
	v_mov_b32_e32 v34, v42
	v_mov_b32_e32 v35, v45
	v_pk_add_f32 v[32:33], v[32:33], v[34:35]
	s_waitcnt lgkmcnt(1)
	v_mov_b32_e32 v52, v47
	v_add_f32_e32 v32, v32, v33
	v_add_f32_e32 v50, 0, v32
	ds_read_b128 v[32:35], v51 offset:3072
	v_mov_b32_e32 v53, v48
	v_mov_b32_e32 v54, v46
	v_mov_b32_e32 v55, v49
	v_pk_add_f32 v[52:53], v[52:53], v[54:55]
	s_waitcnt lgkmcnt(1)
	v_add_f32_e32 v54, v36, v37
	v_pk_add_f32 v[52:53], v[52:53], v[52:53] op_sel:[0,1] op_sel_hi:[1,0]
	v_add_f32_e32 v56, v38, v39
	s_waitcnt lgkmcnt(0)
	v_mov_b32_e32 v51, v32
	v_mov_b32_e32 v53, v33
	v_mov_b32_e32 v55, v34
	v_mov_b32_e32 v57, v35
	v_pk_add_f32 v[50:51], v[50:51], v[52:53]
	v_pk_add_f32 v[52:53], v[54:55], v[56:57]
	s_nop 0
	v_pk_add_f32 v[50:51], v[50:51], v[52:53]
	s_nop 0
	v_add_f32_e32 v50, v50, v51
	v_mbcnt_lo_u32_b32 v51, -1, 0
	v_mbcnt_hi_u32_b32 v51, -1, v51
	s_nop 0
	v_lshlrev_b32_e32 v51, 2, v51
	v_xor_b32_e32 v52, 4, v51
	ds_bpermute_b32 v52, v52, v50
	s_waitcnt lgkmcnt(0)
	v_add_f32_e32 v50, v50, v52
	v_xor_b32_e32 v52, 8, v51
	ds_bpermute_b32 v52, v52, v50
	s_waitcnt lgkmcnt(0)
	v_add_f32_e32 v50, v50, v52
	v_xor_b32_e32 v52, 16, v51
	ds_bpermute_b32 v52, v52, v50
	s_waitcnt lgkmcnt(0)
	v_add_f32_e32 v50, v50, v52
	v_xor_b32_e32 v52, 32, v51
	ds_bpermute_b32 v52, v52, v50
	s_waitcnt lgkmcnt(0)
	v_add_f32_e32 v50, v50, v52
	v_xor_b32_e32 v52, 64, v51
	ds_bpermute_b32 v52, v52, v50
	v_xor_b32_e32 v51, 0x80, v51
	s_waitcnt lgkmcnt(0)
	v_add_f32_e32 v50, v50, v52
	ds_bpermute_b32 v51, v51, v50
	s_waitcnt lgkmcnt(0)
; __device__ __forceinline__ void conf_unit(const Frame& F, int l, int unit) {
;     ...
;         const float mean = wave_sum(s) * (1.0f / 1024.0f); float q = 0.f;
; #pragma unroll
;         for (int j = 0; j < 4; ++j) { v[j] = v[j] - mean; q += (v[j][0] * v[j][0] + v[j][1] * v[j][1]) + (v[j][2] * v[j][2] + v[j][3] * v[j][3]); }
	v_add_f32_e32 v58, v50, v51
	v_fmamk_f32 v43, v58, 0xba800000, v43
	v_fmamk_f32 v42, v58, 0xba800000, v42
	v_fmamk_f32 v45, v58, 0xba800000, v45
	v_fmac_f32_e32 v44, 0xba800000, v58
	v_pk_mul_f32 v[50:51], v[44:45], v[44:45]
	v_pk_mul_f32 v[52:53], v[42:43], v[42:43]
	v_fmamk_f32 v47, v58, 0xba800000, v47
	v_pk_mov_b32 v[54:55], v[52:53], v[50:51] op_sel:[1,0]
	v_mov_b32_e32 v53, v51
	v_pk_add_f32 v[50:51], v[54:55], v[52:53]
	v_fmamk_f32 v46, v58, 0xba800000, v46
	v_fmamk_f32 v49, v58, 0xba800000, v49
	v_fmac_f32_e32 v48, 0xba800000, v58
	v_pk_add_f32 v[50:51], v[50:51], v[50:51] op_sel_hi:[0,1]
	v_pk_mul_f32 v[52:53], v[48:49], v[48:49]
	v_pk_mul_f32 v[54:55], v[46:47], v[46:47]
	v_fmamk_f32 v36, v58, 0xba800000, v36
	v_pk_mov_b32 v[56:57], v[54:55], v[52:53] op_sel:[1,0]
	v_mov_b32_e32 v55, v53
	v_fmamk_f32 v37, v58, 0xba800000, v37
	v_fmac_f32_e32 v38, 0xba800000, v58
	v_mul_f32_e32 v50, v36, v36
	v_pk_add_f32 v[52:53], v[56:57], v[54:55]
	v_fmamk_f32 v39, v58, 0xba800000, v39
	v_pk_fma_f32 v[54:55], v[36:37], v[36:37], v[50:51] op_sel_hi:[1,1,0]
	v_mul_f32_e32 v50, v38, v38
	v_pk_add_f32 v[52:53], v[52:53], v[52:53] op_sel_hi:[0,1]
	v_pk_fma_f32 v[56:57], v[38:39], v[38:39], v[50:51] op_sel_hi:[1,1,0]
	v_fmamk_f32 v35, v58, 0xba800000, v35
	v_fmamk_f32 v34, v58, 0xba800000, v34
	v_fmamk_f32 v33, v58, 0xba800000, v33
	v_fmac_f32_e32 v32, 0xba800000, v58
	v_mul_f32_e32 v54, v32, v32
	v_mul_f32_e32 v56, v33, v33
	v_mul_f32_e32 v50, v34, v34
	v_mul_f32_e32 v52, v35, v35
	v_pk_add_f32 v[54:55], v[54:55], v[56:57]
	v_pk_add_f32 v[50:51], v[50:51], v[52:53]
	s_nop 0
	v_pk_add_f32 v[50:51], v[54:55], v[50:51]
	s_nop 0
	v_add_f32_e32 v50, v50, v51
	v_mbcnt_lo_u32_b32 v51, -1, 0
	v_mbcnt_hi_u32_b32 v51, -1, v51
	s_nop 0
	v_lshlrev_b32_e32 v51, 2, v51
	v_xor_b32_e32 v52, 4, v51
	ds_bpermute_b32 v52, v52, v50
	s_waitcnt lgkmcnt(0)
	v_add_f32_e32 v50, v50, v52
	v_xor_b32_e32 v52, 8, v51
	ds_bpermute_b32 v52, v52, v50
	s_waitcnt lgkmcnt(0)
	v_add_f32_e32 v50, v50, v52
	v_xor_b32_e32 v52, 16, v51
	ds_bpermute_b32 v52, v52, v50
	s_waitcnt lgkmcnt(0)
	v_add_f32_e32 v50, v50, v52
	v_xor_b32_e32 v52, 32, v51
	ds_bpermute_b32 v52, v52, v50
	s_waitcnt lgkmcnt(0)
	v_add_f32_e32 v50, v50, v52
	v_xor_b32_e32 v52, 64, v51
	ds_bpermute_b32 v52, v52, v50
	v_xor_b32_e32 v51, 0x80, v51
	s_waitcnt lgkmcnt(0)
	v_add_f32_e32 v50, v50, v52
	ds_bpermute_b32 v51, v51, v50
	s_waitcnt lgkmcnt(0)
; #define LAS __attribute__((address_space(3)))
; __device__ __forceinline__ unsigned pk4_fp8(f32x4 v) { int w = 0; w = __builtin_amdgcn_cvt_pk_fp8_f32(v[0], v[1], w, false); w = __builtin_amdgcn_cvt_pk_fp8_f32(v[2], v[3], w, true); return (unsigned)w; }
; __device__ __forceinline__ float sigmoidf_(float x) { return frcp(1.0f + __expf(-x)); }
; __device__ __forceinline__ int fresh_lane() { int ln; asm volatile("v_mbcnt_lo_u32_b32 %0, -1, 0\n\tv_mbcnt_hi_u32_b32 %0, -1, %0" : "=v"(ln)); return ln; }
; __device__ __forceinline__ int q_block(const Frame& F, int cw) {
;     volatile LAS int* slot = (volatile LAS int*)(F.lds + LDS_MISC + 64);
;     __syncthreads();
;     if (F.wave == 0 && fresh_lane() == 0) *slot = (int)__hip_atomic_fetch_add(F.ctl + cw, 1u, __ATOMIC_RELAXED, __HIP_MEMORY_SCOPE_AGENT);
;     __syncthreads();
;     return *slot;
; }
; __device__ __forceinline__ void conf_unit(const Frame& F, int l, int unit) {
;     ...
;         const float rstd = 1.0f / sqrtf(wave_sum(q) * (1.0f / 1024.0f) + LN_EPS);
; #pragma unroll
;         for (int j = 0; j < 4; ++j) { const int cix = 256 * j + 4 * lane; const f32x4 gg = lgv[j], bb = lbv[j]; f32x4 y = v[j] * rstd * gg + bb;
; #pragma unroll
;             for (int e = 0; e < 4; ++e) y[e] = y[e] * sigmoidf_(y[e]);
;             *(unsigned*)(YB + (size_t)(r0 + t) * WL + cix) = pk4_fp8(y); } }
;     __syncthreads();
; }
	v_add_f32_e32 v50, v50, v51
	v_fmamk_f32 v50, v50, 0x3a800000, v232
	v_mul_f32_e32 v51, 0x4f800000, v50
	v_cmp_gt_f32_e32 vcc, s89, v50
	s_nop 1
	v_cndmask_b32_e32 v50, v50, v51, vcc
	v_sqrt_f32_e32 v51, v50
	s_nop 0
	v_add_u32_e32 v52, -1, v51
	v_fma_f32 v53, -v52, v51, v50
	v_cmp_ge_f32_e64 s[0:1], 0, v53
	v_add_u32_e32 v53, 1, v51
	s_nop 0
	v_cndmask_b32_e64 v52, v51, v52, s[0:1]
	v_fma_f32 v51, -v53, v51, v50
	v_cmp_lt_f32_e64 s[0:1], 0, v51
	s_nop 1
	v_cndmask_b32_e64 v51, v52, v53, s[0:1]
	v_mul_f32_e32 v52, 0x37800000, v51
	v_cndmask_b32_e32 v51, v51, v52, vcc
	v_cmp_class_f32_e32 vcc, v50, v223
	s_nop 1
	v_cndmask_b32_e32 v50, v51, v50, vcc
	v_div_scale_f32 v51, s[0:1], v50, v50, 1.0
	v_rcp_f32_e32 v52, v51
	s_add_i32 s0, s20, s28
	s_ashr_i32 s1, s0, 31
	s_lshl_b64 s[0:1], s[0:1], 10
	v_fma_f32 v53, -v51, v52, 1.0
	v_fmac_f32_e32 v52, v53, v52
	v_div_scale_f32 v53, vcc, 1.0, v50, 1.0
	v_mul_f32_e32 v54, v53, v52
	v_fma_f32 v55, -v51, v54, v53
	v_fmac_f32_e32 v54, v55, v52
	v_fma_f32 v51, -v51, v54, v53
	v_div_fmas_f32 v51, v51, v52, v54
	v_div_fixup_f32 v50, v51, v50, 1.0
	v_pk_mul_f32 v[42:43], v[42:43], v[50:51] op_sel_hi:[1,0]
	s_add_u32 s0, s4, s0
	v_pk_fma_f32 v[24:25], v[24:25], v[42:43], v[28:29]
	s_addc_u32 s1, s5, s1
	v_mul_f32_e32 v28, 0xbfb8aa3b, v24
	v_exp_f32_e32 v28, v28
	s_andn2_b64 vcc, exec, s[48:49]
	v_add_f32_e32 v28, 1.0, v28
	v_rcp_f32_e32 v42, v28
	v_mul_f32_e32 v28, 0xbfb8aa3b, v25
	v_exp_f32_e32 v43, v28
	v_pk_mul_f32 v[28:29], v[44:45], v[50:51] op_sel_hi:[1,0]
	v_mul_f32_e32 v24, v24, v42
	v_pk_fma_f32 v[26:27], v[26:27], v[28:29], v[30:31]
	v_add_f32_e32 v28, 1.0, v43
	v_mul_f32_e32 v29, 0xbfb8aa3b, v26
	v_mul_f32_e32 v30, 0xbfb8aa3b, v27
	v_rcp_f32_e32 v28, v28
	v_exp_f32_e32 v29, v29
	v_exp_f32_e32 v30, v30
	v_mul_f32_e32 v25, v25, v28
	v_add_f32_e32 v28, 1.0, v29
	v_add_f32_e32 v29, 1.0, v30
	v_rcp_f32_e32 v28, v28
	v_rcp_f32_e32 v29, v29
	v_mov_b32_e32 v30, v201
	v_cvt_pk_fp8_f32 v30, v24, v25
	v_mul_f32_e32 v24, v26, v28
	v_mul_f32_e32 v25, v27, v29
	v_pk_mul_f32 v[26:27], v[46:47], v[50:51] op_sel_hi:[1,0]
	v_pk_mul_f32 v[28:29], v[48:49], v[50:51] op_sel_hi:[1,0]
	v_pk_fma_f32 v[16:17], v[16:17], v[26:27], v[20:21]
	v_pk_fma_f32 v[18:19], v[18:19], v[28:29], v[22:23]
	v_mul_f32_e32 v20, 0xbfb8aa3b, v16
	v_mul_f32_e32 v21, 0xbfb8aa3b, v17
	v_exp_f32_e32 v20, v20
	v_exp_f32_e32 v21, v21
	v_mul_f32_e32 v22, 0xbfb8aa3b, v18
	v_mul_f32_e32 v23, 0xbfb8aa3b, v19
	v_add_f32_e32 v20, 1.0, v20
	v_add_f32_e32 v21, 1.0, v21
	v_rcp_f32_e32 v20, v20
	v_rcp_f32_e32 v21, v21
	v_exp_f32_e32 v22, v22
	v_exp_f32_e32 v23, v23
	v_mul_f32_e32 v16, v16, v20
	v_mul_f32_e32 v17, v17, v21
	v_mov_b32_e32 v20, v201
	v_cvt_pk_fp8_f32 v20, v16, v17
	v_pk_mul_f32 v[16:17], v[36:37], v[50:51] op_sel_hi:[1,0]
	v_add_f32_e32 v22, 1.0, v22
	v_pk_fma_f32 v[8:9], v[8:9], v[16:17], v[12:13]
	v_add_f32_e32 v23, 1.0, v23
	v_mul_f32_e32 v12, 0xbfb8aa3b, v8
	v_exp_f32_e32 v16, v12
	v_pk_mul_f32 v[12:13], v[38:39], v[50:51] op_sel_hi:[1,0]
	v_rcp_f32_e32 v22, v22
	v_pk_fma_f32 v[10:11], v[10:11], v[12:13], v[14:15]
	v_mul_f32_e32 v13, 0xbfb8aa3b, v9
	v_mul_f32_e32 v14, 0xbfb8aa3b, v10
	v_exp_f32_e32 v13, v13
	v_exp_f32_e32 v14, v14
	v_add_f32_e32 v12, 1.0, v16
	v_mul_f32_e32 v15, 0xbfb8aa3b, v11
	v_rcp_f32_e32 v12, v12
	v_add_f32_e32 v13, 1.0, v13
	v_add_f32_e32 v14, 1.0, v14
	v_exp_f32_e32 v15, v15
	v_rcp_f32_e32 v13, v13
	v_rcp_f32_e32 v14, v14
	v_mul_f32_e32 v12, v8, v12
	v_add_f32_e32 v8, 1.0, v15
	v_mul_f32_e32 v13, v9, v13
	v_mul_f32_e32 v10, v10, v14
	v_rcp_f32_e32 v14, v8
	v_pk_mul_f32 v[8:9], v[32:33], v[50:51] op_sel_hi:[1,0]
	v_rcp_f32_e32 v23, v23
	v_pk_fma_f32 v[0:1], v[0:1], v[8:9], v[4:5]
	v_mul_f32_e32 v8, v11, v14
	v_mul_f32_e32 v4, 0xbfb8aa3b, v0
	v_exp_f32_e32 v4, v4
	v_mov_b32_e32 v9, v201
	v_cvt_pk_fp8_f32 v9, v12, v13
	v_cvt_pk_fp8_f32 v30, v24, v25 op_sel:[0,0,1]
	v_add_f32_e32 v4, 1.0, v4
	v_rcp_f32_e32 v11, v4
	v_mul_f32_e32 v4, 0xbfb8aa3b, v1
	v_exp_f32_e32 v12, v4
	v_pk_mul_f32 v[4:5], v[34:35], v[50:51] op_sel_hi:[1,0]
	v_mul_f32_e32 v0, v0, v11
	v_pk_fma_f32 v[2:3], v[2:3], v[4:5], v[6:7]
	v_add_f32_e32 v4, 1.0, v12
	v_mul_f32_e32 v5, 0xbfb8aa3b, v2
	v_mul_f32_e32 v6, 0xbfb8aa3b, v3
	v_rcp_f32_e32 v4, v4
	v_exp_f32_e32 v5, v5
	v_exp_f32_e32 v6, v6
	v_mul_f32_e32 v18, v18, v22
	v_mul_f32_e32 v1, v1, v4
	v_add_f32_e32 v4, 1.0, v5
	v_add_f32_e32 v5, 1.0, v6
	v_rcp_f32_e32 v4, v4
	v_rcp_f32_e32 v5, v5
	v_mov_b32_e32 v6, v201
	v_cvt_pk_fp8_f32 v6, v0, v1
	v_mul_f32_e32 v19, v19, v23
	v_cvt_pk_fp8_f32 v20, v18, v19 op_sel:[0,0,1]
	v_cvt_pk_fp8_f32 v9, v10, v8 op_sel:[0,0,1]
	v_mul_f32_e32 v0, v2, v4
	v_mul_f32_e32 v1, v3, v5
	v_lshl_add_u64 v[24:25], s[0:1], 0, v[40:41]
	v_cvt_pk_fp8_f32 v6, v0, v1 op_sel:[0,0,1]
	global_store_dword v[24:25], v30, off
	global_store_dword v[24:25], v20, off offset:256
	global_store_dword v[24:25], v9, off offset:512
	global_store_dword v[24:25], v6, off offset:768
	s_barrier
	s_barrier
	s_cbranch_vccnz .LBB0_900
	v_mbcnt_lo_u32_b32 v0, -1, 0
	v_mbcnt_hi_u32_b32 v0, -1, v0
	s_nop 0
	v_cmp_eq_u32_e32 vcc, 0, v0
	s_and_saveexec_b64 s[0:1], vcc
	s_cbranch_execz .LBB0_899
	s_mov_b64 s[6:7], exec
	v_mbcnt_lo_u32_b32 v0, s6, 0
	v_mbcnt_hi_u32_b32 v0, s7, v0
	v_cmp_eq_u32_e32 vcc, 0, v0
	s_and_saveexec_b64 s[4:5], vcc
	s_cbranch_execz .LBB0_898
	s_bcnt1_i32_b64 s6, s[6:7]
	v_mov_b32_e32 v1, s6
	global_atomic_add v1, v201, v1, s[18:19] sc0
	s_branch .LBB0_898
